# LDS-DMA issue hoisted above ds_reads in all GEMM load segments; s_setprio toggles removed
# baseline (speedup 1.0000x reference)
.LBB0_174:
	s_ashr_i32 s31, s30, 31
	s_lshl_b64 s[34:35], s[30:31], 19
	s_add_u32 s34, s48, s34
	s_addc_u32 s35, s49, s35
	s_ashr_i32 s29, s28, 31
	s_lshl_b64 s[36:37], s[28:29], 19
	s_add_u32 s36, s51, s36
	s_mov_b32 s44, 0
	s_addc_u32 s37, s52, s37
	s_ashr_i32 s45, s44, 31
	s_lshl_b64 s[76:77], s[44:45], 7
	s_add_u32 s78, s76, 0x100
	s_addc_u32 s79, s77, 0
	s_add_u32 s44, s42, s78
	ds_read_b128 v[0:3], v141
	ds_read_b128 v[4:7], v141 offset:1024
	ds_read_b128 v[8:11], v141 offset:2048
	ds_read_b128 v[12:15], v141 offset:3072
	ds_read_b128 v[16:19], v142
	ds_read_b128 v[20:23], v142 offset:1024
	ds_read_b128 v[24:27], v142 offset:2048
	ds_read_b128 v[28:31], v142 offset:3072
	s_addc_u32 s45, s43, s79
	s_and_b64 s[74:75], s[4:5], exec
	s_cselect_b32 s31, s37, s41
	s_cselect_b32 s74, s36, s40
	s_add_u32 s78, s40, s78
	s_addc_u32 s79, s41, s79
	s_add_u32 s76, s42, s76
	s_mov_b32 s29, 0
	s_addc_u32 s77, s43, s77
	v_lshl_add_u64 v[64:65], s[76:77], 0, v[130:131]
	s_mov_b32 m0, s66
	v_lshl_add_u64 v[66:67], v[64:65], 0, s[22:23]
	ds_read_b128 v[32:35], v143
	ds_read_b128 v[36:39], v143 offset:1024
	ds_read_b128 v[40:43], v143 offset:2048
	ds_read_b128 v[44:47], v143 offset:3072
	ds_read_b128 v[48:51], v143 offset:4096
	ds_read_b128 v[52:55], v143 offset:5120
	ds_read_b128 v[56:59], v143 offset:6144
	ds_read_b128 v[60:63], v143 offset:7168
	global_load_lds_dwordx4 v[66:67], off
	v_lshl_add_u64 v[64:65], v[64:65], 0, s[24:25]
	s_mov_b32 m0, s67
	s_and_b64 s[76:77], s[4:5], exec
	global_load_lds_dwordx4 v[64:65], off
	s_waitcnt vmcnt(16)
	s_waitcnt lgkmcnt(0)
	s_cselect_b32 s75, s35, s43
	s_cselect_b32 s76, s34, s42
	s_barrier
	s_waitcnt lgkmcnt(0)
	v_mfma_f32_16x16x32_bf16 v[64:67], v[0:3], v[32:35], 0
	v_mfma_f32_16x16x32_bf16 v[68:71], v[8:11], v[32:35], 0
	v_mfma_f32_16x16x32_bf16 v[72:75], v[0:3], v[40:43], 0
	v_mfma_f32_16x16x32_bf16 v[76:79], v[8:11], v[40:43], 0
	v_mfma_f32_16x16x32_bf16 v[80:83], v[0:3], v[48:51], 0
	v_mfma_f32_16x16x32_bf16 v[84:87], v[8:11], v[48:51], 0
	v_mfma_f32_16x16x32_bf16 v[88:91], v[0:3], v[56:59], 0
	v_mfma_f32_16x16x32_bf16 v[92:95], v[8:11], v[56:59], 0
	v_mfma_f32_16x16x32_bf16 v[64:67], v[4:7], v[36:39], v[64:67]
	v_mfma_f32_16x16x32_bf16 v[68:71], v[12:15], v[36:39], v[68:71]
	v_mfma_f32_16x16x32_bf16 v[72:75], v[4:7], v[44:47], v[72:75]
	v_mfma_f32_16x16x32_bf16 v[76:79], v[12:15], v[44:47], v[76:79]
	v_mfma_f32_16x16x32_bf16 v[80:83], v[4:7], v[52:55], v[80:83]
	v_mfma_f32_16x16x32_bf16 v[84:87], v[12:15], v[52:55], v[84:87]
	v_mfma_f32_16x16x32_bf16 v[88:91], v[4:7], v[60:63], v[88:91]
	v_mfma_f32_16x16x32_bf16 v[100:103], v[12:15], v[60:63], v[92:95]
	v_mfma_f32_16x16x32_bf16 v[92:95], v[16:19], v[32:35], 0
	v_mfma_f32_16x16x32_bf16 v[32:35], v[24:27], v[32:35], 0
	v_mfma_f32_16x16x32_bf16 v[104:107], v[20:23], v[36:39], v[92:95]
	v_mfma_f32_16x16x32_bf16 v[32:35], v[28:31], v[36:39], v[32:35]
	v_mfma_f32_16x16x32_bf16 v[36:39], v[16:19], v[40:43], 0
	v_mfma_f32_16x16x32_bf16 v[40:43], v[24:27], v[40:43], 0
	v_mfma_f32_16x16x32_bf16 v[36:39], v[20:23], v[44:47], v[36:39]
	v_mfma_f32_16x16x32_bf16 v[40:43], v[28:31], v[44:47], v[40:43]
	v_mfma_f32_16x16x32_bf16 v[44:47], v[16:19], v[48:51], 0
	v_mfma_f32_16x16x32_bf16 v[48:51], v[24:27], v[48:51], 0
	v_mfma_f32_16x16x32_bf16 v[44:47], v[20:23], v[52:55], v[44:47]
	v_mfma_f32_16x16x32_bf16 v[48:51], v[28:31], v[52:55], v[48:51]
	v_mfma_f32_16x16x32_bf16 v[52:55], v[16:19], v[56:59], 0
	v_mfma_f32_16x16x32_bf16 v[56:59], v[24:27], v[56:59], 0
	v_mfma_f32_16x16x32_bf16 v[52:55], v[20:23], v[60:63], v[52:55]
	v_mfma_f32_16x16x32_bf16 v[56:59], v[28:31], v[60:63], v[56:59]
	s_barrier
	s_mov_b32 m0, s68
	v_lshl_add_u64 v[244:245], s[78:79], 0, v[128:129]
	global_load_lds_dwordx4 v[244:245], off
	v_lshl_add_u64 v[136:137], v[244:245], 0, s[0:1]
	s_mov_b32 m0, s69
	v_lshl_add_u64 v[246:247], s[44:45], 0, v[130:131]
	global_load_lds_dwordx4 v[136:137], off
	v_lshl_add_u64 v[136:137], v[244:245], 0, s[2:3]
	s_mov_b32 m0, s70
	s_nop 0
	global_load_lds_dwordx4 v[136:137], off
	v_lshl_add_u64 v[136:137], v[244:245], 0, s[8:9]
	s_mov_b32 m0, s71
	s_nop 0
	global_load_lds_dwordx4 v[136:137], off
	s_mov_b32 m0, s39
	v_lshl_add_u64 v[136:137], v[246:247], 0, s[0:1]
	global_load_lds_dwordx4 v[246:247], off
	s_mov_b32 m0, s56
	s_nop 0
	global_load_lds_dwordx4 v[136:137], off
	ds_read_b128 v[60:63], v143 offset:16384
	ds_read_b128 v[92:95], v143 offset:17408
	ds_read_b128 v[96:99], v143 offset:18432
	ds_read_b128 v[108:111], v143 offset:19456
	ds_read_b128 v[112:115], v143 offset:20480
	ds_read_b128 v[116:119], v143 offset:21504
	ds_read_b128 v[120:123], v143 offset:22528
	ds_read_b128 v[124:127], v143 offset:23552
	s_waitcnt vmcnt(16)
	s_waitcnt lgkmcnt(0)
	s_barrier
	s_waitcnt lgkmcnt(0)
	v_mfma_f32_16x16x32_bf16 v[146:149], v[0:3], v[60:63], 0
	v_mfma_f32_16x16x32_bf16 v[154:157], v[0:3], v[96:99], 0
	v_mfma_f32_16x16x32_bf16 v[162:165], v[0:3], v[112:115], 0
	v_mfma_f32_16x16x32_bf16 v[0:3], v[0:3], v[120:123], 0
	v_mfma_f32_16x16x32_bf16 v[146:149], v[4:7], v[92:95], v[146:149]
	v_mfma_f32_16x16x32_bf16 v[154:157], v[4:7], v[108:111], v[154:157]
	v_mfma_f32_16x16x32_bf16 v[162:165], v[4:7], v[116:119], v[162:165]
	v_mfma_f32_16x16x32_bf16 v[0:3], v[4:7], v[124:127], v[0:3]
	v_mfma_f32_16x16x32_bf16 v[4:7], v[8:11], v[120:123], 0
	v_mfma_f32_16x16x32_bf16 v[150:153], v[8:11], v[60:63], 0
	v_mfma_f32_16x16x32_bf16 v[158:161], v[8:11], v[96:99], 0
	v_mfma_f32_16x16x32_bf16 v[166:169], v[8:11], v[112:115], 0
	v_mfma_f32_16x16x32_bf16 v[4:7], v[12:15], v[124:127], v[4:7]
	v_mfma_f32_16x16x32_bf16 v[150:153], v[12:15], v[92:95], v[150:153]
	v_mfma_f32_16x16x32_bf16 v[158:161], v[12:15], v[108:111], v[158:161]
	v_mfma_f32_16x16x32_bf16 v[166:169], v[12:15], v[116:119], v[166:169]
	v_mfma_f32_16x16x32_bf16 v[12:15], v[24:27], v[60:63], 0
	v_mfma_f32_16x16x32_bf16 v[170:173], v[28:31], v[92:95], v[12:15]
	v_mfma_f32_16x16x32_bf16 v[12:15], v[16:19], v[96:99], 0
	v_mfma_f32_16x16x32_bf16 v[174:177], v[20:23], v[108:111], v[12:15]
	v_mfma_f32_16x16x32_bf16 v[12:15], v[24:27], v[96:99], 0
	v_mfma_f32_16x16x32_bf16 v[178:181], v[28:31], v[108:111], v[12:15]
	v_mfma_f32_16x16x32_bf16 v[12:15], v[16:19], v[112:115], 0
	v_mfma_f32_16x16x32_bf16 v[182:185], v[20:23], v[116:119], v[12:15]
	v_mfma_f32_16x16x32_bf16 v[12:15], v[24:27], v[112:115], 0
	v_mfma_f32_16x16x32_bf16 v[8:11], v[16:19], v[60:63], 0
	v_mfma_f32_16x16x32_bf16 v[186:189], v[28:31], v[116:119], v[12:15]
	v_mfma_f32_16x16x32_bf16 v[12:15], v[16:19], v[120:123], 0
	v_mfma_f32_16x16x32_bf16 v[8:11], v[20:23], v[92:95], v[8:11]
	v_mfma_f32_16x16x32_bf16 v[190:193], v[20:23], v[124:127], v[12:15]
	v_mfma_f32_16x16x32_bf16 v[12:15], v[24:27], v[120:123], 0
	v_mfma_f32_16x16x32_bf16 v[194:197], v[28:31], v[124:127], v[12:15]
	s_barrier
	s_add_i32 s79, 0, 0x1c000
	v_add_u32_e32 v136, s79, v140
	s_nop 2
	s_mov_b32 m0, s57
	v_lshl_add_u64 v[92:93], v[246:247], 0, s[2:3]
	global_load_lds_dwordx4 v[92:93], off
	v_lshl_add_u64 v[92:93], v[246:247], 0, s[8:9]
	s_mov_b32 m0, s58
	s_nop 0
	global_load_lds_dwordx4 v[92:93], off
	ds_read_b128 v[12:15], v144
	ds_read_b128 v[20:23], v144 offset:1024
	ds_read_b128 v[24:27], v144 offset:2048
	ds_read_b128 v[198:201], v144 offset:3072
	ds_read_b128 v[202:205], v136
	ds_read_b128 v[206:209], v136 offset:1024
	ds_read_b128 v[212:215], v136 offset:2048
	ds_read_b128 v[216:219], v136 offset:3072
	ds_read_b128 v[16:19], v143 offset:32768
	ds_read_b128 v[28:31], v143 offset:33792
	ds_read_b128 v[60:63], v143 offset:34816
	ds_read_b128 v[220:223], v143 offset:35840
	ds_read_b128 v[224:227], v143 offset:36864
	ds_read_b128 v[228:231], v143 offset:37888
	ds_read_b128 v[232:235], v143 offset:38912
	ds_read_b128 v[236:239], v143 offset:39936
	s_waitcnt vmcnt(8)
	s_waitcnt lgkmcnt(0)
	s_barrier
	s_waitcnt lgkmcnt(0)
	v_mfma_f32_16x16x32_bf16 v[64:67], v[12:15], v[16:19], v[64:67]
	v_mfma_f32_16x16x32_bf16 v[124:127], v[20:23], v[28:31], v[64:67]
	v_mfma_f32_16x16x32_bf16 v[64:67], v[24:27], v[16:19], v[68:71]
	v_mfma_f32_16x16x32_bf16 v[112:115], v[198:201], v[28:31], v[64:67]
	v_mfma_f32_16x16x32_bf16 v[64:67], v[12:15], v[60:63], v[72:75]
	v_mfma_f32_16x16x32_bf16 v[108:111], v[20:23], v[220:223], v[64:67]
	v_mfma_f32_16x16x32_bf16 v[64:67], v[24:27], v[60:63], v[76:79]
	v_mfma_f32_16x16x32_bf16 v[96:99], v[198:201], v[220:223], v[64:67]
	v_mfma_f32_16x16x32_bf16 v[64:67], v[12:15], v[224:227], v[80:83]
	v_mfma_f32_16x16x32_bf16 v[92:95], v[20:23], v[228:231], v[64:67]
	v_mfma_f32_16x16x32_bf16 v[64:67], v[24:27], v[224:227], v[84:87]
	v_mfma_f32_16x16x32_bf16 v[80:83], v[198:201], v[228:231], v[64:67]
	v_mfma_f32_16x16x32_bf16 v[64:67], v[12:15], v[232:235], v[88:91]
	v_mfma_f32_16x16x32_bf16 v[76:79], v[20:23], v[236:239], v[64:67]
	v_mfma_f32_16x16x32_bf16 v[64:67], v[24:27], v[232:235], v[100:103]
	v_mfma_f32_16x16x32_bf16 v[64:67], v[198:201], v[236:239], v[64:67]
	v_mfma_f32_16x16x32_bf16 v[68:71], v[202:205], v[16:19], v[104:107]
	v_mfma_f32_16x16x32_bf16 v[16:19], v[212:215], v[16:19], v[32:35]
	v_mfma_f32_16x16x32_bf16 v[116:119], v[216:219], v[28:31], v[16:19]
	v_mfma_f32_16x16x32_bf16 v[16:19], v[202:205], v[60:63], v[36:39]
	v_mfma_f32_16x16x32_bf16 v[104:107], v[206:209], v[220:223], v[16:19]
	v_mfma_f32_16x16x32_bf16 v[16:19], v[212:215], v[60:63], v[40:43]
	v_mfma_f32_16x16x32_bf16 v[100:103], v[216:219], v[220:223], v[16:19]
	v_mfma_f32_16x16x32_bf16 v[16:19], v[202:205], v[224:227], v[44:47]
	v_mfma_f32_16x16x32_bf16 v[88:91], v[206:209], v[228:231], v[16:19]
	v_mfma_f32_16x16x32_bf16 v[16:19], v[212:215], v[224:227], v[48:51]
	v_mfma_f32_16x16x32_bf16 v[84:87], v[216:219], v[228:231], v[16:19]
	v_mfma_f32_16x16x32_bf16 v[16:19], v[202:205], v[232:235], v[52:55]
	v_mfma_f32_16x16x32_bf16 v[72:75], v[206:209], v[236:239], v[16:19]
	v_mfma_f32_16x16x32_bf16 v[16:19], v[212:215], v[232:235], v[56:59]
	v_mfma_f32_16x16x32_bf16 v[120:123], v[206:209], v[28:31], v[68:71]
	v_mfma_f32_16x16x32_bf16 v[68:71], v[216:219], v[236:239], v[16:19]
	s_barrier
	s_add_i32 s77, s72, s53
	s_nop 2
	v_lshl_add_u64 v[16:17], v[244:245], 0, s[18:19]
	s_mov_b32 m0, s77
	s_add_i32 s78, s77, 0x2000
	global_load_lds_dwordx4 v[16:17], off
	v_lshl_add_u64 v[16:17], v[244:245], 0, s[20:21]
	s_mov_b32 m0, s78
	s_add_i32 s79, s79, s53
	global_load_lds_dwordx4 v[16:17], off
	v_lshl_add_u64 v[16:17], v[244:245], 0, s[22:23]
	s_mov_b32 m0, s79
	s_add_i32 s80, s79, 0x2000
	global_load_lds_dwordx4 v[16:17], off
	v_lshl_add_u64 v[16:17], v[244:245], 0, s[24:25]
	s_mov_b32 m0, s80
	s_nop 0
	global_load_lds_dwordx4 v[16:17], off
	v_lshl_add_u64 v[16:17], v[246:247], 0, s[18:19]
	s_mov_b32 m0, s60
	s_nop 0
	global_load_lds_dwordx4 v[16:17], off
	v_lshl_add_u64 v[16:17], v[246:247], 0, s[20:21]
	s_mov_b32 m0, s61
	s_nop 0
	global_load_lds_dwordx4 v[16:17], off
	ds_read_b128 v[36:39], v143 offset:49152
	ds_read_b128 v[40:43], v143 offset:50176
	ds_read_b128 v[220:223], v143 offset:51200
	ds_read_b128 v[224:227], v143 offset:52224
	ds_read_b128 v[228:231], v143 offset:53248
	ds_read_b128 v[232:235], v143 offset:54272
	ds_read_b128 v[236:239], v143 offset:55296
	ds_read_b128 v[240:243], v143 offset:56320
	s_waitcnt vmcnt(8)
	s_waitcnt lgkmcnt(0)
	s_barrier
	s_waitcnt lgkmcnt(0)
	v_mfma_f32_16x16x32_bf16 v[16:19], v[12:15], v[36:39], v[146:149]
	v_mfma_f32_16x16x32_bf16 v[60:63], v[20:23], v[40:43], v[16:19]
	v_mfma_f32_16x16x32_bf16 v[16:19], v[24:27], v[36:39], v[150:153]
	v_mfma_f32_16x16x32_bf16 v[48:51], v[198:201], v[40:43], v[16:19]
	v_mfma_f32_16x16x32_bf16 v[16:19], v[12:15], v[220:223], v[154:157]
	v_mfma_f32_16x16x32_bf16 v[44:47], v[20:23], v[224:227], v[16:19]
	v_mfma_f32_16x16x32_bf16 v[16:19], v[24:27], v[220:223], v[158:161]
	v_mfma_f32_16x16x32_bf16 v[32:35], v[198:201], v[224:227], v[16:19]
	v_mfma_f32_16x16x32_bf16 v[16:19], v[12:15], v[228:231], v[162:165]
	v_mfma_f32_16x16x32_bf16 v[0:3], v[12:15], v[236:239], v[0:3]
	v_mfma_f32_16x16x32_bf16 v[28:31], v[20:23], v[232:235], v[16:19]
	v_mfma_f32_16x16x32_bf16 v[16:19], v[24:27], v[228:231], v[166:169]
	v_mfma_f32_16x16x32_bf16 v[12:15], v[20:23], v[240:243], v[0:3]
	v_mfma_f32_16x16x32_bf16 v[0:3], v[24:27], v[236:239], v[4:7]
	v_mfma_f32_16x16x32_bf16 v[16:19], v[198:201], v[232:235], v[16:19]
	v_mfma_f32_16x16x32_bf16 v[0:3], v[198:201], v[240:243], v[0:3]
	v_mfma_f32_16x16x32_bf16 v[4:7], v[202:205], v[36:39], v[8:11]
	v_mfma_f32_16x16x32_bf16 v[56:59], v[206:209], v[40:43], v[4:7]
	v_mfma_f32_16x16x32_bf16 v[4:7], v[212:215], v[36:39], v[170:173]
	v_mfma_f32_16x16x32_bf16 v[52:55], v[216:219], v[40:43], v[4:7]
	v_mfma_f32_16x16x32_bf16 v[4:7], v[202:205], v[220:223], v[174:177]
	v_mfma_f32_16x16x32_bf16 v[40:43], v[206:209], v[224:227], v[4:7]
	v_mfma_f32_16x16x32_bf16 v[4:7], v[212:215], v[220:223], v[178:181]
	v_mfma_f32_16x16x32_bf16 v[36:39], v[216:219], v[224:227], v[4:7]
	v_mfma_f32_16x16x32_bf16 v[4:7], v[202:205], v[228:231], v[182:185]
	v_mfma_f32_16x16x32_bf16 v[24:27], v[206:209], v[232:235], v[4:7]
	v_mfma_f32_16x16x32_bf16 v[4:7], v[212:215], v[228:231], v[186:189]
	v_mfma_f32_16x16x32_bf16 v[20:23], v[216:219], v[232:235], v[4:7]
	v_mfma_f32_16x16x32_bf16 v[4:7], v[202:205], v[236:239], v[190:193]
	v_mfma_f32_16x16x32_bf16 v[8:11], v[206:209], v[240:243], v[4:7]
	v_mfma_f32_16x16x32_bf16 v[4:7], v[212:215], v[236:239], v[194:197]
	v_mfma_f32_16x16x32_bf16 v[4:7], v[216:219], v[240:243], v[4:7]
	s_barrier
.LBB0_175:
	s_add_i32 s29, s29, 2
	s_mov_b32 s44, s29
	s_ashr_i32 s45, s44, 31
	s_lshl_b64 s[82:83], s[44:45], 7
	s_add_u32 s45, s82, 0x100
	s_addc_u32 s81, s83, 0
	s_add_u32 s84, s42, s45
	s_addc_u32 s85, s43, s81
	s_add_u32 s86, s40, s45
	s_addc_u32 s81, s41, s81
	s_cmp_eq_u32 s44, 14
	s_cselect_b32 s45, s75, s85
	s_cselect_b32 s44, s76, s84
	s_cselect_b32 s85, s31, s81
	s_cselect_b32 s84, s74, s86
	s_add_u32 s82, s42, s82
	s_addc_u32 s83, s43, s83
	v_lshl_add_u64 v[212:213], s[82:83], 0, v[130:131]
	s_mov_b32 m0, s66
	v_lshl_add_u64 v[214:215], v[212:213], 0, s[22:23]
	global_load_lds_dwordx4 v[214:215], off
	v_lshl_add_u64 v[212:213], v[212:213], 0, s[24:25]
	s_mov_b32 m0, s67
	s_nop 0
	global_load_lds_dwordx4 v[212:213], off
	ds_read_b128 v[146:149], v141
	ds_read_b128 v[150:153], v141 offset:1024
	ds_read_b128 v[154:157], v141 offset:2048
	ds_read_b128 v[158:161], v141 offset:3072
	ds_read_b128 v[162:165], v142
	ds_read_b128 v[166:169], v142 offset:1024
	ds_read_b128 v[170:173], v142 offset:2048
	ds_read_b128 v[174:177], v142 offset:3072
	ds_read_b128 v[178:181], v143
	ds_read_b128 v[182:185], v143 offset:1024
	ds_read_b128 v[186:189], v143 offset:2048
	ds_read_b128 v[190:193], v143 offset:3072
	ds_read_b128 v[194:197], v143 offset:4096
	ds_read_b128 v[198:201], v143 offset:5120
	ds_read_b128 v[202:205], v143 offset:6144
	ds_read_b128 v[206:209], v143 offset:7168
	s_waitcnt vmcnt(8)
	s_waitcnt lgkmcnt(0)
	s_barrier
	s_waitcnt lgkmcnt(0)
	v_mfma_f32_16x16x32_bf16 v[124:127], v[146:149], v[178:181], v[124:127]
	v_mfma_f32_16x16x32_bf16 v[112:115], v[154:157], v[178:181], v[112:115]
	v_mfma_f32_16x16x32_bf16 v[108:111], v[146:149], v[186:189], v[108:111]
	v_mfma_f32_16x16x32_bf16 v[96:99], v[154:157], v[186:189], v[96:99]
	v_mfma_f32_16x16x32_bf16 v[92:95], v[146:149], v[194:197], v[92:95]
	v_mfma_f32_16x16x32_bf16 v[80:83], v[154:157], v[194:197], v[80:83]
	v_mfma_f32_16x16x32_bf16 v[76:79], v[146:149], v[202:205], v[76:79]
	v_mfma_f32_16x16x32_bf16 v[64:67], v[154:157], v[202:205], v[64:67]
	v_mfma_f32_16x16x32_bf16 v[124:127], v[150:153], v[182:185], v[124:127]
	v_mfma_f32_16x16x32_bf16 v[112:115], v[158:161], v[182:185], v[112:115]
	v_mfma_f32_16x16x32_bf16 v[108:111], v[150:153], v[190:193], v[108:111]
	v_mfma_f32_16x16x32_bf16 v[96:99], v[158:161], v[190:193], v[96:99]
	v_mfma_f32_16x16x32_bf16 v[92:95], v[150:153], v[198:201], v[92:95]
	v_mfma_f32_16x16x32_bf16 v[80:83], v[158:161], v[198:201], v[80:83]
	v_mfma_f32_16x16x32_bf16 v[76:79], v[150:153], v[206:209], v[76:79]
	v_mfma_f32_16x16x32_bf16 v[64:67], v[158:161], v[206:209], v[64:67]
	v_mfma_f32_16x16x32_bf16 v[120:123], v[162:165], v[178:181], v[120:123]
	v_mfma_f32_16x16x32_bf16 v[116:119], v[170:173], v[178:181], v[116:119]
	v_mfma_f32_16x16x32_bf16 v[104:107], v[162:165], v[186:189], v[104:107]
	v_mfma_f32_16x16x32_bf16 v[100:103], v[170:173], v[186:189], v[100:103]
	v_mfma_f32_16x16x32_bf16 v[88:91], v[162:165], v[194:197], v[88:91]
	v_mfma_f32_16x16x32_bf16 v[84:87], v[170:173], v[194:197], v[84:87]
	v_mfma_f32_16x16x32_bf16 v[72:75], v[162:165], v[202:205], v[72:75]
	v_mfma_f32_16x16x32_bf16 v[68:71], v[170:173], v[202:205], v[68:71]
	v_mfma_f32_16x16x32_bf16 v[120:123], v[166:169], v[182:185], v[120:123]
	v_mfma_f32_16x16x32_bf16 v[116:119], v[174:177], v[182:185], v[116:119]
	v_mfma_f32_16x16x32_bf16 v[104:107], v[166:169], v[190:193], v[104:107]
	v_mfma_f32_16x16x32_bf16 v[100:103], v[174:177], v[190:193], v[100:103]
	v_mfma_f32_16x16x32_bf16 v[88:91], v[166:169], v[198:201], v[88:91]
	v_mfma_f32_16x16x32_bf16 v[84:87], v[174:177], v[198:201], v[84:87]
	v_mfma_f32_16x16x32_bf16 v[72:75], v[166:169], v[206:209], v[72:75]
	v_mfma_f32_16x16x32_bf16 v[68:71], v[174:177], v[206:209], v[68:71]
	s_barrier
	s_mov_b32 m0, s68
	v_lshl_add_u64 v[212:213], s[84:85], 0, v[128:129]
	global_load_lds_dwordx4 v[212:213], off
	v_lshl_add_u64 v[214:215], v[212:213], 0, s[0:1]
	s_mov_b32 m0, s69
	s_nop 0
	global_load_lds_dwordx4 v[214:215], off
	v_lshl_add_u64 v[214:215], v[212:213], 0, s[2:3]
	s_mov_b32 m0, s70
	s_nop 0
	global_load_lds_dwordx4 v[214:215], off
	v_lshl_add_u64 v[214:215], v[212:213], 0, s[8:9]
	s_mov_b32 m0, s71
	s_nop 0
	global_load_lds_dwordx4 v[214:215], off
	v_lshl_add_u64 v[214:215], s[44:45], 0, v[130:131]
	s_mov_b32 m0, s39
	v_lshl_add_u64 v[216:217], v[214:215], 0, s[0:1]
	global_load_lds_dwordx4 v[214:215], off
	s_mov_b32 m0, s56
	s_nop 0
	global_load_lds_dwordx4 v[216:217], off
	ds_read_b128 v[178:181], v143 offset:16384
	ds_read_b128 v[182:185], v143 offset:17408
	ds_read_b128 v[186:189], v143 offset:18432
	ds_read_b128 v[190:193], v143 offset:19456
	ds_read_b128 v[194:197], v143 offset:20480
	ds_read_b128 v[198:201], v143 offset:21504
	ds_read_b128 v[202:205], v143 offset:22528
	ds_read_b128 v[206:209], v143 offset:23552
	s_waitcnt vmcnt(8)
	s_waitcnt lgkmcnt(0)
	s_barrier
	s_waitcnt lgkmcnt(0)
	v_mfma_f32_16x16x32_bf16 v[60:63], v[146:149], v[178:181], v[60:63]
	v_mfma_f32_16x16x32_bf16 v[48:51], v[154:157], v[178:181], v[48:51]
	v_mfma_f32_16x16x32_bf16 v[44:47], v[146:149], v[186:189], v[44:47]
	v_mfma_f32_16x16x32_bf16 v[32:35], v[154:157], v[186:189], v[32:35]
	v_mfma_f32_16x16x32_bf16 v[28:31], v[146:149], v[194:197], v[28:31]
	v_mfma_f32_16x16x32_bf16 v[16:19], v[154:157], v[194:197], v[16:19]
	v_mfma_f32_16x16x32_bf16 v[12:15], v[146:149], v[202:205], v[12:15]
	v_mfma_f32_16x16x32_bf16 v[0:3], v[154:157], v[202:205], v[0:3]
	v_mfma_f32_16x16x32_bf16 v[60:63], v[150:153], v[182:185], v[60:63]
	v_mfma_f32_16x16x32_bf16 v[48:51], v[158:161], v[182:185], v[48:51]
	v_mfma_f32_16x16x32_bf16 v[44:47], v[150:153], v[190:193], v[44:47]
	v_mfma_f32_16x16x32_bf16 v[32:35], v[158:161], v[190:193], v[32:35]
	v_mfma_f32_16x16x32_bf16 v[28:31], v[150:153], v[198:201], v[28:31]
	v_mfma_f32_16x16x32_bf16 v[16:19], v[158:161], v[198:201], v[16:19]
	v_mfma_f32_16x16x32_bf16 v[12:15], v[150:153], v[206:209], v[12:15]
	v_mfma_f32_16x16x32_bf16 v[0:3], v[158:161], v[206:209], v[0:3]
	v_mfma_f32_16x16x32_bf16 v[56:59], v[162:165], v[178:181], v[56:59]
	v_mfma_f32_16x16x32_bf16 v[52:55], v[170:173], v[178:181], v[52:55]
	v_mfma_f32_16x16x32_bf16 v[40:43], v[162:165], v[186:189], v[40:43]
	v_mfma_f32_16x16x32_bf16 v[36:39], v[170:173], v[186:189], v[36:39]
	v_mfma_f32_16x16x32_bf16 v[24:27], v[162:165], v[194:197], v[24:27]
	v_mfma_f32_16x16x32_bf16 v[20:23], v[170:173], v[194:197], v[20:23]
	v_mfma_f32_16x16x32_bf16 v[8:11], v[162:165], v[202:205], v[8:11]
	v_mfma_f32_16x16x32_bf16 v[4:7], v[170:173], v[202:205], v[4:7]
	v_mfma_f32_16x16x32_bf16 v[56:59], v[166:169], v[182:185], v[56:59]
	v_mfma_f32_16x16x32_bf16 v[52:55], v[174:177], v[182:185], v[52:55]
	v_mfma_f32_16x16x32_bf16 v[40:43], v[166:169], v[190:193], v[40:43]
	v_mfma_f32_16x16x32_bf16 v[36:39], v[174:177], v[190:193], v[36:39]
	v_mfma_f32_16x16x32_bf16 v[24:27], v[166:169], v[198:201], v[24:27]
	v_mfma_f32_16x16x32_bf16 v[20:23], v[174:177], v[198:201], v[20:23]
	v_mfma_f32_16x16x32_bf16 v[8:11], v[166:169], v[206:209], v[8:11]
	v_mfma_f32_16x16x32_bf16 v[4:7], v[174:177], v[206:209], v[4:7]
	s_barrier
	s_mov_b32 m0, s57
	v_lshl_add_u64 v[216:217], v[214:215], 0, s[2:3]
	global_load_lds_dwordx4 v[216:217], off
	v_lshl_add_u64 v[216:217], v[214:215], 0, s[8:9]
	s_mov_b32 m0, s58
	s_nop 0
	global_load_lds_dwordx4 v[216:217], off
	ds_read_b128 v[146:149], v144
	ds_read_b128 v[150:153], v144 offset:1024
	ds_read_b128 v[154:157], v144 offset:2048
	ds_read_b128 v[158:161], v144 offset:3072
	ds_read_b128 v[162:165], v136
	ds_read_b128 v[166:169], v136 offset:1024
	ds_read_b128 v[170:173], v136 offset:2048
	ds_read_b128 v[174:177], v136 offset:3072
	ds_read_b128 v[178:181], v143 offset:32768
	ds_read_b128 v[182:185], v143 offset:33792
	ds_read_b128 v[186:189], v143 offset:34816
	ds_read_b128 v[190:193], v143 offset:35840
	ds_read_b128 v[194:197], v143 offset:36864
	ds_read_b128 v[198:201], v143 offset:37888
	ds_read_b128 v[202:205], v143 offset:38912
	ds_read_b128 v[206:209], v143 offset:39936
	s_waitcnt vmcnt(8)
	s_waitcnt lgkmcnt(0)
	s_barrier
	s_waitcnt lgkmcnt(0)
	v_mfma_f32_16x16x32_bf16 v[124:127], v[146:149], v[178:181], v[124:127]
	v_mfma_f32_16x16x32_bf16 v[112:115], v[154:157], v[178:181], v[112:115]
	v_mfma_f32_16x16x32_bf16 v[108:111], v[146:149], v[186:189], v[108:111]
	v_mfma_f32_16x16x32_bf16 v[96:99], v[154:157], v[186:189], v[96:99]
	v_mfma_f32_16x16x32_bf16 v[92:95], v[146:149], v[194:197], v[92:95]
	v_mfma_f32_16x16x32_bf16 v[80:83], v[154:157], v[194:197], v[80:83]
	v_mfma_f32_16x16x32_bf16 v[76:79], v[146:149], v[202:205], v[76:79]
	v_mfma_f32_16x16x32_bf16 v[64:67], v[154:157], v[202:205], v[64:67]
	v_mfma_f32_16x16x32_bf16 v[124:127], v[150:153], v[182:185], v[124:127]
	v_mfma_f32_16x16x32_bf16 v[112:115], v[158:161], v[182:185], v[112:115]
	v_mfma_f32_16x16x32_bf16 v[108:111], v[150:153], v[190:193], v[108:111]
	v_mfma_f32_16x16x32_bf16 v[96:99], v[158:161], v[190:193], v[96:99]
	v_mfma_f32_16x16x32_bf16 v[92:95], v[150:153], v[198:201], v[92:95]
	v_mfma_f32_16x16x32_bf16 v[80:83], v[158:161], v[198:201], v[80:83]
	v_mfma_f32_16x16x32_bf16 v[76:79], v[150:153], v[206:209], v[76:79]
	v_mfma_f32_16x16x32_bf16 v[64:67], v[158:161], v[206:209], v[64:67]
	v_mfma_f32_16x16x32_bf16 v[120:123], v[162:165], v[178:181], v[120:123]
	v_mfma_f32_16x16x32_bf16 v[116:119], v[170:173], v[178:181], v[116:119]
	v_mfma_f32_16x16x32_bf16 v[104:107], v[162:165], v[186:189], v[104:107]
	v_mfma_f32_16x16x32_bf16 v[100:103], v[170:173], v[186:189], v[100:103]
	v_mfma_f32_16x16x32_bf16 v[88:91], v[162:165], v[194:197], v[88:91]
	v_mfma_f32_16x16x32_bf16 v[84:87], v[170:173], v[194:197], v[84:87]
	v_mfma_f32_16x16x32_bf16 v[72:75], v[162:165], v[202:205], v[72:75]
	v_mfma_f32_16x16x32_bf16 v[68:71], v[170:173], v[202:205], v[68:71]
	v_mfma_f32_16x16x32_bf16 v[120:123], v[166:169], v[182:185], v[120:123]
	v_mfma_f32_16x16x32_bf16 v[116:119], v[174:177], v[182:185], v[116:119]
	v_mfma_f32_16x16x32_bf16 v[104:107], v[166:169], v[190:193], v[104:107]
	v_mfma_f32_16x16x32_bf16 v[100:103], v[174:177], v[190:193], v[100:103]
	v_mfma_f32_16x16x32_bf16 v[88:91], v[166:169], v[198:201], v[88:91]
	v_mfma_f32_16x16x32_bf16 v[84:87], v[174:177], v[198:201], v[84:87]
	v_mfma_f32_16x16x32_bf16 v[72:75], v[166:169], v[206:209], v[72:75]
	v_mfma_f32_16x16x32_bf16 v[68:71], v[174:177], v[206:209], v[68:71]
	s_barrier
	s_mov_b32 m0, s77
	v_lshl_add_u64 v[216:217], v[212:213], 0, s[18:19]
	global_load_lds_dwordx4 v[216:217], off
	v_lshl_add_u64 v[216:217], v[212:213], 0, s[20:21]
	s_mov_b32 m0, s78
	s_nop 0
	global_load_lds_dwordx4 v[216:217], off
	v_lshl_add_u64 v[216:217], v[212:213], 0, s[22:23]
	s_mov_b32 m0, s79
	v_lshl_add_u64 v[212:213], v[212:213], 0, s[24:25]
	global_load_lds_dwordx4 v[216:217], off
	s_mov_b32 m0, s80
	s_nop 0
	global_load_lds_dwordx4 v[212:213], off
	v_lshl_add_u64 v[212:213], v[214:215], 0, s[18:19]
	s_mov_b32 m0, s60
	s_nop 0
	global_load_lds_dwordx4 v[212:213], off
	v_lshl_add_u64 v[212:213], v[214:215], 0, s[20:21]
	s_mov_b32 m0, s61
	s_nop 0
	global_load_lds_dwordx4 v[212:213], off
	ds_read_b128 v[178:181], v143 offset:49152
	ds_read_b128 v[182:185], v143 offset:50176
	ds_read_b128 v[186:189], v143 offset:51200
	ds_read_b128 v[190:193], v143 offset:52224
	ds_read_b128 v[194:197], v143 offset:53248
	ds_read_b128 v[198:201], v143 offset:54272
	ds_read_b128 v[202:205], v143 offset:55296
	ds_read_b128 v[206:209], v143 offset:56320
	s_waitcnt vmcnt(8)
	s_waitcnt lgkmcnt(0)
	s_barrier
	s_waitcnt lgkmcnt(0)
	v_mfma_f32_16x16x32_bf16 v[60:63], v[146:149], v[178:181], v[60:63]
	v_mfma_f32_16x16x32_bf16 v[48:51], v[154:157], v[178:181], v[48:51]
	v_mfma_f32_16x16x32_bf16 v[44:47], v[146:149], v[186:189], v[44:47]
	v_mfma_f32_16x16x32_bf16 v[32:35], v[154:157], v[186:189], v[32:35]
	v_mfma_f32_16x16x32_bf16 v[28:31], v[146:149], v[194:197], v[28:31]
	v_mfma_f32_16x16x32_bf16 v[16:19], v[154:157], v[194:197], v[16:19]
	v_mfma_f32_16x16x32_bf16 v[12:15], v[146:149], v[202:205], v[12:15]
	v_mfma_f32_16x16x32_bf16 v[0:3], v[154:157], v[202:205], v[0:3]
	v_mfma_f32_16x16x32_bf16 v[60:63], v[150:153], v[182:185], v[60:63]
	v_mfma_f32_16x16x32_bf16 v[48:51], v[158:161], v[182:185], v[48:51]
	v_mfma_f32_16x16x32_bf16 v[44:47], v[150:153], v[190:193], v[44:47]
	v_mfma_f32_16x16x32_bf16 v[32:35], v[158:161], v[190:193], v[32:35]
	v_mfma_f32_16x16x32_bf16 v[28:31], v[150:153], v[198:201], v[28:31]
	v_mfma_f32_16x16x32_bf16 v[16:19], v[158:161], v[198:201], v[16:19]
	v_mfma_f32_16x16x32_bf16 v[12:15], v[150:153], v[206:209], v[12:15]
	v_mfma_f32_16x16x32_bf16 v[0:3], v[158:161], v[206:209], v[0:3]
	v_mfma_f32_16x16x32_bf16 v[56:59], v[162:165], v[178:181], v[56:59]
	v_mfma_f32_16x16x32_bf16 v[52:55], v[170:173], v[178:181], v[52:55]
	v_mfma_f32_16x16x32_bf16 v[40:43], v[162:165], v[186:189], v[40:43]
	v_mfma_f32_16x16x32_bf16 v[36:39], v[170:173], v[186:189], v[36:39]
	v_mfma_f32_16x16x32_bf16 v[24:27], v[162:165], v[194:197], v[24:27]
	v_mfma_f32_16x16x32_bf16 v[20:23], v[170:173], v[194:197], v[20:23]
	v_mfma_f32_16x16x32_bf16 v[8:11], v[162:165], v[202:205], v[8:11]
	v_mfma_f32_16x16x32_bf16 v[4:7], v[170:173], v[202:205], v[4:7]
	v_mfma_f32_16x16x32_bf16 v[56:59], v[166:169], v[182:185], v[56:59]
	v_mfma_f32_16x16x32_bf16 v[52:55], v[174:177], v[182:185], v[52:55]
	v_mfma_f32_16x16x32_bf16 v[40:43], v[166:169], v[190:193], v[40:43]
	v_mfma_f32_16x16x32_bf16 v[36:39], v[174:177], v[190:193], v[36:39]
	v_mfma_f32_16x16x32_bf16 v[24:27], v[166:169], v[198:201], v[24:27]
	v_mfma_f32_16x16x32_bf16 v[20:23], v[174:177], v[198:201], v[20:23]
	v_mfma_f32_16x16x32_bf16 v[8:11], v[166:169], v[206:209], v[8:11]
	v_mfma_f32_16x16x32_bf16 v[4:7], v[174:177], v[206:209], v[4:7]
	s_barrier
	s_cmp_gt_u32 s29, 13
	s_cbranch_scc0 .LBB0_175
	s_and_b64 vcc, exec, s[26:27]
	s_cbranch_vccz .LBB0_178
	s_barrier

.LBB0_255:
	s_add_i32 s73, s73, 2
	s_mov_b32 s74, s73
	s_ashr_i32 s75, s74, 31
	s_lshl_b64 s[76:77], s[74:75], 7
	s_add_u32 s75, s76, 0x100
	s_addc_u32 s78, s77, 0
	s_add_u32 s79, s40, s75
	s_addc_u32 s80, s41, s78
	s_add_u32 s81, s38, s75
	s_addc_u32 s78, s39, s78
	s_cmp_eq_u32 s74, 42
	s_cselect_b32 s75, s1, s80
	s_cselect_b32 s74, s0, s79
	s_cselect_b32 s79, s43, s78
	s_cselect_b32 s78, s42, s81
	v_lshl_add_u64 v[208:209], v[136:137], 0, s[76:77]
	v_lshl_add_u64 v[212:213], v[208:209], 0, s[20:21]
	s_add_i32 m0, s53, 0xc000
	s_nop 0
	global_load_lds_dwordx4 v[212:213], off
	v_lshl_add_u64 v[208:209], v[208:209], 0, s[22:23]
	s_add_i32 m0, s53, 0xe000
	s_nop 0
	global_load_lds_dwordx4 v[208:209], off
	ds_read_b128 v[144:147], v141
	ds_read_b128 v[148:151], v141 offset:1024
	ds_read_b128 v[152:155], v141 offset:2048
	ds_read_b128 v[156:159], v141 offset:3072
	ds_read_b128 v[160:163], v142
	ds_read_b128 v[164:167], v142 offset:1024
	ds_read_b128 v[168:171], v142 offset:2048
	ds_read_b128 v[172:175], v142 offset:3072
	ds_read_b128 v[176:179], v143
	ds_read_b128 v[180:183], v143 offset:1024
	ds_read_b128 v[184:187], v143 offset:2048
	ds_read_b128 v[188:191], v143 offset:3072
	ds_read_b128 v[192:195], v143 offset:4096
	ds_read_b128 v[196:199], v143 offset:5120
	ds_read_b128 v[200:203], v143 offset:6144
	ds_read_b128 v[204:207], v143 offset:7168
	s_waitcnt vmcnt(8)
	s_waitcnt lgkmcnt(0)
	s_barrier
	s_waitcnt lgkmcnt(0)
	v_mfma_f32_16x16x32_bf16 v[124:127], v[144:147], v[176:179], v[124:127]
	v_mfma_f32_16x16x32_bf16 v[120:123], v[152:155], v[176:179], v[120:123]
	v_mfma_f32_16x16x32_bf16 v[116:119], v[144:147], v[184:187], v[116:119]
	v_mfma_f32_16x16x32_bf16 v[112:115], v[152:155], v[184:187], v[112:115]
	v_mfma_f32_16x16x32_bf16 v[100:103], v[144:147], v[192:195], v[100:103]
	v_mfma_f32_16x16x32_bf16 v[96:99], v[152:155], v[192:195], v[96:99]
	v_mfma_f32_16x16x32_bf16 v[84:87], v[144:147], v[200:203], v[84:87]
	v_mfma_f32_16x16x32_bf16 v[80:83], v[152:155], v[200:203], v[80:83]
	v_mfma_f32_16x16x32_bf16 v[124:127], v[148:151], v[180:183], v[124:127]
	v_mfma_f32_16x16x32_bf16 v[120:123], v[156:159], v[180:183], v[120:123]
	v_mfma_f32_16x16x32_bf16 v[116:119], v[148:151], v[188:191], v[116:119]
	v_mfma_f32_16x16x32_bf16 v[112:115], v[156:159], v[188:191], v[112:115]
	v_mfma_f32_16x16x32_bf16 v[100:103], v[148:151], v[196:199], v[100:103]
	v_mfma_f32_16x16x32_bf16 v[96:99], v[156:159], v[196:199], v[96:99]
	v_mfma_f32_16x16x32_bf16 v[84:87], v[148:151], v[204:207], v[84:87]
	v_mfma_f32_16x16x32_bf16 v[80:83], v[156:159], v[204:207], v[80:83]
	v_mfma_f32_16x16x32_bf16 v[108:111], v[160:163], v[176:179], v[108:111]
	v_mfma_f32_16x16x32_bf16 v[104:107], v[168:171], v[176:179], v[104:107]
	v_mfma_f32_16x16x32_bf16 v[92:95], v[160:163], v[184:187], v[92:95]
	v_mfma_f32_16x16x32_bf16 v[88:91], v[168:171], v[184:187], v[88:91]
	v_mfma_f32_16x16x32_bf16 v[76:79], v[160:163], v[192:195], v[76:79]
	v_mfma_f32_16x16x32_bf16 v[72:75], v[168:171], v[192:195], v[72:75]
	v_mfma_f32_16x16x32_bf16 v[68:71], v[160:163], v[200:203], v[68:71]
	v_mfma_f32_16x16x32_bf16 v[64:67], v[168:171], v[200:203], v[64:67]
	v_mfma_f32_16x16x32_bf16 v[108:111], v[164:167], v[180:183], v[108:111]
	v_mfma_f32_16x16x32_bf16 v[104:107], v[172:175], v[180:183], v[104:107]
	v_mfma_f32_16x16x32_bf16 v[92:95], v[164:167], v[188:191], v[92:95]
	v_mfma_f32_16x16x32_bf16 v[88:91], v[172:175], v[188:191], v[88:91]
	v_mfma_f32_16x16x32_bf16 v[76:79], v[164:167], v[196:199], v[76:79]
	v_mfma_f32_16x16x32_bf16 v[72:75], v[172:175], v[196:199], v[72:75]
	v_mfma_f32_16x16x32_bf16 v[68:71], v[164:167], v[204:207], v[68:71]
	v_mfma_f32_16x16x32_bf16 v[64:67], v[172:175], v[204:207], v[64:67]
	s_barrier
	s_add_i32 s76, s63, s52
	v_lshl_add_u64 v[208:209], s[78:79], 0, v[130:131]
	s_mov_b32 m0, s76
	s_nop 0
	global_load_lds_dwordx4 v[208:209], off
	v_lshl_add_u64 v[212:213], v[208:209], 0, s[2:3]
	s_add_i32 m0, s76, 0x2000
	s_add_i32 s76, s64, s52
	global_load_lds_dwordx4 v[212:213], off
	v_lshl_add_u64 v[212:213], v[208:209], 0, s[8:9]
	s_mov_b32 m0, s76
	s_nop 0
	global_load_lds_dwordx4 v[212:213], off
	v_lshl_add_u64 v[212:213], v[208:209], 0, s[14:15]
	s_add_i32 m0, s76, 0x2000
	s_nop 0
	global_load_lds_dwordx4 v[212:213], off
	v_lshl_add_u64 v[212:213], s[74:75], 0, v[128:129]
	s_mov_b32 m0, s53
	v_lshl_add_u64 v[214:215], v[212:213], 0, s[2:3]
	global_load_lds_dwordx4 v[212:213], off
	s_mov_b32 m0, s54
	s_nop 0
	global_load_lds_dwordx4 v[214:215], off
	ds_read_b128 v[176:179], v143 offset:16384
	ds_read_b128 v[180:183], v143 offset:17408
	ds_read_b128 v[184:187], v143 offset:18432
	ds_read_b128 v[188:191], v143 offset:19456
	ds_read_b128 v[192:195], v143 offset:20480
	ds_read_b128 v[196:199], v143 offset:21504
	ds_read_b128 v[200:203], v143 offset:22528
	ds_read_b128 v[204:207], v143 offset:23552
	s_waitcnt vmcnt(8)
	s_waitcnt lgkmcnt(0)
	s_barrier
	s_waitcnt lgkmcnt(0)
	v_mfma_f32_16x16x32_bf16 v[60:63], v[144:147], v[176:179], v[60:63]
	v_mfma_f32_16x16x32_bf16 v[56:59], v[152:155], v[176:179], v[56:59]
	v_mfma_f32_16x16x32_bf16 v[52:55], v[144:147], v[184:187], v[52:55]
	v_mfma_f32_16x16x32_bf16 v[48:51], v[152:155], v[184:187], v[48:51]
	v_mfma_f32_16x16x32_bf16 v[36:39], v[144:147], v[192:195], v[36:39]
	v_mfma_f32_16x16x32_bf16 v[32:35], v[152:155], v[192:195], v[32:35]
	v_mfma_f32_16x16x32_bf16 v[20:23], v[144:147], v[200:203], v[20:23]
	v_mfma_f32_16x16x32_bf16 v[16:19], v[152:155], v[200:203], v[16:19]
	v_mfma_f32_16x16x32_bf16 v[60:63], v[148:151], v[180:183], v[60:63]
	v_mfma_f32_16x16x32_bf16 v[56:59], v[156:159], v[180:183], v[56:59]
	v_mfma_f32_16x16x32_bf16 v[52:55], v[148:151], v[188:191], v[52:55]
	v_mfma_f32_16x16x32_bf16 v[48:51], v[156:159], v[188:191], v[48:51]
	v_mfma_f32_16x16x32_bf16 v[36:39], v[148:151], v[196:199], v[36:39]
	v_mfma_f32_16x16x32_bf16 v[32:35], v[156:159], v[196:199], v[32:35]
	v_mfma_f32_16x16x32_bf16 v[20:23], v[148:151], v[204:207], v[20:23]
	v_mfma_f32_16x16x32_bf16 v[16:19], v[156:159], v[204:207], v[16:19]
	v_mfma_f32_16x16x32_bf16 v[44:47], v[160:163], v[176:179], v[44:47]
	v_mfma_f32_16x16x32_bf16 v[40:43], v[168:171], v[176:179], v[40:43]
	v_mfma_f32_16x16x32_bf16 v[28:31], v[160:163], v[184:187], v[28:31]
	v_mfma_f32_16x16x32_bf16 v[24:27], v[168:171], v[184:187], v[24:27]
	v_mfma_f32_16x16x32_bf16 v[12:15], v[160:163], v[192:195], v[12:15]
	v_mfma_f32_16x16x32_bf16 v[8:11], v[168:171], v[192:195], v[8:11]
	v_mfma_f32_16x16x32_bf16 v[4:7], v[160:163], v[200:203], v[4:7]
	v_mfma_f32_16x16x32_bf16 v[0:3], v[168:171], v[200:203], v[0:3]
	v_mfma_f32_16x16x32_bf16 v[44:47], v[164:167], v[180:183], v[44:47]
	v_mfma_f32_16x16x32_bf16 v[40:43], v[172:175], v[180:183], v[40:43]
	v_mfma_f32_16x16x32_bf16 v[28:31], v[164:167], v[188:191], v[28:31]
	v_mfma_f32_16x16x32_bf16 v[24:27], v[172:175], v[188:191], v[24:27]
	v_mfma_f32_16x16x32_bf16 v[12:15], v[164:167], v[196:199], v[12:15]
	v_mfma_f32_16x16x32_bf16 v[8:11], v[172:175], v[196:199], v[8:11]
	v_mfma_f32_16x16x32_bf16 v[4:7], v[164:167], v[204:207], v[4:7]
	v_mfma_f32_16x16x32_bf16 v[0:3], v[172:175], v[204:207], v[0:3]
	s_barrier
	s_add_i32 s74, 0, 0x18000
	s_add_i32 s75, 0, 0x1c000
	v_add_u32_e32 v156, s74, v140
	v_add_u32_e32 v172, s75, v140
	s_mov_b32 m0, s55
	v_lshl_add_u64 v[214:215], v[212:213], 0, s[8:9]
	global_load_lds_dwordx4 v[214:215], off
	v_lshl_add_u64 v[214:215], v[212:213], 0, s[14:15]
	s_mov_b32 m0, s56
	s_nop 0
	global_load_lds_dwordx4 v[214:215], off
	ds_read_b128 v[144:147], v156
	ds_read_b128 v[148:151], v156 offset:1024
	ds_read_b128 v[152:155], v156 offset:2048
	ds_read_b128 v[156:159], v156 offset:3072
	ds_read_b128 v[160:163], v172
	ds_read_b128 v[164:167], v172 offset:1024
	ds_read_b128 v[168:171], v172 offset:2048
	ds_read_b128 v[172:175], v172 offset:3072
	ds_read_b128 v[176:179], v143 offset:32768
	ds_read_b128 v[180:183], v143 offset:33792
	ds_read_b128 v[184:187], v143 offset:34816
	ds_read_b128 v[188:191], v143 offset:35840
	ds_read_b128 v[192:195], v143 offset:36864
	ds_read_b128 v[196:199], v143 offset:37888
	ds_read_b128 v[200:203], v143 offset:38912
	ds_read_b128 v[204:207], v143 offset:39936
	s_waitcnt vmcnt(8)
	s_waitcnt lgkmcnt(0)
	s_barrier
	s_waitcnt lgkmcnt(0)
	v_mfma_f32_16x16x32_bf16 v[124:127], v[144:147], v[176:179], v[124:127]
	v_mfma_f32_16x16x32_bf16 v[120:123], v[152:155], v[176:179], v[120:123]
	v_mfma_f32_16x16x32_bf16 v[116:119], v[144:147], v[184:187], v[116:119]
	v_mfma_f32_16x16x32_bf16 v[112:115], v[152:155], v[184:187], v[112:115]
	v_mfma_f32_16x16x32_bf16 v[100:103], v[144:147], v[192:195], v[100:103]
	v_mfma_f32_16x16x32_bf16 v[96:99], v[152:155], v[192:195], v[96:99]
	v_mfma_f32_16x16x32_bf16 v[84:87], v[144:147], v[200:203], v[84:87]
	v_mfma_f32_16x16x32_bf16 v[80:83], v[152:155], v[200:203], v[80:83]
	v_mfma_f32_16x16x32_bf16 v[124:127], v[148:151], v[180:183], v[124:127]
	v_mfma_f32_16x16x32_bf16 v[120:123], v[156:159], v[180:183], v[120:123]
	v_mfma_f32_16x16x32_bf16 v[116:119], v[148:151], v[188:191], v[116:119]
	v_mfma_f32_16x16x32_bf16 v[112:115], v[156:159], v[188:191], v[112:115]
	v_mfma_f32_16x16x32_bf16 v[100:103], v[148:151], v[196:199], v[100:103]
	v_mfma_f32_16x16x32_bf16 v[96:99], v[156:159], v[196:199], v[96:99]
	v_mfma_f32_16x16x32_bf16 v[84:87], v[148:151], v[204:207], v[84:87]
	v_mfma_f32_16x16x32_bf16 v[80:83], v[156:159], v[204:207], v[80:83]
	v_mfma_f32_16x16x32_bf16 v[108:111], v[160:163], v[176:179], v[108:111]
	v_mfma_f32_16x16x32_bf16 v[104:107], v[168:171], v[176:179], v[104:107]
	v_mfma_f32_16x16x32_bf16 v[92:95], v[160:163], v[184:187], v[92:95]
	v_mfma_f32_16x16x32_bf16 v[88:91], v[168:171], v[184:187], v[88:91]
	v_mfma_f32_16x16x32_bf16 v[76:79], v[160:163], v[192:195], v[76:79]
	v_mfma_f32_16x16x32_bf16 v[72:75], v[168:171], v[192:195], v[72:75]
	v_mfma_f32_16x16x32_bf16 v[68:71], v[160:163], v[200:203], v[68:71]
	v_mfma_f32_16x16x32_bf16 v[64:67], v[168:171], v[200:203], v[64:67]
	v_mfma_f32_16x16x32_bf16 v[108:111], v[164:167], v[180:183], v[108:111]
	v_mfma_f32_16x16x32_bf16 v[104:107], v[172:175], v[180:183], v[104:107]
	v_mfma_f32_16x16x32_bf16 v[92:95], v[164:167], v[188:191], v[92:95]
	v_mfma_f32_16x16x32_bf16 v[88:91], v[172:175], v[188:191], v[88:91]
	v_mfma_f32_16x16x32_bf16 v[76:79], v[164:167], v[196:199], v[76:79]
	v_mfma_f32_16x16x32_bf16 v[72:75], v[172:175], v[196:199], v[72:75]
	v_mfma_f32_16x16x32_bf16 v[68:71], v[164:167], v[204:207], v[68:71]
	v_mfma_f32_16x16x32_bf16 v[64:67], v[172:175], v[204:207], v[64:67]
	s_barrier
	s_add_i32 s74, s74, s52
	v_lshl_add_u64 v[214:215], v[208:209], 0, s[20:21]
	s_mov_b32 m0, s74
	s_nop 0
	global_load_lds_dwordx4 v[214:215], off
	v_lshl_add_u64 v[214:215], v[208:209], 0, s[22:23]
	s_add_i32 m0, s74, 0x2000
	s_add_i32 s74, s75, s52
	global_load_lds_dwordx4 v[214:215], off
	v_lshl_add_u64 v[214:215], v[208:209], 0, s[24:25]
	s_mov_b32 m0, s74
	v_lshl_add_u64 v[208:209], v[208:209], 0, s[26:27]
	global_load_lds_dwordx4 v[214:215], off
	s_add_i32 m0, s74, 0x2000
	s_nop 0
	global_load_lds_dwordx4 v[208:209], off
	v_lshl_add_u64 v[208:209], v[212:213], 0, s[20:21]
	s_mov_b32 m0, s58
	s_nop 0
	global_load_lds_dwordx4 v[208:209], off
	v_lshl_add_u64 v[208:209], v[212:213], 0, s[22:23]
	s_mov_b32 m0, s59
	s_nop 0
	global_load_lds_dwordx4 v[208:209], off
	ds_read_b128 v[176:179], v143 offset:49152
	ds_read_b128 v[180:183], v143 offset:50176
	ds_read_b128 v[184:187], v143 offset:51200
	ds_read_b128 v[188:191], v143 offset:52224
	ds_read_b128 v[192:195], v143 offset:53248
	ds_read_b128 v[196:199], v143 offset:54272
	ds_read_b128 v[200:203], v143 offset:55296
	ds_read_b128 v[204:207], v143 offset:56320
	s_waitcnt vmcnt(8)
	s_waitcnt lgkmcnt(0)
	s_barrier
	s_waitcnt lgkmcnt(0)
	v_mfma_f32_16x16x32_bf16 v[60:63], v[144:147], v[176:179], v[60:63]
	v_mfma_f32_16x16x32_bf16 v[56:59], v[152:155], v[176:179], v[56:59]
	v_mfma_f32_16x16x32_bf16 v[52:55], v[144:147], v[184:187], v[52:55]
	v_mfma_f32_16x16x32_bf16 v[48:51], v[152:155], v[184:187], v[48:51]
	v_mfma_f32_16x16x32_bf16 v[36:39], v[144:147], v[192:195], v[36:39]
	v_mfma_f32_16x16x32_bf16 v[32:35], v[152:155], v[192:195], v[32:35]
	v_mfma_f32_16x16x32_bf16 v[20:23], v[144:147], v[200:203], v[20:23]
	v_mfma_f32_16x16x32_bf16 v[16:19], v[152:155], v[200:203], v[16:19]
	v_mfma_f32_16x16x32_bf16 v[60:63], v[148:151], v[180:183], v[60:63]
	v_mfma_f32_16x16x32_bf16 v[56:59], v[156:159], v[180:183], v[56:59]
	v_mfma_f32_16x16x32_bf16 v[52:55], v[148:151], v[188:191], v[52:55]
	v_mfma_f32_16x16x32_bf16 v[48:51], v[156:159], v[188:191], v[48:51]
	v_mfma_f32_16x16x32_bf16 v[36:39], v[148:151], v[196:199], v[36:39]
	v_mfma_f32_16x16x32_bf16 v[32:35], v[156:159], v[196:199], v[32:35]
	v_mfma_f32_16x16x32_bf16 v[20:23], v[148:151], v[204:207], v[20:23]
	v_mfma_f32_16x16x32_bf16 v[16:19], v[156:159], v[204:207], v[16:19]
	v_mfma_f32_16x16x32_bf16 v[44:47], v[160:163], v[176:179], v[44:47]
	v_mfma_f32_16x16x32_bf16 v[40:43], v[168:171], v[176:179], v[40:43]
	v_mfma_f32_16x16x32_bf16 v[28:31], v[160:163], v[184:187], v[28:31]
	v_mfma_f32_16x16x32_bf16 v[24:27], v[168:171], v[184:187], v[24:27]
	v_mfma_f32_16x16x32_bf16 v[12:15], v[160:163], v[192:195], v[12:15]
	v_mfma_f32_16x16x32_bf16 v[8:11], v[168:171], v[192:195], v[8:11]
	v_mfma_f32_16x16x32_bf16 v[4:7], v[160:163], v[200:203], v[4:7]
	v_mfma_f32_16x16x32_bf16 v[0:3], v[168:171], v[200:203], v[0:3]
	v_mfma_f32_16x16x32_bf16 v[44:47], v[164:167], v[180:183], v[44:47]
	v_mfma_f32_16x16x32_bf16 v[40:43], v[172:175], v[180:183], v[40:43]
	v_mfma_f32_16x16x32_bf16 v[28:31], v[164:167], v[188:191], v[28:31]
	v_mfma_f32_16x16x32_bf16 v[24:27], v[172:175], v[188:191], v[24:27]
	v_mfma_f32_16x16x32_bf16 v[12:15], v[164:167], v[196:199], v[12:15]
	v_mfma_f32_16x16x32_bf16 v[8:11], v[172:175], v[196:199], v[8:11]
	v_mfma_f32_16x16x32_bf16 v[4:7], v[164:167], v[204:207], v[4:7]
	v_mfma_f32_16x16x32_bf16 v[0:3], v[172:175], v[204:207], v[0:3]
	s_barrier
	s_cmp_gt_u32 s73, 41
	s_cbranch_scc0 .LBB0_255
	s_and_b64 vcc, exec, s[28:29]
	s_cbranch_vccz .LBB0_258
	s_barrier

.LBB0_386:
	s_add_i32 s70, s70, 2
	s_mov_b32 s42, s70
	s_ashr_i32 s43, s42, 31
	s_lshl_b64 s[72:73], s[42:43], 7
	s_add_u32 s43, s72, 0x100
	s_addc_u32 s71, s73, 0
	s_add_u32 s79, s8, s43
	s_addc_u32 s80, s9, s71
	s_add_u32 s82, s2, s43
	s_addc_u32 s71, s3, s71
	s_add_i32 s83, 0, 0x10000
	s_cmp_eq_u32 s42, 14
	s_cselect_b32 s43, s1, s80
	s_cselect_b32 s42, s57, s79
	s_cselect_b32 s81, s68, s71
	s_cselect_b32 s80, s69, s82
	s_add_i32 s71, 0, 0x14000
	v_add_u32_e32 v140, s83, v220
	v_add_u32_e32 v156, s71, v220
	s_add_u32 s72, s8, s72
	s_addc_u32 s73, s9, s73
	v_lshl_add_u64 v[222:223], s[72:73], 0, v[182:183]
	v_lshl_add_u64 v[224:225], v[222:223], 0, s[14:15]
	s_add_i32 m0, s39, 0xc000
	s_nop 0
	global_load_lds_dwordx4 v[224:225], off
	v_lshl_add_u64 v[222:223], v[222:223], 0, s[16:17]
	s_add_i32 m0, s39, 0xe000
	s_nop 0
	global_load_lds_dwordx4 v[222:223], off
	ds_read_b128 v[128:131], v140
	ds_read_b128 v[132:135], v140 offset:1024
	ds_read_b128 v[136:139], v140 offset:2048
	ds_read_b128 v[140:143], v140 offset:3072
	ds_read_b128 v[144:147], v156
	ds_read_b128 v[148:151], v156 offset:1024
	ds_read_b128 v[152:155], v156 offset:2048
	ds_read_b128 v[156:159], v156 offset:3072
	ds_read_b128 v[160:163], v221
	ds_read_b128 v[164:167], v221 offset:1024
	ds_read_b128 v[186:189], v221 offset:2048
	ds_read_b128 v[190:193], v221 offset:3072
	ds_read_b128 v[194:197], v221 offset:4096
	ds_read_b128 v[198:201], v221 offset:5120
	ds_read_b128 v[202:205], v221 offset:6144
	ds_read_b128 v[206:209], v221 offset:7168
	s_waitcnt vmcnt(8)
	s_waitcnt lgkmcnt(0)
	s_barrier
	s_waitcnt lgkmcnt(0)
	v_mfma_f32_16x16x32_bf16 v[124:127], v[128:131], v[160:163], v[124:127]
	v_mfma_f32_16x16x32_bf16 v[120:123], v[136:139], v[160:163], v[120:123]
	v_mfma_f32_16x16x32_bf16 v[112:115], v[128:131], v[186:189], v[112:115]
	v_mfma_f32_16x16x32_bf16 v[104:107], v[136:139], v[186:189], v[104:107]
	v_mfma_f32_16x16x32_bf16 v[96:99], v[128:131], v[194:197], v[96:99]
	v_mfma_f32_16x16x32_bf16 v[88:91], v[136:139], v[194:197], v[88:91]
	v_mfma_f32_16x16x32_bf16 v[80:83], v[128:131], v[202:205], v[80:83]
	v_mfma_f32_16x16x32_bf16 v[72:75], v[136:139], v[202:205], v[72:75]
	v_mfma_f32_16x16x32_bf16 v[124:127], v[132:135], v[164:167], v[124:127]
	v_mfma_f32_16x16x32_bf16 v[120:123], v[140:143], v[164:167], v[120:123]
	v_mfma_f32_16x16x32_bf16 v[112:115], v[132:135], v[190:193], v[112:115]
	v_mfma_f32_16x16x32_bf16 v[104:107], v[140:143], v[190:193], v[104:107]
	v_mfma_f32_16x16x32_bf16 v[96:99], v[132:135], v[198:201], v[96:99]
	v_mfma_f32_16x16x32_bf16 v[88:91], v[140:143], v[198:201], v[88:91]
	v_mfma_f32_16x16x32_bf16 v[80:83], v[132:135], v[206:209], v[80:83]
	v_mfma_f32_16x16x32_bf16 v[72:75], v[140:143], v[206:209], v[72:75]
	v_mfma_f32_16x16x32_bf16 v[116:119], v[144:147], v[160:163], v[116:119]
	v_mfma_f32_16x16x32_bf16 v[108:111], v[152:155], v[160:163], v[108:111]
	v_mfma_f32_16x16x32_bf16 v[100:103], v[144:147], v[186:189], v[100:103]
	v_mfma_f32_16x16x32_bf16 v[92:95], v[152:155], v[186:189], v[92:95]
	v_mfma_f32_16x16x32_bf16 v[84:87], v[144:147], v[194:197], v[84:87]
	v_mfma_f32_16x16x32_bf16 v[76:79], v[152:155], v[194:197], v[76:79]
	v_mfma_f32_16x16x32_bf16 v[68:71], v[144:147], v[202:205], v[68:71]
	v_mfma_f32_16x16x32_bf16 v[64:67], v[152:155], v[202:205], v[64:67]
	v_mfma_f32_16x16x32_bf16 v[116:119], v[148:151], v[164:167], v[116:119]
	v_mfma_f32_16x16x32_bf16 v[108:111], v[156:159], v[164:167], v[108:111]
	v_mfma_f32_16x16x32_bf16 v[100:103], v[148:151], v[190:193], v[100:103]
	v_mfma_f32_16x16x32_bf16 v[92:95], v[156:159], v[190:193], v[92:95]
	v_mfma_f32_16x16x32_bf16 v[84:87], v[148:151], v[198:201], v[84:87]
	v_mfma_f32_16x16x32_bf16 v[76:79], v[156:159], v[198:201], v[76:79]
	v_mfma_f32_16x16x32_bf16 v[68:71], v[148:151], v[206:209], v[68:71]
	v_mfma_f32_16x16x32_bf16 v[64:67], v[156:159], v[206:209], v[64:67]
	s_barrier
	s_add_i32 s72, s83, s74
	v_lshl_add_u64 v[222:223], s[80:81], 0, v[184:185]
	s_mov_b32 m0, s72
	s_nop 0
	global_load_lds_dwordx4 v[222:223], off
	v_lshl_add_u64 v[224:225], v[222:223], 0, s[40:41]
	s_add_i32 m0, s72, 0x2000
	s_add_i32 s71, s71, s74
	global_load_lds_dwordx4 v[224:225], off
	v_lshl_add_u64 v[224:225], v[222:223], 0, s[4:5]
	s_mov_b32 m0, s71
	s_nop 0
	global_load_lds_dwordx4 v[224:225], off
	v_lshl_add_u64 v[224:225], v[222:223], 0, s[6:7]
	s_add_i32 m0, s71, 0x2000
	s_nop 0
	global_load_lds_dwordx4 v[224:225], off
	v_lshl_add_u64 v[224:225], s[42:43], 0, v[182:183]
	s_mov_b32 m0, s39
	v_lshl_add_u64 v[226:227], v[224:225], 0, s[40:41]
	global_load_lds_dwordx4 v[224:225], off
	s_mov_b32 m0, s75
	s_nop 0
	global_load_lds_dwordx4 v[226:227], off
	ds_read_b128 v[160:163], v221 offset:16384
	ds_read_b128 v[164:167], v221 offset:17408
	ds_read_b128 v[186:189], v221 offset:18432
	ds_read_b128 v[190:193], v221 offset:19456
	ds_read_b128 v[194:197], v221 offset:20480
	ds_read_b128 v[198:201], v221 offset:21504
	ds_read_b128 v[202:205], v221 offset:22528
	ds_read_b128 v[206:209], v221 offset:23552
	s_waitcnt vmcnt(8)
	s_waitcnt lgkmcnt(0)
	s_barrier
	s_waitcnt lgkmcnt(0)
	v_mfma_f32_16x16x32_bf16 v[60:63], v[128:131], v[160:163], v[60:63]
	v_mfma_f32_16x16x32_bf16 v[56:59], v[136:139], v[160:163], v[56:59]
	v_mfma_f32_16x16x32_bf16 v[48:51], v[128:131], v[186:189], v[48:51]
	v_mfma_f32_16x16x32_bf16 v[40:43], v[136:139], v[186:189], v[40:43]
	v_mfma_f32_16x16x32_bf16 v[32:35], v[128:131], v[194:197], v[32:35]
	v_mfma_f32_16x16x32_bf16 v[24:27], v[136:139], v[194:197], v[24:27]
	v_mfma_f32_16x16x32_bf16 v[16:19], v[128:131], v[202:205], v[16:19]
	v_mfma_f32_16x16x32_bf16 v[8:11], v[136:139], v[202:205], v[8:11]
	v_mfma_f32_16x16x32_bf16 v[60:63], v[132:135], v[164:167], v[60:63]
	v_mfma_f32_16x16x32_bf16 v[56:59], v[140:143], v[164:167], v[56:59]
	v_mfma_f32_16x16x32_bf16 v[48:51], v[132:135], v[190:193], v[48:51]
	v_mfma_f32_16x16x32_bf16 v[40:43], v[140:143], v[190:193], v[40:43]
	v_mfma_f32_16x16x32_bf16 v[32:35], v[132:135], v[198:201], v[32:35]
	v_mfma_f32_16x16x32_bf16 v[24:27], v[140:143], v[198:201], v[24:27]
	v_mfma_f32_16x16x32_bf16 v[16:19], v[132:135], v[206:209], v[16:19]
	v_mfma_f32_16x16x32_bf16 v[8:11], v[140:143], v[206:209], v[8:11]
	v_mfma_f32_16x16x32_bf16 v[52:55], v[144:147], v[160:163], v[52:55]
	v_mfma_f32_16x16x32_bf16 v[44:47], v[152:155], v[160:163], v[44:47]
	v_mfma_f32_16x16x32_bf16 v[36:39], v[144:147], v[186:189], v[36:39]
	v_mfma_f32_16x16x32_bf16 v[28:31], v[152:155], v[186:189], v[28:31]
	v_mfma_f32_16x16x32_bf16 v[20:23], v[144:147], v[194:197], v[20:23]
	v_mfma_f32_16x16x32_bf16 v[12:15], v[152:155], v[194:197], v[12:15]
	v_mfma_f32_16x16x32_bf16 v[4:7], v[144:147], v[202:205], v[4:7]
	v_mfma_f32_16x16x32_bf16 v[0:3], v[152:155], v[202:205], v[0:3]
	v_mfma_f32_16x16x32_bf16 v[52:55], v[148:151], v[164:167], v[52:55]
	v_mfma_f32_16x16x32_bf16 v[44:47], v[156:159], v[164:167], v[44:47]
	v_mfma_f32_16x16x32_bf16 v[36:39], v[148:151], v[190:193], v[36:39]
	v_mfma_f32_16x16x32_bf16 v[28:31], v[156:159], v[190:193], v[28:31]
	v_mfma_f32_16x16x32_bf16 v[20:23], v[148:151], v[198:201], v[20:23]
	v_mfma_f32_16x16x32_bf16 v[12:15], v[156:159], v[198:201], v[12:15]
	v_mfma_f32_16x16x32_bf16 v[4:7], v[148:151], v[206:209], v[4:7]
	v_mfma_f32_16x16x32_bf16 v[0:3], v[156:159], v[206:209], v[0:3]
	s_barrier
	s_add_i32 s42, 0, 0x18000
	s_add_i32 s43, 0, 0x1c000
	v_add_u32_e32 v140, s42, v220
	v_add_u32_e32 v156, s43, v220
	s_mov_b32 m0, s30
	v_lshl_add_u64 v[226:227], v[224:225], 0, s[4:5]
	global_load_lds_dwordx4 v[226:227], off
	v_lshl_add_u64 v[226:227], v[224:225], 0, s[6:7]
	s_mov_b32 m0, s31
	s_nop 0
	global_load_lds_dwordx4 v[226:227], off
	ds_read_b128 v[128:131], v140
	ds_read_b128 v[132:135], v140 offset:1024
	ds_read_b128 v[136:139], v140 offset:2048
	ds_read_b128 v[140:143], v140 offset:3072
	ds_read_b128 v[144:147], v156
	ds_read_b128 v[148:151], v156 offset:1024
	ds_read_b128 v[152:155], v156 offset:2048
	ds_read_b128 v[156:159], v156 offset:3072
	ds_read_b128 v[160:163], v221 offset:32768
	ds_read_b128 v[164:167], v221 offset:33792
	ds_read_b128 v[186:189], v221 offset:34816
	ds_read_b128 v[190:193], v221 offset:35840
	ds_read_b128 v[194:197], v221 offset:36864
	ds_read_b128 v[198:201], v221 offset:37888
	ds_read_b128 v[202:205], v221 offset:38912
	ds_read_b128 v[206:209], v221 offset:39936
	s_waitcnt vmcnt(8)
	s_waitcnt lgkmcnt(0)
	s_barrier
	s_waitcnt lgkmcnt(0)
	v_mfma_f32_16x16x32_bf16 v[124:127], v[128:131], v[160:163], v[124:127]
	v_mfma_f32_16x16x32_bf16 v[120:123], v[136:139], v[160:163], v[120:123]
	v_mfma_f32_16x16x32_bf16 v[112:115], v[128:131], v[186:189], v[112:115]
	v_mfma_f32_16x16x32_bf16 v[104:107], v[136:139], v[186:189], v[104:107]
	v_mfma_f32_16x16x32_bf16 v[96:99], v[128:131], v[194:197], v[96:99]
	v_mfma_f32_16x16x32_bf16 v[88:91], v[136:139], v[194:197], v[88:91]
	v_mfma_f32_16x16x32_bf16 v[80:83], v[128:131], v[202:205], v[80:83]
	v_mfma_f32_16x16x32_bf16 v[72:75], v[136:139], v[202:205], v[72:75]
	v_mfma_f32_16x16x32_bf16 v[124:127], v[132:135], v[164:167], v[124:127]
	v_mfma_f32_16x16x32_bf16 v[120:123], v[140:143], v[164:167], v[120:123]
	v_mfma_f32_16x16x32_bf16 v[112:115], v[132:135], v[190:193], v[112:115]
	v_mfma_f32_16x16x32_bf16 v[104:107], v[140:143], v[190:193], v[104:107]
	v_mfma_f32_16x16x32_bf16 v[96:99], v[132:135], v[198:201], v[96:99]
	v_mfma_f32_16x16x32_bf16 v[88:91], v[140:143], v[198:201], v[88:91]
	v_mfma_f32_16x16x32_bf16 v[80:83], v[132:135], v[206:209], v[80:83]
	v_mfma_f32_16x16x32_bf16 v[72:75], v[140:143], v[206:209], v[72:75]
	v_mfma_f32_16x16x32_bf16 v[116:119], v[144:147], v[160:163], v[116:119]
	v_mfma_f32_16x16x32_bf16 v[108:111], v[152:155], v[160:163], v[108:111]
	v_mfma_f32_16x16x32_bf16 v[100:103], v[144:147], v[186:189], v[100:103]
	v_mfma_f32_16x16x32_bf16 v[92:95], v[152:155], v[186:189], v[92:95]
	v_mfma_f32_16x16x32_bf16 v[84:87], v[144:147], v[194:197], v[84:87]
	v_mfma_f32_16x16x32_bf16 v[76:79], v[152:155], v[194:197], v[76:79]
	v_mfma_f32_16x16x32_bf16 v[68:71], v[144:147], v[202:205], v[68:71]
	v_mfma_f32_16x16x32_bf16 v[64:67], v[152:155], v[202:205], v[64:67]
	v_mfma_f32_16x16x32_bf16 v[116:119], v[148:151], v[164:167], v[116:119]
	v_mfma_f32_16x16x32_bf16 v[108:111], v[156:159], v[164:167], v[108:111]
	v_mfma_f32_16x16x32_bf16 v[100:103], v[148:151], v[190:193], v[100:103]
	v_mfma_f32_16x16x32_bf16 v[92:95], v[156:159], v[190:193], v[92:95]
	v_mfma_f32_16x16x32_bf16 v[84:87], v[148:151], v[198:201], v[84:87]
	v_mfma_f32_16x16x32_bf16 v[76:79], v[156:159], v[198:201], v[76:79]
	v_mfma_f32_16x16x32_bf16 v[68:71], v[148:151], v[206:209], v[68:71]
	v_mfma_f32_16x16x32_bf16 v[64:67], v[156:159], v[206:209], v[64:67]
	s_barrier
	s_add_i32 s42, s42, s74
	v_lshl_add_u64 v[226:227], v[222:223], 0, s[10:11]
	s_mov_b32 m0, s42
	s_nop 0
	global_load_lds_dwordx4 v[226:227], off
	v_lshl_add_u64 v[226:227], v[222:223], 0, s[12:13]
	s_add_i32 m0, s42, 0x2000
	s_add_i32 s42, s43, s74
	global_load_lds_dwordx4 v[226:227], off
	v_lshl_add_u64 v[226:227], v[222:223], 0, s[14:15]
	s_mov_b32 m0, s42
	v_lshl_add_u64 v[222:223], v[222:223], 0, s[16:17]
	global_load_lds_dwordx4 v[226:227], off
	s_add_i32 m0, s42, 0x2000
	s_nop 0
	global_load_lds_dwordx4 v[222:223], off
	v_lshl_add_u64 v[222:223], v[224:225], 0, s[10:11]
	s_mov_b32 m0, s26
	s_nop 0
	global_load_lds_dwordx4 v[222:223], off
	v_lshl_add_u64 v[222:223], v[224:225], 0, s[12:13]
	s_mov_b32 m0, s27
	s_nop 0
	global_load_lds_dwordx4 v[222:223], off
	ds_read_b128 v[160:163], v221 offset:49152
	ds_read_b128 v[164:167], v221 offset:50176
	ds_read_b128 v[186:189], v221 offset:51200
	ds_read_b128 v[190:193], v221 offset:52224
	ds_read_b128 v[194:197], v221 offset:53248
	ds_read_b128 v[198:201], v221 offset:54272
	ds_read_b128 v[202:205], v221 offset:55296
	ds_read_b128 v[206:209], v221 offset:56320
	s_waitcnt vmcnt(8)
	s_waitcnt lgkmcnt(0)
	s_barrier
	s_waitcnt lgkmcnt(0)
	v_mfma_f32_16x16x32_bf16 v[60:63], v[128:131], v[160:163], v[60:63]
	v_mfma_f32_16x16x32_bf16 v[56:59], v[136:139], v[160:163], v[56:59]
	v_mfma_f32_16x16x32_bf16 v[48:51], v[128:131], v[186:189], v[48:51]
	v_mfma_f32_16x16x32_bf16 v[40:43], v[136:139], v[186:189], v[40:43]
	v_mfma_f32_16x16x32_bf16 v[32:35], v[128:131], v[194:197], v[32:35]
	v_mfma_f32_16x16x32_bf16 v[24:27], v[136:139], v[194:197], v[24:27]
	v_mfma_f32_16x16x32_bf16 v[16:19], v[128:131], v[202:205], v[16:19]
	v_mfma_f32_16x16x32_bf16 v[8:11], v[136:139], v[202:205], v[8:11]
	v_mfma_f32_16x16x32_bf16 v[60:63], v[132:135], v[164:167], v[60:63]
	v_mfma_f32_16x16x32_bf16 v[56:59], v[140:143], v[164:167], v[56:59]
	v_mfma_f32_16x16x32_bf16 v[48:51], v[132:135], v[190:193], v[48:51]
	v_mfma_f32_16x16x32_bf16 v[40:43], v[140:143], v[190:193], v[40:43]
	v_mfma_f32_16x16x32_bf16 v[32:35], v[132:135], v[198:201], v[32:35]
	v_mfma_f32_16x16x32_bf16 v[24:27], v[140:143], v[198:201], v[24:27]
	v_mfma_f32_16x16x32_bf16 v[16:19], v[132:135], v[206:209], v[16:19]
	v_mfma_f32_16x16x32_bf16 v[8:11], v[140:143], v[206:209], v[8:11]
	v_mfma_f32_16x16x32_bf16 v[52:55], v[144:147], v[160:163], v[52:55]
	v_mfma_f32_16x16x32_bf16 v[44:47], v[152:155], v[160:163], v[44:47]
	v_mfma_f32_16x16x32_bf16 v[36:39], v[144:147], v[186:189], v[36:39]
	v_mfma_f32_16x16x32_bf16 v[28:31], v[152:155], v[186:189], v[28:31]
	v_mfma_f32_16x16x32_bf16 v[20:23], v[144:147], v[194:197], v[20:23]
	v_mfma_f32_16x16x32_bf16 v[12:15], v[152:155], v[194:197], v[12:15]
	v_mfma_f32_16x16x32_bf16 v[4:7], v[144:147], v[202:205], v[4:7]
	v_mfma_f32_16x16x32_bf16 v[0:3], v[152:155], v[202:205], v[0:3]
	v_mfma_f32_16x16x32_bf16 v[52:55], v[148:151], v[164:167], v[52:55]
	v_mfma_f32_16x16x32_bf16 v[44:47], v[156:159], v[164:167], v[44:47]
	v_mfma_f32_16x16x32_bf16 v[36:39], v[148:151], v[190:193], v[36:39]
	v_mfma_f32_16x16x32_bf16 v[28:31], v[156:159], v[190:193], v[28:31]
	v_mfma_f32_16x16x32_bf16 v[20:23], v[148:151], v[198:201], v[20:23]
	v_mfma_f32_16x16x32_bf16 v[12:15], v[156:159], v[198:201], v[12:15]
	v_mfma_f32_16x16x32_bf16 v[4:7], v[148:151], v[206:209], v[4:7]
	v_mfma_f32_16x16x32_bf16 v[0:3], v[156:159], v[206:209], v[0:3]
	s_barrier
	s_cmp_gt_u32 s70, 13
	s_cbranch_scc0 .LBB0_386
	s_and_b64 vcc, exec, s[58:59]
	s_cbranch_vccz .LBB0_389
	s_barrier

.LBB0_760:
	s_add_i32 s78, s78, 2
	s_mov_b32 s50, s78
	s_ashr_i32 s51, s50, 31
	s_lshl_b64 s[80:81], s[50:51], 7
	s_add_u32 s51, s80, 0x100
	s_addc_u32 s79, s81, 0
	s_add_u32 s82, s48, s51
	s_addc_u32 s83, s49, s79
	s_add_u32 s84, s8, s51
	s_addc_u32 s79, s9, s79
	s_add_i32 s85, 0, 0x10000
	s_cmp_eq_u32 s50, 14
	s_cselect_b32 s51, s35, s83
	s_cselect_b32 s50, s76, s82
	s_cselect_b32 s83, s31, s79
	s_cselect_b32 s82, s77, s84
	s_add_i32 s79, 0, 0x14000
	s_add_u32 s80, s48, s80
	s_addc_u32 s81, s49, s81
	v_lshl_add_u64 v[134:135], s[80:81], 0, v[128:129]
	v_lshl_add_u64 v[224:225], v[134:135], 0, s[14:15]
	s_add_i32 m0, s62, 0xc000
	s_nop 0
	global_load_lds_dwordx4 v[224:225], off
	v_lshl_add_u64 v[134:135], v[134:135], 0, s[16:17]
	s_add_i32 m0, s62, 0xe000
	s_nop 0
	global_load_lds_dwordx4 v[134:135], off
	v_add_u32_e32 v134, s85, v137
	ds_read_b128 v[130:133], v134
	ds_read_b128 v[140:143], v134 offset:1024
	ds_read_b128 v[144:147], v134 offset:2048
	ds_read_b128 v[148:151], v134 offset:3072
	v_add_u32_e32 v134, s79, v137
	ds_read_b128 v[152:155], v134
	ds_read_b128 v[156:159], v134 offset:1024
	ds_read_b128 v[160:163], v134 offset:2048
	ds_read_b128 v[164:167], v134 offset:3072
	ds_read_b128 v[182:185], v138
	ds_read_b128 v[186:189], v138 offset:1024
	ds_read_b128 v[190:193], v138 offset:2048
	ds_read_b128 v[194:197], v138 offset:3072
	ds_read_b128 v[198:201], v138 offset:4096
	ds_read_b128 v[202:205], v138 offset:5120
	ds_read_b128 v[206:209], v138 offset:6144
	ds_read_b128 v[220:223], v138 offset:7168
	s_nop 0
	s_waitcnt vmcnt(8)
	s_waitcnt lgkmcnt(0)
	s_barrier
	s_waitcnt lgkmcnt(0)
	v_mfma_f32_16x16x32_bf16 v[124:127], v[130:133], v[182:185], v[124:127]
	v_mfma_f32_16x16x32_bf16 v[120:123], v[144:147], v[182:185], v[120:123]
	v_mfma_f32_16x16x32_bf16 v[108:111], v[130:133], v[190:193], v[108:111]
	v_mfma_f32_16x16x32_bf16 v[104:107], v[144:147], v[190:193], v[104:107]
	v_mfma_f32_16x16x32_bf16 v[92:95], v[130:133], v[198:201], v[92:95]
	v_mfma_f32_16x16x32_bf16 v[88:91], v[144:147], v[198:201], v[88:91]
	v_mfma_f32_16x16x32_bf16 v[76:79], v[130:133], v[206:209], v[76:79]
	v_mfma_f32_16x16x32_bf16 v[72:75], v[144:147], v[206:209], v[72:75]
	v_mfma_f32_16x16x32_bf16 v[124:127], v[140:143], v[186:189], v[124:127]
	v_mfma_f32_16x16x32_bf16 v[120:123], v[148:151], v[186:189], v[120:123]
	v_mfma_f32_16x16x32_bf16 v[108:111], v[140:143], v[194:197], v[108:111]
	v_mfma_f32_16x16x32_bf16 v[104:107], v[148:151], v[194:197], v[104:107]
	v_mfma_f32_16x16x32_bf16 v[92:95], v[140:143], v[202:205], v[92:95]
	v_mfma_f32_16x16x32_bf16 v[88:91], v[148:151], v[202:205], v[88:91]
	v_mfma_f32_16x16x32_bf16 v[76:79], v[140:143], v[220:223], v[76:79]
	v_mfma_f32_16x16x32_bf16 v[72:75], v[148:151], v[220:223], v[72:75]
	v_mfma_f32_16x16x32_bf16 v[116:119], v[152:155], v[182:185], v[116:119]
	v_mfma_f32_16x16x32_bf16 v[112:115], v[160:163], v[182:185], v[112:115]
	v_mfma_f32_16x16x32_bf16 v[100:103], v[152:155], v[190:193], v[100:103]
	v_mfma_f32_16x16x32_bf16 v[96:99], v[160:163], v[190:193], v[96:99]
	v_mfma_f32_16x16x32_bf16 v[84:87], v[152:155], v[198:201], v[84:87]
	v_mfma_f32_16x16x32_bf16 v[80:83], v[160:163], v[198:201], v[80:83]
	v_mfma_f32_16x16x32_bf16 v[68:71], v[152:155], v[206:209], v[68:71]
	v_mfma_f32_16x16x32_bf16 v[64:67], v[160:163], v[206:209], v[64:67]
	v_mfma_f32_16x16x32_bf16 v[116:119], v[156:159], v[186:189], v[116:119]
	v_mfma_f32_16x16x32_bf16 v[112:115], v[164:167], v[186:189], v[112:115]
	v_mfma_f32_16x16x32_bf16 v[100:103], v[156:159], v[194:197], v[100:103]
	v_mfma_f32_16x16x32_bf16 v[96:99], v[164:167], v[194:197], v[96:99]
	v_mfma_f32_16x16x32_bf16 v[84:87], v[156:159], v[202:205], v[84:87]
	v_mfma_f32_16x16x32_bf16 v[80:83], v[164:167], v[202:205], v[80:83]
	v_mfma_f32_16x16x32_bf16 v[68:71], v[156:159], v[220:223], v[68:71]
	v_mfma_f32_16x16x32_bf16 v[64:67], v[164:167], v[220:223], v[64:67]
	s_barrier
	s_add_i32 s80, s85, s59
	v_lshl_add_u64 v[134:135], s[82:83], 0, v[172:173]
	s_mov_b32 m0, s80
	s_nop 0
	global_load_lds_dwordx4 v[134:135], off
	v_lshl_add_u64 v[224:225], v[134:135], 0, s[40:41]
	s_add_i32 m0, s80, 0x2000
	s_add_i32 s79, s79, s59
	global_load_lds_dwordx4 v[224:225], off
	v_lshl_add_u64 v[224:225], v[134:135], 0, s[4:5]
	s_mov_b32 m0, s79
	s_nop 0
	global_load_lds_dwordx4 v[224:225], off
	v_lshl_add_u64 v[224:225], v[134:135], 0, s[6:7]
	s_add_i32 m0, s79, 0x2000
	s_nop 0
	global_load_lds_dwordx4 v[224:225], off
	v_lshl_add_u64 v[224:225], s[50:51], 0, v[128:129]
	s_mov_b32 m0, s62
	v_lshl_add_u64 v[226:227], v[224:225], 0, s[40:41]
	global_load_lds_dwordx4 v[224:225], off
	s_mov_b32 m0, s63
	s_nop 0
	global_load_lds_dwordx4 v[226:227], off
	ds_read_b128 v[182:185], v138 offset:16384
	ds_read_b128 v[186:189], v138 offset:17408
	ds_read_b128 v[190:193], v138 offset:18432
	ds_read_b128 v[194:197], v138 offset:19456
	ds_read_b128 v[198:201], v138 offset:20480
	ds_read_b128 v[202:205], v138 offset:21504
	ds_read_b128 v[206:209], v138 offset:22528
	ds_read_b128 v[220:223], v138 offset:23552
	s_waitcnt vmcnt(8)
	s_waitcnt lgkmcnt(0)
	s_barrier
	s_waitcnt lgkmcnt(0)
	v_mfma_f32_16x16x32_bf16 v[60:63], v[130:133], v[182:185], v[60:63]
	v_mfma_f32_16x16x32_bf16 v[56:59], v[144:147], v[182:185], v[56:59]
	v_mfma_f32_16x16x32_bf16 v[44:47], v[130:133], v[190:193], v[44:47]
	v_mfma_f32_16x16x32_bf16 v[40:43], v[144:147], v[190:193], v[40:43]
	v_mfma_f32_16x16x32_bf16 v[28:31], v[130:133], v[198:201], v[28:31]
	v_mfma_f32_16x16x32_bf16 v[24:27], v[144:147], v[198:201], v[24:27]
	v_mfma_f32_16x16x32_bf16 v[12:15], v[130:133], v[206:209], v[12:15]
	v_mfma_f32_16x16x32_bf16 v[8:11], v[144:147], v[206:209], v[8:11]
	v_mfma_f32_16x16x32_bf16 v[60:63], v[140:143], v[186:189], v[60:63]
	v_mfma_f32_16x16x32_bf16 v[56:59], v[148:151], v[186:189], v[56:59]
	v_mfma_f32_16x16x32_bf16 v[44:47], v[140:143], v[194:197], v[44:47]
	v_mfma_f32_16x16x32_bf16 v[40:43], v[148:151], v[194:197], v[40:43]
	v_mfma_f32_16x16x32_bf16 v[28:31], v[140:143], v[202:205], v[28:31]
	v_mfma_f32_16x16x32_bf16 v[24:27], v[148:151], v[202:205], v[24:27]
	v_mfma_f32_16x16x32_bf16 v[12:15], v[140:143], v[220:223], v[12:15]
	v_mfma_f32_16x16x32_bf16 v[8:11], v[148:151], v[220:223], v[8:11]
	v_mfma_f32_16x16x32_bf16 v[52:55], v[152:155], v[182:185], v[52:55]
	v_mfma_f32_16x16x32_bf16 v[48:51], v[160:163], v[182:185], v[48:51]
	v_mfma_f32_16x16x32_bf16 v[36:39], v[152:155], v[190:193], v[36:39]
	v_mfma_f32_16x16x32_bf16 v[32:35], v[160:163], v[190:193], v[32:35]
	v_mfma_f32_16x16x32_bf16 v[20:23], v[152:155], v[198:201], v[20:23]
	v_mfma_f32_16x16x32_bf16 v[16:19], v[160:163], v[198:201], v[16:19]
	v_mfma_f32_16x16x32_bf16 v[4:7], v[152:155], v[206:209], v[4:7]
	v_mfma_f32_16x16x32_bf16 v[0:3], v[160:163], v[206:209], v[0:3]
	v_mfma_f32_16x16x32_bf16 v[52:55], v[156:159], v[186:189], v[52:55]
	v_mfma_f32_16x16x32_bf16 v[48:51], v[164:167], v[186:189], v[48:51]
	v_mfma_f32_16x16x32_bf16 v[36:39], v[156:159], v[194:197], v[36:39]
	v_mfma_f32_16x16x32_bf16 v[32:35], v[164:167], v[194:197], v[32:35]
	v_mfma_f32_16x16x32_bf16 v[20:23], v[156:159], v[202:205], v[20:23]
	v_mfma_f32_16x16x32_bf16 v[16:19], v[164:167], v[202:205], v[16:19]
	v_mfma_f32_16x16x32_bf16 v[4:7], v[156:159], v[220:223], v[4:7]
	v_mfma_f32_16x16x32_bf16 v[0:3], v[164:167], v[220:223], v[0:3]
	s_barrier
	s_mov_b32 m0, s68
	v_lshl_add_u64 v[226:227], v[224:225], 0, s[4:5]
	global_load_lds_dwordx4 v[226:227], off
	v_lshl_add_u64 v[226:227], v[224:225], 0, s[6:7]
	s_mov_b32 m0, s69
	s_nop 0
	global_load_lds_dwordx4 v[226:227], off
	s_add_i32 s50, 0, 0x18000
	v_add_u32_e32 v139, s50, v137
	s_add_i32 s51, 0, 0x1c000
	ds_read_b128 v[130:133], v139
	ds_read_b128 v[140:143], v139 offset:1024
	ds_read_b128 v[144:147], v139 offset:2048
	ds_read_b128 v[148:151], v139 offset:3072
	v_add_u32_e32 v139, s51, v137
	ds_read_b128 v[152:155], v139
	ds_read_b128 v[156:159], v139 offset:1024
	ds_read_b128 v[160:163], v139 offset:2048
	ds_read_b128 v[164:167], v139 offset:3072
	ds_read_b128 v[182:185], v138 offset:32768
	ds_read_b128 v[186:189], v138 offset:33792
	ds_read_b128 v[190:193], v138 offset:34816
	ds_read_b128 v[194:197], v138 offset:35840
	ds_read_b128 v[198:201], v138 offset:36864
	ds_read_b128 v[202:205], v138 offset:37888
	ds_read_b128 v[206:209], v138 offset:38912
	ds_read_b128 v[220:223], v138 offset:39936
	s_nop 0
	s_waitcnt vmcnt(8)
	s_waitcnt lgkmcnt(0)
	s_barrier
	s_waitcnt lgkmcnt(0)
	v_mfma_f32_16x16x32_bf16 v[124:127], v[130:133], v[182:185], v[124:127]
	v_mfma_f32_16x16x32_bf16 v[120:123], v[144:147], v[182:185], v[120:123]
	v_mfma_f32_16x16x32_bf16 v[108:111], v[130:133], v[190:193], v[108:111]
	v_mfma_f32_16x16x32_bf16 v[104:107], v[144:147], v[190:193], v[104:107]
	v_mfma_f32_16x16x32_bf16 v[92:95], v[130:133], v[198:201], v[92:95]
	v_mfma_f32_16x16x32_bf16 v[88:91], v[144:147], v[198:201], v[88:91]
	v_mfma_f32_16x16x32_bf16 v[76:79], v[130:133], v[206:209], v[76:79]
	v_mfma_f32_16x16x32_bf16 v[72:75], v[144:147], v[206:209], v[72:75]
	v_mfma_f32_16x16x32_bf16 v[124:127], v[140:143], v[186:189], v[124:127]
	v_mfma_f32_16x16x32_bf16 v[120:123], v[148:151], v[186:189], v[120:123]
	v_mfma_f32_16x16x32_bf16 v[108:111], v[140:143], v[194:197], v[108:111]
	v_mfma_f32_16x16x32_bf16 v[104:107], v[148:151], v[194:197], v[104:107]
	v_mfma_f32_16x16x32_bf16 v[92:95], v[140:143], v[202:205], v[92:95]
	v_mfma_f32_16x16x32_bf16 v[88:91], v[148:151], v[202:205], v[88:91]
	v_mfma_f32_16x16x32_bf16 v[76:79], v[140:143], v[220:223], v[76:79]
	v_mfma_f32_16x16x32_bf16 v[72:75], v[148:151], v[220:223], v[72:75]
	v_mfma_f32_16x16x32_bf16 v[116:119], v[152:155], v[182:185], v[116:119]
	v_mfma_f32_16x16x32_bf16 v[112:115], v[160:163], v[182:185], v[112:115]
	v_mfma_f32_16x16x32_bf16 v[100:103], v[152:155], v[190:193], v[100:103]
	v_mfma_f32_16x16x32_bf16 v[96:99], v[160:163], v[190:193], v[96:99]
	v_mfma_f32_16x16x32_bf16 v[84:87], v[152:155], v[198:201], v[84:87]
	v_mfma_f32_16x16x32_bf16 v[80:83], v[160:163], v[198:201], v[80:83]
	v_mfma_f32_16x16x32_bf16 v[68:71], v[152:155], v[206:209], v[68:71]
	v_mfma_f32_16x16x32_bf16 v[64:67], v[160:163], v[206:209], v[64:67]
	v_mfma_f32_16x16x32_bf16 v[116:119], v[156:159], v[186:189], v[116:119]
	v_mfma_f32_16x16x32_bf16 v[112:115], v[164:167], v[186:189], v[112:115]
	v_mfma_f32_16x16x32_bf16 v[100:103], v[156:159], v[194:197], v[100:103]
	v_mfma_f32_16x16x32_bf16 v[96:99], v[164:167], v[194:197], v[96:99]
	v_mfma_f32_16x16x32_bf16 v[84:87], v[156:159], v[202:205], v[84:87]
	v_mfma_f32_16x16x32_bf16 v[80:83], v[164:167], v[202:205], v[80:83]
	v_mfma_f32_16x16x32_bf16 v[68:71], v[156:159], v[220:223], v[68:71]
	v_mfma_f32_16x16x32_bf16 v[64:67], v[164:167], v[220:223], v[64:67]
	s_barrier
	s_add_i32 s50, s50, s59
	v_lshl_add_u64 v[226:227], v[134:135], 0, s[10:11]
	s_mov_b32 m0, s50
	s_nop 0
	global_load_lds_dwordx4 v[226:227], off
	v_lshl_add_u64 v[226:227], v[134:135], 0, s[12:13]
	s_add_i32 m0, s50, 0x2000
	s_add_i32 s50, s51, s59
	global_load_lds_dwordx4 v[226:227], off
	v_lshl_add_u64 v[226:227], v[134:135], 0, s[14:15]
	s_mov_b32 m0, s50
	v_lshl_add_u64 v[134:135], v[134:135], 0, s[16:17]
	global_load_lds_dwordx4 v[226:227], off
	s_add_i32 m0, s50, 0x2000
	s_nop 0
	global_load_lds_dwordx4 v[134:135], off
	v_lshl_add_u64 v[134:135], v[224:225], 0, s[10:11]
	s_mov_b32 m0, s72
	s_nop 0
	global_load_lds_dwordx4 v[134:135], off
	v_lshl_add_u64 v[134:135], v[224:225], 0, s[12:13]
	s_mov_b32 m0, s73
	s_nop 0
	global_load_lds_dwordx4 v[134:135], off
	ds_read_b128 v[182:185], v138 offset:49152
	ds_read_b128 v[186:189], v138 offset:50176
	ds_read_b128 v[190:193], v138 offset:51200
	ds_read_b128 v[194:197], v138 offset:52224
	ds_read_b128 v[198:201], v138 offset:53248
	ds_read_b128 v[202:205], v138 offset:54272
	ds_read_b128 v[206:209], v138 offset:55296
	ds_read_b128 v[220:223], v138 offset:56320
	s_waitcnt vmcnt(8)
	s_waitcnt lgkmcnt(0)
	s_barrier
	s_waitcnt lgkmcnt(0)
	v_mfma_f32_16x16x32_bf16 v[60:63], v[130:133], v[182:185], v[60:63]
	v_mfma_f32_16x16x32_bf16 v[56:59], v[144:147], v[182:185], v[56:59]
	v_mfma_f32_16x16x32_bf16 v[44:47], v[130:133], v[190:193], v[44:47]
	v_mfma_f32_16x16x32_bf16 v[40:43], v[144:147], v[190:193], v[40:43]
	v_mfma_f32_16x16x32_bf16 v[28:31], v[130:133], v[198:201], v[28:31]
	v_mfma_f32_16x16x32_bf16 v[24:27], v[144:147], v[198:201], v[24:27]
	v_mfma_f32_16x16x32_bf16 v[12:15], v[130:133], v[206:209], v[12:15]
	v_mfma_f32_16x16x32_bf16 v[8:11], v[144:147], v[206:209], v[8:11]
	v_mfma_f32_16x16x32_bf16 v[60:63], v[140:143], v[186:189], v[60:63]
	v_mfma_f32_16x16x32_bf16 v[56:59], v[148:151], v[186:189], v[56:59]
	v_mfma_f32_16x16x32_bf16 v[44:47], v[140:143], v[194:197], v[44:47]
	v_mfma_f32_16x16x32_bf16 v[40:43], v[148:151], v[194:197], v[40:43]
	v_mfma_f32_16x16x32_bf16 v[28:31], v[140:143], v[202:205], v[28:31]
	v_mfma_f32_16x16x32_bf16 v[24:27], v[148:151], v[202:205], v[24:27]
	v_mfma_f32_16x16x32_bf16 v[12:15], v[140:143], v[220:223], v[12:15]
	v_mfma_f32_16x16x32_bf16 v[8:11], v[148:151], v[220:223], v[8:11]
	v_mfma_f32_16x16x32_bf16 v[52:55], v[152:155], v[182:185], v[52:55]
	v_mfma_f32_16x16x32_bf16 v[48:51], v[160:163], v[182:185], v[48:51]
	v_mfma_f32_16x16x32_bf16 v[36:39], v[152:155], v[190:193], v[36:39]
	v_mfma_f32_16x16x32_bf16 v[32:35], v[160:163], v[190:193], v[32:35]
	v_mfma_f32_16x16x32_bf16 v[20:23], v[152:155], v[198:201], v[20:23]
	v_mfma_f32_16x16x32_bf16 v[16:19], v[160:163], v[198:201], v[16:19]
	v_mfma_f32_16x16x32_bf16 v[4:7], v[152:155], v[206:209], v[4:7]
	v_mfma_f32_16x16x32_bf16 v[0:3], v[160:163], v[206:209], v[0:3]
	v_mfma_f32_16x16x32_bf16 v[52:55], v[156:159], v[186:189], v[52:55]
	v_mfma_f32_16x16x32_bf16 v[48:51], v[164:167], v[186:189], v[48:51]
	v_mfma_f32_16x16x32_bf16 v[36:39], v[156:159], v[194:197], v[36:39]
	v_mfma_f32_16x16x32_bf16 v[32:35], v[164:167], v[194:197], v[32:35]
	v_mfma_f32_16x16x32_bf16 v[20:23], v[156:159], v[202:205], v[20:23]
	v_mfma_f32_16x16x32_bf16 v[16:19], v[164:167], v[202:205], v[16:19]
	v_mfma_f32_16x16x32_bf16 v[4:7], v[156:159], v[220:223], v[4:7]
	v_mfma_f32_16x16x32_bf16 v[0:3], v[164:167], v[220:223], v[0:3]
	s_barrier
	s_cmp_gt_u32 s78, 13
	s_cbranch_scc0 .LBB0_760
	s_and_b64 vcc, exec, s[28:29]
	s_cbranch_vccz .LBB0_763
	s_barrier

.LBB0_784:
	s_add_i32 s80, s80, 2
	s_mov_b32 s48, s80
	s_ashr_i32 s49, s48, 31
	s_lshl_b64 s[82:83], s[48:49], 7
	s_add_u32 s49, s82, 0x100
	s_addc_u32 s81, s83, 0
	s_add_u32 s84, s42, s49
	s_addc_u32 s85, s43, s81
	s_add_u32 s86, s8, s49
	s_addc_u32 s81, s9, s81
	s_add_i32 s87, 0, 0x10000
	s_cmp_eq_u32 s48, 14
	s_cselect_b32 s49, s39, s85
	s_cselect_b32 s48, s72, s84
	s_cselect_b32 s85, s35, s81
	s_cselect_b32 s84, s73, s86
	s_add_i32 s81, 0, 0x14000
	s_add_u32 s82, s42, s82
	s_addc_u32 s83, s43, s83
	v_lshl_add_u64 v[134:135], s[82:83], 0, v[128:129]
	v_lshl_add_u64 v[224:225], v[134:135], 0, s[14:15]
	s_add_i32 m0, s74, 0xc000
	s_nop 0
	global_load_lds_dwordx4 v[224:225], off
	v_lshl_add_u64 v[134:135], v[134:135], 0, s[16:17]
	s_add_i32 m0, s74, 0xe000
	s_nop 0
	global_load_lds_dwordx4 v[134:135], off
	v_add_u32_e32 v134, s87, v137
	ds_read_b128 v[130:133], v134
	ds_read_b128 v[140:143], v134 offset:1024
	ds_read_b128 v[144:147], v134 offset:2048
	ds_read_b128 v[148:151], v134 offset:3072
	v_add_u32_e32 v134, s81, v137
	ds_read_b128 v[152:155], v134
	ds_read_b128 v[156:159], v134 offset:1024
	ds_read_b128 v[160:163], v134 offset:2048
	ds_read_b128 v[164:167], v134 offset:3072
	ds_read_b128 v[182:185], v138
	ds_read_b128 v[186:189], v138 offset:1024
	ds_read_b128 v[190:193], v138 offset:2048
	ds_read_b128 v[194:197], v138 offset:3072
	ds_read_b128 v[198:201], v138 offset:4096
	ds_read_b128 v[202:205], v138 offset:5120
	ds_read_b128 v[206:209], v138 offset:6144
	ds_read_b128 v[220:223], v138 offset:7168
	s_nop 0
	s_waitcnt vmcnt(8)
	s_waitcnt lgkmcnt(0)
	s_barrier
	s_waitcnt lgkmcnt(0)
	v_mfma_f32_16x16x32_bf16 v[124:127], v[130:133], v[182:185], v[124:127]
	v_mfma_f32_16x16x32_bf16 v[120:123], v[144:147], v[182:185], v[120:123]
	v_mfma_f32_16x16x32_bf16 v[108:111], v[130:133], v[190:193], v[108:111]
	v_mfma_f32_16x16x32_bf16 v[104:107], v[144:147], v[190:193], v[104:107]
	v_mfma_f32_16x16x32_bf16 v[92:95], v[130:133], v[198:201], v[92:95]
	v_mfma_f32_16x16x32_bf16 v[88:91], v[144:147], v[198:201], v[88:91]
	v_mfma_f32_16x16x32_bf16 v[76:79], v[130:133], v[206:209], v[76:79]
	v_mfma_f32_16x16x32_bf16 v[72:75], v[144:147], v[206:209], v[72:75]
	v_mfma_f32_16x16x32_bf16 v[124:127], v[140:143], v[186:189], v[124:127]
	v_mfma_f32_16x16x32_bf16 v[120:123], v[148:151], v[186:189], v[120:123]
	v_mfma_f32_16x16x32_bf16 v[108:111], v[140:143], v[194:197], v[108:111]
	v_mfma_f32_16x16x32_bf16 v[104:107], v[148:151], v[194:197], v[104:107]
	v_mfma_f32_16x16x32_bf16 v[92:95], v[140:143], v[202:205], v[92:95]
	v_mfma_f32_16x16x32_bf16 v[88:91], v[148:151], v[202:205], v[88:91]
	v_mfma_f32_16x16x32_bf16 v[76:79], v[140:143], v[220:223], v[76:79]
	v_mfma_f32_16x16x32_bf16 v[72:75], v[148:151], v[220:223], v[72:75]
	v_mfma_f32_16x16x32_bf16 v[116:119], v[152:155], v[182:185], v[116:119]
	v_mfma_f32_16x16x32_bf16 v[112:115], v[160:163], v[182:185], v[112:115]
	v_mfma_f32_16x16x32_bf16 v[100:103], v[152:155], v[190:193], v[100:103]
	v_mfma_f32_16x16x32_bf16 v[96:99], v[160:163], v[190:193], v[96:99]
	v_mfma_f32_16x16x32_bf16 v[84:87], v[152:155], v[198:201], v[84:87]
	v_mfma_f32_16x16x32_bf16 v[80:83], v[160:163], v[198:201], v[80:83]
	v_mfma_f32_16x16x32_bf16 v[68:71], v[152:155], v[206:209], v[68:71]
	v_mfma_f32_16x16x32_bf16 v[64:67], v[160:163], v[206:209], v[64:67]
	v_mfma_f32_16x16x32_bf16 v[116:119], v[156:159], v[186:189], v[116:119]
	v_mfma_f32_16x16x32_bf16 v[112:115], v[164:167], v[186:189], v[112:115]
	v_mfma_f32_16x16x32_bf16 v[100:103], v[156:159], v[194:197], v[100:103]
	v_mfma_f32_16x16x32_bf16 v[96:99], v[164:167], v[194:197], v[96:99]
	v_mfma_f32_16x16x32_bf16 v[84:87], v[156:159], v[202:205], v[84:87]
	v_mfma_f32_16x16x32_bf16 v[80:83], v[164:167], v[202:205], v[80:83]
	v_mfma_f32_16x16x32_bf16 v[68:71], v[156:159], v[220:223], v[68:71]
	v_mfma_f32_16x16x32_bf16 v[64:67], v[164:167], v[220:223], v[64:67]
	s_barrier
	s_add_i32 s82, s87, s63
	v_lshl_add_u64 v[134:135], s[84:85], 0, v[172:173]
	s_mov_b32 m0, s82
	s_nop 0
	global_load_lds_dwordx4 v[134:135], off
	v_lshl_add_u64 v[224:225], v[134:135], 0, s[40:41]
	s_add_i32 m0, s82, 0x2000
	s_add_i32 s81, s81, s63
	global_load_lds_dwordx4 v[224:225], off
	v_lshl_add_u64 v[224:225], v[134:135], 0, s[4:5]
	s_mov_b32 m0, s81
	s_nop 0
	global_load_lds_dwordx4 v[224:225], off
	v_lshl_add_u64 v[224:225], v[134:135], 0, s[6:7]
	s_add_i32 m0, s81, 0x2000
	s_nop 0
	global_load_lds_dwordx4 v[224:225], off
	v_lshl_add_u64 v[224:225], s[48:49], 0, v[128:129]
	s_mov_b32 m0, s74
	v_lshl_add_u64 v[226:227], v[224:225], 0, s[40:41]
	global_load_lds_dwordx4 v[224:225], off
	s_mov_b32 m0, s75
	s_nop 0
	global_load_lds_dwordx4 v[226:227], off
	ds_read_b128 v[182:185], v138 offset:16384
	ds_read_b128 v[186:189], v138 offset:17408
	ds_read_b128 v[190:193], v138 offset:18432
	ds_read_b128 v[194:197], v138 offset:19456
	ds_read_b128 v[198:201], v138 offset:20480
	ds_read_b128 v[202:205], v138 offset:21504
	ds_read_b128 v[206:209], v138 offset:22528
	ds_read_b128 v[220:223], v138 offset:23552
	s_waitcnt vmcnt(8)
	s_waitcnt lgkmcnt(0)
	s_barrier
	s_waitcnt lgkmcnt(0)
	v_mfma_f32_16x16x32_bf16 v[60:63], v[130:133], v[182:185], v[60:63]
	v_mfma_f32_16x16x32_bf16 v[56:59], v[144:147], v[182:185], v[56:59]
	v_mfma_f32_16x16x32_bf16 v[44:47], v[130:133], v[190:193], v[44:47]
	v_mfma_f32_16x16x32_bf16 v[40:43], v[144:147], v[190:193], v[40:43]
	v_mfma_f32_16x16x32_bf16 v[28:31], v[130:133], v[198:201], v[28:31]
	v_mfma_f32_16x16x32_bf16 v[24:27], v[144:147], v[198:201], v[24:27]
	v_mfma_f32_16x16x32_bf16 v[12:15], v[130:133], v[206:209], v[12:15]
	v_mfma_f32_16x16x32_bf16 v[8:11], v[144:147], v[206:209], v[8:11]
	v_mfma_f32_16x16x32_bf16 v[60:63], v[140:143], v[186:189], v[60:63]
	v_mfma_f32_16x16x32_bf16 v[56:59], v[148:151], v[186:189], v[56:59]
	v_mfma_f32_16x16x32_bf16 v[44:47], v[140:143], v[194:197], v[44:47]
	v_mfma_f32_16x16x32_bf16 v[40:43], v[148:151], v[194:197], v[40:43]
	v_mfma_f32_16x16x32_bf16 v[28:31], v[140:143], v[202:205], v[28:31]
	v_mfma_f32_16x16x32_bf16 v[24:27], v[148:151], v[202:205], v[24:27]
	v_mfma_f32_16x16x32_bf16 v[12:15], v[140:143], v[220:223], v[12:15]
	v_mfma_f32_16x16x32_bf16 v[8:11], v[148:151], v[220:223], v[8:11]
	v_mfma_f32_16x16x32_bf16 v[52:55], v[152:155], v[182:185], v[52:55]
	v_mfma_f32_16x16x32_bf16 v[48:51], v[160:163], v[182:185], v[48:51]
	v_mfma_f32_16x16x32_bf16 v[36:39], v[152:155], v[190:193], v[36:39]
	v_mfma_f32_16x16x32_bf16 v[32:35], v[160:163], v[190:193], v[32:35]
	v_mfma_f32_16x16x32_bf16 v[20:23], v[152:155], v[198:201], v[20:23]
	v_mfma_f32_16x16x32_bf16 v[16:19], v[160:163], v[198:201], v[16:19]
	v_mfma_f32_16x16x32_bf16 v[4:7], v[152:155], v[206:209], v[4:7]
	v_mfma_f32_16x16x32_bf16 v[0:3], v[160:163], v[206:209], v[0:3]
	v_mfma_f32_16x16x32_bf16 v[52:55], v[156:159], v[186:189], v[52:55]
	v_mfma_f32_16x16x32_bf16 v[48:51], v[164:167], v[186:189], v[48:51]
	v_mfma_f32_16x16x32_bf16 v[36:39], v[156:159], v[194:197], v[36:39]
	v_mfma_f32_16x16x32_bf16 v[32:35], v[164:167], v[194:197], v[32:35]
	v_mfma_f32_16x16x32_bf16 v[20:23], v[156:159], v[202:205], v[20:23]
	v_mfma_f32_16x16x32_bf16 v[16:19], v[164:167], v[202:205], v[16:19]
	v_mfma_f32_16x16x32_bf16 v[4:7], v[156:159], v[220:223], v[4:7]
	v_mfma_f32_16x16x32_bf16 v[0:3], v[164:167], v[220:223], v[0:3]
	s_barrier
	s_mov_b32 m0, s76
	v_lshl_add_u64 v[226:227], v[224:225], 0, s[4:5]
	global_load_lds_dwordx4 v[226:227], off
	v_lshl_add_u64 v[226:227], v[224:225], 0, s[6:7]
	s_mov_b32 m0, s77
	s_nop 0
	global_load_lds_dwordx4 v[226:227], off
	s_add_i32 s48, 0, 0x18000
	v_add_u32_e32 v139, s48, v137
	s_add_i32 s49, 0, 0x1c000
	ds_read_b128 v[130:133], v139
	ds_read_b128 v[140:143], v139 offset:1024
	ds_read_b128 v[144:147], v139 offset:2048
	ds_read_b128 v[148:151], v139 offset:3072
	v_add_u32_e32 v139, s49, v137
	ds_read_b128 v[152:155], v139
	ds_read_b128 v[156:159], v139 offset:1024
	ds_read_b128 v[160:163], v139 offset:2048
	ds_read_b128 v[164:167], v139 offset:3072
	ds_read_b128 v[182:185], v138 offset:32768
	ds_read_b128 v[186:189], v138 offset:33792
	ds_read_b128 v[190:193], v138 offset:34816
	ds_read_b128 v[194:197], v138 offset:35840
	ds_read_b128 v[198:201], v138 offset:36864
	ds_read_b128 v[202:205], v138 offset:37888
	ds_read_b128 v[206:209], v138 offset:38912
	ds_read_b128 v[220:223], v138 offset:39936
	s_nop 0
	s_waitcnt vmcnt(8)
	s_waitcnt lgkmcnt(0)
	s_barrier
	s_waitcnt lgkmcnt(0)
	v_mfma_f32_16x16x32_bf16 v[124:127], v[130:133], v[182:185], v[124:127]
	v_mfma_f32_16x16x32_bf16 v[120:123], v[144:147], v[182:185], v[120:123]
	v_mfma_f32_16x16x32_bf16 v[108:111], v[130:133], v[190:193], v[108:111]
	v_mfma_f32_16x16x32_bf16 v[104:107], v[144:147], v[190:193], v[104:107]
	v_mfma_f32_16x16x32_bf16 v[92:95], v[130:133], v[198:201], v[92:95]
	v_mfma_f32_16x16x32_bf16 v[88:91], v[144:147], v[198:201], v[88:91]
	v_mfma_f32_16x16x32_bf16 v[76:79], v[130:133], v[206:209], v[76:79]
	v_mfma_f32_16x16x32_bf16 v[72:75], v[144:147], v[206:209], v[72:75]
	v_mfma_f32_16x16x32_bf16 v[124:127], v[140:143], v[186:189], v[124:127]
	v_mfma_f32_16x16x32_bf16 v[120:123], v[148:151], v[186:189], v[120:123]
	v_mfma_f32_16x16x32_bf16 v[108:111], v[140:143], v[194:197], v[108:111]
	v_mfma_f32_16x16x32_bf16 v[104:107], v[148:151], v[194:197], v[104:107]
	v_mfma_f32_16x16x32_bf16 v[92:95], v[140:143], v[202:205], v[92:95]
	v_mfma_f32_16x16x32_bf16 v[88:91], v[148:151], v[202:205], v[88:91]
	v_mfma_f32_16x16x32_bf16 v[76:79], v[140:143], v[220:223], v[76:79]
	v_mfma_f32_16x16x32_bf16 v[72:75], v[148:151], v[220:223], v[72:75]
	v_mfma_f32_16x16x32_bf16 v[116:119], v[152:155], v[182:185], v[116:119]
	v_mfma_f32_16x16x32_bf16 v[112:115], v[160:163], v[182:185], v[112:115]
	v_mfma_f32_16x16x32_bf16 v[100:103], v[152:155], v[190:193], v[100:103]
	v_mfma_f32_16x16x32_bf16 v[96:99], v[160:163], v[190:193], v[96:99]
	v_mfma_f32_16x16x32_bf16 v[84:87], v[152:155], v[198:201], v[84:87]
	v_mfma_f32_16x16x32_bf16 v[80:83], v[160:163], v[198:201], v[80:83]
	v_mfma_f32_16x16x32_bf16 v[68:71], v[152:155], v[206:209], v[68:71]
	v_mfma_f32_16x16x32_bf16 v[64:67], v[160:163], v[206:209], v[64:67]
	v_mfma_f32_16x16x32_bf16 v[116:119], v[156:159], v[186:189], v[116:119]
	v_mfma_f32_16x16x32_bf16 v[112:115], v[164:167], v[186:189], v[112:115]
	v_mfma_f32_16x16x32_bf16 v[100:103], v[156:159], v[194:197], v[100:103]
	v_mfma_f32_16x16x32_bf16 v[96:99], v[164:167], v[194:197], v[96:99]
	v_mfma_f32_16x16x32_bf16 v[84:87], v[156:159], v[202:205], v[84:87]
	v_mfma_f32_16x16x32_bf16 v[80:83], v[164:167], v[202:205], v[80:83]
	v_mfma_f32_16x16x32_bf16 v[68:71], v[156:159], v[220:223], v[68:71]
	v_mfma_f32_16x16x32_bf16 v[64:67], v[164:167], v[220:223], v[64:67]
	s_barrier
	s_add_i32 s48, s48, s63
	v_lshl_add_u64 v[226:227], v[134:135], 0, s[10:11]
	s_mov_b32 m0, s48
	s_nop 0
	global_load_lds_dwordx4 v[226:227], off
	v_lshl_add_u64 v[226:227], v[134:135], 0, s[12:13]
	s_add_i32 m0, s48, 0x2000
	s_add_i32 s48, s49, s63
	global_load_lds_dwordx4 v[226:227], off
	v_lshl_add_u64 v[226:227], v[134:135], 0, s[14:15]
	s_mov_b32 m0, s48
	v_lshl_add_u64 v[134:135], v[134:135], 0, s[16:17]
	global_load_lds_dwordx4 v[226:227], off
	s_add_i32 m0, s48, 0x2000
	s_nop 0
	global_load_lds_dwordx4 v[134:135], off
	v_lshl_add_u64 v[134:135], v[224:225], 0, s[10:11]
	s_mov_b32 m0, s68
	s_nop 0
	global_load_lds_dwordx4 v[134:135], off
	v_lshl_add_u64 v[134:135], v[224:225], 0, s[12:13]
	s_mov_b32 m0, s69
	s_nop 0
	global_load_lds_dwordx4 v[134:135], off
	ds_read_b128 v[182:185], v138 offset:49152
	ds_read_b128 v[186:189], v138 offset:50176
	ds_read_b128 v[190:193], v138 offset:51200
	ds_read_b128 v[194:197], v138 offset:52224
	ds_read_b128 v[198:201], v138 offset:53248
	ds_read_b128 v[202:205], v138 offset:54272
	ds_read_b128 v[206:209], v138 offset:55296
	ds_read_b128 v[220:223], v138 offset:56320
	s_waitcnt vmcnt(8)
	s_waitcnt lgkmcnt(0)
	s_barrier
	s_waitcnt lgkmcnt(0)
	v_mfma_f32_16x16x32_bf16 v[60:63], v[130:133], v[182:185], v[60:63]
	v_mfma_f32_16x16x32_bf16 v[56:59], v[144:147], v[182:185], v[56:59]
	v_mfma_f32_16x16x32_bf16 v[44:47], v[130:133], v[190:193], v[44:47]
	v_mfma_f32_16x16x32_bf16 v[40:43], v[144:147], v[190:193], v[40:43]
	v_mfma_f32_16x16x32_bf16 v[28:31], v[130:133], v[198:201], v[28:31]
	v_mfma_f32_16x16x32_bf16 v[24:27], v[144:147], v[198:201], v[24:27]
	v_mfma_f32_16x16x32_bf16 v[12:15], v[130:133], v[206:209], v[12:15]
	v_mfma_f32_16x16x32_bf16 v[8:11], v[144:147], v[206:209], v[8:11]
	v_mfma_f32_16x16x32_bf16 v[60:63], v[140:143], v[186:189], v[60:63]
	v_mfma_f32_16x16x32_bf16 v[56:59], v[148:151], v[186:189], v[56:59]
	v_mfma_f32_16x16x32_bf16 v[44:47], v[140:143], v[194:197], v[44:47]
	v_mfma_f32_16x16x32_bf16 v[40:43], v[148:151], v[194:197], v[40:43]
	v_mfma_f32_16x16x32_bf16 v[28:31], v[140:143], v[202:205], v[28:31]
	v_mfma_f32_16x16x32_bf16 v[24:27], v[148:151], v[202:205], v[24:27]
	v_mfma_f32_16x16x32_bf16 v[12:15], v[140:143], v[220:223], v[12:15]
	v_mfma_f32_16x16x32_bf16 v[8:11], v[148:151], v[220:223], v[8:11]
	v_mfma_f32_16x16x32_bf16 v[52:55], v[152:155], v[182:185], v[52:55]
	v_mfma_f32_16x16x32_bf16 v[48:51], v[160:163], v[182:185], v[48:51]
	v_mfma_f32_16x16x32_bf16 v[36:39], v[152:155], v[190:193], v[36:39]
	v_mfma_f32_16x16x32_bf16 v[32:35], v[160:163], v[190:193], v[32:35]
	v_mfma_f32_16x16x32_bf16 v[20:23], v[152:155], v[198:201], v[20:23]
	v_mfma_f32_16x16x32_bf16 v[16:19], v[160:163], v[198:201], v[16:19]
	v_mfma_f32_16x16x32_bf16 v[4:7], v[152:155], v[206:209], v[4:7]
	v_mfma_f32_16x16x32_bf16 v[0:3], v[160:163], v[206:209], v[0:3]
	v_mfma_f32_16x16x32_bf16 v[52:55], v[156:159], v[186:189], v[52:55]
	v_mfma_f32_16x16x32_bf16 v[48:51], v[164:167], v[186:189], v[48:51]
	v_mfma_f32_16x16x32_bf16 v[36:39], v[156:159], v[194:197], v[36:39]
	v_mfma_f32_16x16x32_bf16 v[32:35], v[164:167], v[194:197], v[32:35]
	v_mfma_f32_16x16x32_bf16 v[20:23], v[156:159], v[202:205], v[20:23]
	v_mfma_f32_16x16x32_bf16 v[16:19], v[164:167], v[202:205], v[16:19]
	v_mfma_f32_16x16x32_bf16 v[4:7], v[156:159], v[220:223], v[4:7]
	v_mfma_f32_16x16x32_bf16 v[0:3], v[164:167], v[220:223], v[0:3]
	s_barrier
	s_cmp_gt_u32 s80, 13
	s_cbranch_scc0 .LBB0_784
	s_and_b64 vcc, exec, s[30:31]
	s_cbranch_vccz .LBB0_787
	s_barrier

.LBB0_856:
	s_add_i32 s78, s78, 2
	s_mov_b32 s50, s78
	s_ashr_i32 s51, s50, 31
	s_lshl_b64 s[80:81], s[50:51], 7
	v_lshl_add_u64 v[224:225], v[130:131], 0, s[80:81]
	v_lshl_add_u64 v[226:227], v[224:225], 0, s[10:11]
	s_add_i32 m0, s62, 0xc000
	s_nop 0
	global_load_lds_dwordx4 v[226:227], off
	v_lshl_add_u64 v[224:225], v[224:225], 0, s[12:13]
	s_add_i32 m0, s62, 0xe000
	s_nop 0
	global_load_lds_dwordx4 v[224:225], off
	s_add_u32 s51, s80, 0x100
	s_addc_u32 s79, s81, 0
	s_add_u32 s82, s30, s51
	s_addc_u32 s83, s31, s79
	s_add_u32 s84, s28, s51
	s_addc_u32 s79, s29, s79
	s_add_i32 s85, 0, 0x10000
	s_cmp_eq_u32 s50, 14
	s_cselect_b32 s51, s39, s83
	s_cselect_b32 s50, s76, s82
	v_add_u32_e32 v135, s85, v133
	s_cselect_b32 s83, s35, s79
	s_cselect_b32 s82, s77, s84
	s_add_i32 s79, 0, 0x14000
	ds_read_b128 v[136:139], v135
	ds_read_b128 v[140:143], v135 offset:1024
	ds_read_b128 v[144:147], v135 offset:2048
	ds_read_b128 v[148:151], v135 offset:3072
	v_add_u32_e32 v135, s79, v133
	ds_read_b128 v[152:155], v135
	ds_read_b128 v[156:159], v135 offset:1024
	ds_read_b128 v[160:163], v135 offset:2048
	ds_read_b128 v[164:167], v135 offset:3072
	ds_read_b128 v[182:185], v134
	ds_read_b128 v[186:189], v134 offset:1024
	ds_read_b128 v[190:193], v134 offset:2048
	ds_read_b128 v[194:197], v134 offset:3072
	ds_read_b128 v[198:201], v134 offset:4096
	ds_read_b128 v[202:205], v134 offset:5120
	ds_read_b128 v[206:209], v134 offset:6144
	ds_read_b128 v[220:223], v134 offset:7168
	s_nop 0
	s_waitcnt vmcnt(8)
	s_waitcnt lgkmcnt(0)
	s_barrier
	s_waitcnt lgkmcnt(0)
	v_mfma_f32_16x16x32_bf16 v[124:127], v[136:139], v[182:185], v[124:127]
	v_mfma_f32_16x16x32_bf16 v[120:123], v[144:147], v[182:185], v[120:123]
	v_mfma_f32_16x16x32_bf16 v[116:119], v[136:139], v[190:193], v[116:119]
	v_mfma_f32_16x16x32_bf16 v[112:115], v[144:147], v[190:193], v[112:115]
	v_mfma_f32_16x16x32_bf16 v[100:103], v[136:139], v[198:201], v[100:103]
	v_mfma_f32_16x16x32_bf16 v[96:99], v[144:147], v[198:201], v[96:99]
	v_mfma_f32_16x16x32_bf16 v[84:87], v[136:139], v[206:209], v[84:87]
	v_mfma_f32_16x16x32_bf16 v[80:83], v[144:147], v[206:209], v[80:83]
	v_mfma_f32_16x16x32_bf16 v[124:127], v[140:143], v[186:189], v[124:127]
	v_mfma_f32_16x16x32_bf16 v[120:123], v[148:151], v[186:189], v[120:123]
	v_mfma_f32_16x16x32_bf16 v[116:119], v[140:143], v[194:197], v[116:119]
	v_mfma_f32_16x16x32_bf16 v[112:115], v[148:151], v[194:197], v[112:115]
	v_mfma_f32_16x16x32_bf16 v[100:103], v[140:143], v[202:205], v[100:103]
	v_mfma_f32_16x16x32_bf16 v[96:99], v[148:151], v[202:205], v[96:99]
	v_mfma_f32_16x16x32_bf16 v[84:87], v[140:143], v[220:223], v[84:87]
	v_mfma_f32_16x16x32_bf16 v[80:83], v[148:151], v[220:223], v[80:83]
	v_mfma_f32_16x16x32_bf16 v[108:111], v[152:155], v[182:185], v[108:111]
	v_mfma_f32_16x16x32_bf16 v[104:107], v[160:163], v[182:185], v[104:107]
	v_mfma_f32_16x16x32_bf16 v[92:95], v[152:155], v[190:193], v[92:95]
	v_mfma_f32_16x16x32_bf16 v[88:91], v[160:163], v[190:193], v[88:91]
	v_mfma_f32_16x16x32_bf16 v[76:79], v[152:155], v[198:201], v[76:79]
	v_mfma_f32_16x16x32_bf16 v[72:75], v[160:163], v[198:201], v[72:75]
	v_mfma_f32_16x16x32_bf16 v[68:71], v[152:155], v[206:209], v[68:71]
	v_mfma_f32_16x16x32_bf16 v[64:67], v[160:163], v[206:209], v[64:67]
	v_mfma_f32_16x16x32_bf16 v[108:111], v[156:159], v[186:189], v[108:111]
	v_mfma_f32_16x16x32_bf16 v[104:107], v[164:167], v[186:189], v[104:107]
	v_mfma_f32_16x16x32_bf16 v[92:95], v[156:159], v[194:197], v[92:95]
	v_mfma_f32_16x16x32_bf16 v[88:91], v[164:167], v[194:197], v[88:91]
	v_mfma_f32_16x16x32_bf16 v[76:79], v[156:159], v[202:205], v[76:79]
	v_mfma_f32_16x16x32_bf16 v[72:75], v[164:167], v[202:205], v[72:75]
	v_mfma_f32_16x16x32_bf16 v[68:71], v[156:159], v[220:223], v[68:71]
	v_mfma_f32_16x16x32_bf16 v[64:67], v[164:167], v[220:223], v[64:67]
	s_barrier
	s_add_i32 s80, s85, s59
	v_lshl_add_u64 v[224:225], s[82:83], 0, v[172:173]
	s_mov_b32 m0, s80
	s_nop 0
	global_load_lds_dwordx4 v[224:225], off
	v_lshl_add_u64 v[226:227], v[224:225], 0, s[40:41]
	s_add_i32 m0, s80, 0x2000
	s_add_i32 s79, s79, s59
	global_load_lds_dwordx4 v[226:227], off
	v_lshl_add_u64 v[226:227], v[224:225], 0, s[4:5]
	s_mov_b32 m0, s79
	s_nop 0
	global_load_lds_dwordx4 v[226:227], off
	v_lshl_add_u64 v[226:227], v[224:225], 0, s[6:7]
	s_add_i32 m0, s79, 0x2000
	s_nop 0
	global_load_lds_dwordx4 v[226:227], off
	v_lshl_add_u64 v[226:227], s[50:51], 0, v[128:129]
	s_mov_b32 m0, s62
	v_lshl_add_u64 v[228:229], v[226:227], 0, s[40:41]
	global_load_lds_dwordx4 v[226:227], off
	s_mov_b32 m0, s63
	s_nop 0
	global_load_lds_dwordx4 v[228:229], off
	ds_read_b128 v[182:185], v134 offset:16384
	ds_read_b128 v[186:189], v134 offset:17408
	ds_read_b128 v[190:193], v134 offset:18432
	ds_read_b128 v[194:197], v134 offset:19456
	ds_read_b128 v[198:201], v134 offset:20480
	ds_read_b128 v[202:205], v134 offset:21504
	ds_read_b128 v[206:209], v134 offset:22528
	ds_read_b128 v[220:223], v134 offset:23552
	s_waitcnt vmcnt(8)
	s_waitcnt lgkmcnt(0)
	s_barrier
	s_waitcnt lgkmcnt(0)
	v_mfma_f32_16x16x32_bf16 v[60:63], v[136:139], v[182:185], v[60:63]
	v_mfma_f32_16x16x32_bf16 v[56:59], v[144:147], v[182:185], v[56:59]
	v_mfma_f32_16x16x32_bf16 v[52:55], v[136:139], v[190:193], v[52:55]
	v_mfma_f32_16x16x32_bf16 v[48:51], v[144:147], v[190:193], v[48:51]
	v_mfma_f32_16x16x32_bf16 v[36:39], v[136:139], v[198:201], v[36:39]
	v_mfma_f32_16x16x32_bf16 v[32:35], v[144:147], v[198:201], v[32:35]
	v_mfma_f32_16x16x32_bf16 v[20:23], v[136:139], v[206:209], v[20:23]
	v_mfma_f32_16x16x32_bf16 v[16:19], v[144:147], v[206:209], v[16:19]
	v_mfma_f32_16x16x32_bf16 v[60:63], v[140:143], v[186:189], v[60:63]
	v_mfma_f32_16x16x32_bf16 v[56:59], v[148:151], v[186:189], v[56:59]
	v_mfma_f32_16x16x32_bf16 v[52:55], v[140:143], v[194:197], v[52:55]
	v_mfma_f32_16x16x32_bf16 v[48:51], v[148:151], v[194:197], v[48:51]
	v_mfma_f32_16x16x32_bf16 v[36:39], v[140:143], v[202:205], v[36:39]
	v_mfma_f32_16x16x32_bf16 v[32:35], v[148:151], v[202:205], v[32:35]
	v_mfma_f32_16x16x32_bf16 v[20:23], v[140:143], v[220:223], v[20:23]
	v_mfma_f32_16x16x32_bf16 v[16:19], v[148:151], v[220:223], v[16:19]
	v_mfma_f32_16x16x32_bf16 v[44:47], v[152:155], v[182:185], v[44:47]
	v_mfma_f32_16x16x32_bf16 v[40:43], v[160:163], v[182:185], v[40:43]
	v_mfma_f32_16x16x32_bf16 v[28:31], v[152:155], v[190:193], v[28:31]
	v_mfma_f32_16x16x32_bf16 v[24:27], v[160:163], v[190:193], v[24:27]
	v_mfma_f32_16x16x32_bf16 v[12:15], v[152:155], v[198:201], v[12:15]
	v_mfma_f32_16x16x32_bf16 v[8:11], v[160:163], v[198:201], v[8:11]
	v_mfma_f32_16x16x32_bf16 v[4:7], v[152:155], v[206:209], v[4:7]
	v_mfma_f32_16x16x32_bf16 v[0:3], v[160:163], v[206:209], v[0:3]
	v_mfma_f32_16x16x32_bf16 v[44:47], v[156:159], v[186:189], v[44:47]
	v_mfma_f32_16x16x32_bf16 v[40:43], v[164:167], v[186:189], v[40:43]
	v_mfma_f32_16x16x32_bf16 v[28:31], v[156:159], v[194:197], v[28:31]
	v_mfma_f32_16x16x32_bf16 v[24:27], v[164:167], v[194:197], v[24:27]
	v_mfma_f32_16x16x32_bf16 v[12:15], v[156:159], v[202:205], v[12:15]
	v_mfma_f32_16x16x32_bf16 v[8:11], v[164:167], v[202:205], v[8:11]
	v_mfma_f32_16x16x32_bf16 v[4:7], v[156:159], v[220:223], v[4:7]
	v_mfma_f32_16x16x32_bf16 v[0:3], v[164:167], v[220:223], v[0:3]
	s_barrier
	s_mov_b32 m0, s68
	v_lshl_add_u64 v[228:229], v[226:227], 0, s[4:5]
	global_load_lds_dwordx4 v[228:229], off
	v_lshl_add_u64 v[228:229], v[226:227], 0, s[6:7]
	s_mov_b32 m0, s69
	s_nop 0
	global_load_lds_dwordx4 v[228:229], off
	s_add_i32 s50, 0, 0x18000
	v_add_u32_e32 v135, s50, v133
	s_add_i32 s51, 0, 0x1c000
	ds_read_b128 v[136:139], v135
	ds_read_b128 v[140:143], v135 offset:1024
	ds_read_b128 v[144:147], v135 offset:2048
	ds_read_b128 v[148:151], v135 offset:3072
	v_add_u32_e32 v135, s51, v133
	ds_read_b128 v[152:155], v135
	ds_read_b128 v[156:159], v135 offset:1024
	ds_read_b128 v[160:163], v135 offset:2048
	ds_read_b128 v[164:167], v135 offset:3072
	ds_read_b128 v[182:185], v134 offset:32768
	ds_read_b128 v[186:189], v134 offset:33792
	ds_read_b128 v[190:193], v134 offset:34816
	ds_read_b128 v[194:197], v134 offset:35840
	ds_read_b128 v[198:201], v134 offset:36864
	ds_read_b128 v[202:205], v134 offset:37888
	ds_read_b128 v[206:209], v134 offset:38912
	ds_read_b128 v[220:223], v134 offset:39936
	s_nop 0
	s_waitcnt vmcnt(8)
	s_waitcnt lgkmcnt(0)
	s_barrier
	s_waitcnt lgkmcnt(0)
	v_mfma_f32_16x16x32_bf16 v[124:127], v[136:139], v[182:185], v[124:127]
	v_mfma_f32_16x16x32_bf16 v[120:123], v[144:147], v[182:185], v[120:123]
	v_mfma_f32_16x16x32_bf16 v[116:119], v[136:139], v[190:193], v[116:119]
	v_mfma_f32_16x16x32_bf16 v[112:115], v[144:147], v[190:193], v[112:115]
	v_mfma_f32_16x16x32_bf16 v[100:103], v[136:139], v[198:201], v[100:103]
	v_mfma_f32_16x16x32_bf16 v[96:99], v[144:147], v[198:201], v[96:99]
	v_mfma_f32_16x16x32_bf16 v[84:87], v[136:139], v[206:209], v[84:87]
	v_mfma_f32_16x16x32_bf16 v[80:83], v[144:147], v[206:209], v[80:83]
	v_mfma_f32_16x16x32_bf16 v[124:127], v[140:143], v[186:189], v[124:127]
	v_mfma_f32_16x16x32_bf16 v[120:123], v[148:151], v[186:189], v[120:123]
	v_mfma_f32_16x16x32_bf16 v[116:119], v[140:143], v[194:197], v[116:119]
	v_mfma_f32_16x16x32_bf16 v[112:115], v[148:151], v[194:197], v[112:115]
	v_mfma_f32_16x16x32_bf16 v[100:103], v[140:143], v[202:205], v[100:103]
	v_mfma_f32_16x16x32_bf16 v[96:99], v[148:151], v[202:205], v[96:99]
	v_mfma_f32_16x16x32_bf16 v[84:87], v[140:143], v[220:223], v[84:87]
	v_mfma_f32_16x16x32_bf16 v[80:83], v[148:151], v[220:223], v[80:83]
	v_mfma_f32_16x16x32_bf16 v[108:111], v[152:155], v[182:185], v[108:111]
	v_mfma_f32_16x16x32_bf16 v[104:107], v[160:163], v[182:185], v[104:107]
	v_mfma_f32_16x16x32_bf16 v[92:95], v[152:155], v[190:193], v[92:95]
	v_mfma_f32_16x16x32_bf16 v[88:91], v[160:163], v[190:193], v[88:91]
	v_mfma_f32_16x16x32_bf16 v[76:79], v[152:155], v[198:201], v[76:79]
	v_mfma_f32_16x16x32_bf16 v[72:75], v[160:163], v[198:201], v[72:75]
	v_mfma_f32_16x16x32_bf16 v[68:71], v[152:155], v[206:209], v[68:71]
	v_mfma_f32_16x16x32_bf16 v[64:67], v[160:163], v[206:209], v[64:67]
	v_mfma_f32_16x16x32_bf16 v[108:111], v[156:159], v[186:189], v[108:111]
	v_mfma_f32_16x16x32_bf16 v[104:107], v[164:167], v[186:189], v[104:107]
	v_mfma_f32_16x16x32_bf16 v[92:95], v[156:159], v[194:197], v[92:95]
	v_mfma_f32_16x16x32_bf16 v[88:91], v[164:167], v[194:197], v[88:91]
	v_mfma_f32_16x16x32_bf16 v[76:79], v[156:159], v[202:205], v[76:79]
	v_mfma_f32_16x16x32_bf16 v[72:75], v[164:167], v[202:205], v[72:75]
	v_mfma_f32_16x16x32_bf16 v[68:71], v[156:159], v[220:223], v[68:71]
	v_mfma_f32_16x16x32_bf16 v[64:67], v[164:167], v[220:223], v[64:67]
	s_barrier
	s_add_i32 s50, s50, s59
	v_lshl_add_u64 v[228:229], v[224:225], 0, s[10:11]
	s_mov_b32 m0, s50
	s_nop 0
	global_load_lds_dwordx4 v[228:229], off
	v_lshl_add_u64 v[228:229], v[224:225], 0, s[12:13]
	s_add_i32 m0, s50, 0x2000
	s_add_i32 s50, s51, s59
	global_load_lds_dwordx4 v[228:229], off
	v_lshl_add_u64 v[228:229], v[224:225], 0, s[14:15]
	s_mov_b32 m0, s50
	v_lshl_add_u64 v[224:225], v[224:225], 0, s[16:17]
	global_load_lds_dwordx4 v[228:229], off
	s_add_i32 m0, s50, 0x2000
	s_nop 0
	global_load_lds_dwordx4 v[224:225], off
	v_lshl_add_u64 v[224:225], v[226:227], 0, s[10:11]
	s_mov_b32 m0, s72
	s_nop 0
	global_load_lds_dwordx4 v[224:225], off
	v_lshl_add_u64 v[224:225], v[226:227], 0, s[12:13]
	s_mov_b32 m0, s73
	s_nop 0
	global_load_lds_dwordx4 v[224:225], off
	ds_read_b128 v[182:185], v134 offset:49152
	ds_read_b128 v[186:189], v134 offset:50176
	ds_read_b128 v[190:193], v134 offset:51200
	ds_read_b128 v[194:197], v134 offset:52224
	ds_read_b128 v[198:201], v134 offset:53248
	ds_read_b128 v[202:205], v134 offset:54272
	ds_read_b128 v[206:209], v134 offset:55296
	ds_read_b128 v[220:223], v134 offset:56320
	s_waitcnt vmcnt(8)
	s_waitcnt lgkmcnt(0)
	s_barrier
	s_waitcnt lgkmcnt(0)
	v_mfma_f32_16x16x32_bf16 v[60:63], v[136:139], v[182:185], v[60:63]
	v_mfma_f32_16x16x32_bf16 v[56:59], v[144:147], v[182:185], v[56:59]
	v_mfma_f32_16x16x32_bf16 v[52:55], v[136:139], v[190:193], v[52:55]
	v_mfma_f32_16x16x32_bf16 v[48:51], v[144:147], v[190:193], v[48:51]
	v_mfma_f32_16x16x32_bf16 v[36:39], v[136:139], v[198:201], v[36:39]
	v_mfma_f32_16x16x32_bf16 v[32:35], v[144:147], v[198:201], v[32:35]
	v_mfma_f32_16x16x32_bf16 v[20:23], v[136:139], v[206:209], v[20:23]
	v_mfma_f32_16x16x32_bf16 v[16:19], v[144:147], v[206:209], v[16:19]
	v_mfma_f32_16x16x32_bf16 v[60:63], v[140:143], v[186:189], v[60:63]
	v_mfma_f32_16x16x32_bf16 v[56:59], v[148:151], v[186:189], v[56:59]
	v_mfma_f32_16x16x32_bf16 v[52:55], v[140:143], v[194:197], v[52:55]
	v_mfma_f32_16x16x32_bf16 v[48:51], v[148:151], v[194:197], v[48:51]
	v_mfma_f32_16x16x32_bf16 v[36:39], v[140:143], v[202:205], v[36:39]
	v_mfma_f32_16x16x32_bf16 v[32:35], v[148:151], v[202:205], v[32:35]
	v_mfma_f32_16x16x32_bf16 v[20:23], v[140:143], v[220:223], v[20:23]
	v_mfma_f32_16x16x32_bf16 v[16:19], v[148:151], v[220:223], v[16:19]
	v_mfma_f32_16x16x32_bf16 v[44:47], v[152:155], v[182:185], v[44:47]
	v_mfma_f32_16x16x32_bf16 v[40:43], v[160:163], v[182:185], v[40:43]
	v_mfma_f32_16x16x32_bf16 v[28:31], v[152:155], v[190:193], v[28:31]
	v_mfma_f32_16x16x32_bf16 v[24:27], v[160:163], v[190:193], v[24:27]
	v_mfma_f32_16x16x32_bf16 v[12:15], v[152:155], v[198:201], v[12:15]
	v_mfma_f32_16x16x32_bf16 v[8:11], v[160:163], v[198:201], v[8:11]
	v_mfma_f32_16x16x32_bf16 v[4:7], v[152:155], v[206:209], v[4:7]
	v_mfma_f32_16x16x32_bf16 v[0:3], v[160:163], v[206:209], v[0:3]
	v_mfma_f32_16x16x32_bf16 v[44:47], v[156:159], v[186:189], v[44:47]
	v_mfma_f32_16x16x32_bf16 v[40:43], v[164:167], v[186:189], v[40:43]
	v_mfma_f32_16x16x32_bf16 v[28:31], v[156:159], v[194:197], v[28:31]
	v_mfma_f32_16x16x32_bf16 v[24:27], v[164:167], v[194:197], v[24:27]
	v_mfma_f32_16x16x32_bf16 v[12:15], v[156:159], v[202:205], v[12:15]
	v_mfma_f32_16x16x32_bf16 v[8:11], v[164:167], v[202:205], v[8:11]
	v_mfma_f32_16x16x32_bf16 v[4:7], v[156:159], v[220:223], v[4:7]
	v_mfma_f32_16x16x32_bf16 v[0:3], v[164:167], v[220:223], v[0:3]
	s_barrier
	s_cmp_gt_u32 s78, 13
	s_cbranch_scc0 .LBB0_856
	s_and_b64 vcc, exec, s[8:9]
	s_cbranch_vccz .LBB0_859
	s_barrier

.LBB0_969:
	s_ashr_i32 s23, s22, 31
	s_lshl_b64 s[24:25], s[22:23], 19
	s_add_u32 s24, s41, s24
	s_addc_u32 s25, s42, s25
	s_ashr_i32 s21, s20, 31
	s_lshl_b64 s[26:27], s[20:21], 19
	s_add_u32 s26, s43, s26
	s_mov_b32 s38, 0
	s_addc_u32 s27, s44, s27
	s_ashr_i32 s39, s38, 31
	s_lshl_b64 s[68:69], s[38:39], 7
	s_add_u32 s70, s68, 0x100
	s_addc_u32 s71, s69, 0
	s_add_u32 s38, s34, s70
	ds_read_b128 v[0:3], v140
	ds_read_b128 v[4:7], v140 offset:1024
	ds_read_b128 v[8:11], v140 offset:2048
	ds_read_b128 v[12:15], v140 offset:3072
	ds_read_b128 v[16:19], v141
	ds_read_b128 v[20:23], v141 offset:1024
	ds_read_b128 v[24:27], v141 offset:2048
	ds_read_b128 v[28:31], v141 offset:3072
	s_addc_u32 s39, s35, s71
	s_and_b64 s[66:67], s[36:37], exec
	s_cselect_b32 s23, s27, s31
	s_cselect_b32 s66, s26, s30
	s_add_u32 s70, s30, s70
	s_addc_u32 s71, s31, s71
	s_add_u32 s68, s34, s68
	s_mov_b32 s21, 0
	s_addc_u32 s69, s35, s69
	v_lshl_add_u64 v[64:65], s[68:69], 0, v[130:131]
	s_mov_b32 m0, s59
	v_lshl_add_u64 v[66:67], v[64:65], 0, s[14:15]
	ds_read_b128 v[32:35], v142
	ds_read_b128 v[36:39], v142 offset:1024
	ds_read_b128 v[40:43], v142 offset:2048
	ds_read_b128 v[44:47], v142 offset:3072
	ds_read_b128 v[48:51], v142 offset:4096
	ds_read_b128 v[52:55], v142 offset:5120
	ds_read_b128 v[56:59], v142 offset:6144
	ds_read_b128 v[60:63], v142 offset:7168
	global_load_lds_dwordx4 v[66:67], off
	v_lshl_add_u64 v[64:65], v[64:65], 0, s[16:17]
	s_mov_b32 m0, s60
	s_and_b64 s[68:69], s[36:37], exec
	global_load_lds_dwordx4 v[64:65], off
	s_waitcnt vmcnt(16)
	s_waitcnt lgkmcnt(0)
	s_cselect_b32 s67, s25, s35
	s_cselect_b32 s68, s24, s34
	s_barrier
	s_waitcnt lgkmcnt(0)
	v_mfma_f32_16x16x32_bf16 v[64:67], v[0:3], v[32:35], 0
	v_mfma_f32_16x16x32_bf16 v[68:71], v[8:11], v[32:35], 0
	v_mfma_f32_16x16x32_bf16 v[72:75], v[0:3], v[40:43], 0
	v_mfma_f32_16x16x32_bf16 v[76:79], v[8:11], v[40:43], 0
	v_mfma_f32_16x16x32_bf16 v[80:83], v[0:3], v[48:51], 0
	v_mfma_f32_16x16x32_bf16 v[84:87], v[8:11], v[48:51], 0
	v_mfma_f32_16x16x32_bf16 v[88:91], v[0:3], v[56:59], 0
	v_mfma_f32_16x16x32_bf16 v[92:95], v[8:11], v[56:59], 0
	v_mfma_f32_16x16x32_bf16 v[64:67], v[4:7], v[36:39], v[64:67]
	v_mfma_f32_16x16x32_bf16 v[68:71], v[12:15], v[36:39], v[68:71]
	v_mfma_f32_16x16x32_bf16 v[72:75], v[4:7], v[44:47], v[72:75]
	v_mfma_f32_16x16x32_bf16 v[76:79], v[12:15], v[44:47], v[76:79]
	v_mfma_f32_16x16x32_bf16 v[80:83], v[4:7], v[52:55], v[80:83]
	v_mfma_f32_16x16x32_bf16 v[84:87], v[12:15], v[52:55], v[84:87]
	v_mfma_f32_16x16x32_bf16 v[88:91], v[4:7], v[60:63], v[88:91]
	v_mfma_f32_16x16x32_bf16 v[100:103], v[12:15], v[60:63], v[92:95]
	v_mfma_f32_16x16x32_bf16 v[92:95], v[16:19], v[32:35], 0
	v_mfma_f32_16x16x32_bf16 v[32:35], v[24:27], v[32:35], 0
	v_mfma_f32_16x16x32_bf16 v[104:107], v[20:23], v[36:39], v[92:95]
	v_mfma_f32_16x16x32_bf16 v[32:35], v[28:31], v[36:39], v[32:35]
	v_mfma_f32_16x16x32_bf16 v[36:39], v[16:19], v[40:43], 0
	v_mfma_f32_16x16x32_bf16 v[40:43], v[24:27], v[40:43], 0
	v_mfma_f32_16x16x32_bf16 v[36:39], v[20:23], v[44:47], v[36:39]
	v_mfma_f32_16x16x32_bf16 v[40:43], v[28:31], v[44:47], v[40:43]
	v_mfma_f32_16x16x32_bf16 v[44:47], v[16:19], v[48:51], 0
	v_mfma_f32_16x16x32_bf16 v[48:51], v[24:27], v[48:51], 0
	v_mfma_f32_16x16x32_bf16 v[44:47], v[20:23], v[52:55], v[44:47]
	v_mfma_f32_16x16x32_bf16 v[48:51], v[28:31], v[52:55], v[48:51]
	v_mfma_f32_16x16x32_bf16 v[52:55], v[16:19], v[56:59], 0
	v_mfma_f32_16x16x32_bf16 v[56:59], v[24:27], v[56:59], 0
	v_mfma_f32_16x16x32_bf16 v[52:55], v[20:23], v[60:63], v[52:55]
	v_mfma_f32_16x16x32_bf16 v[56:59], v[28:31], v[60:63], v[56:59]
	s_barrier
	s_mov_b32 m0, s61
	v_lshl_add_u64 v[208:209], s[70:71], 0, v[128:129]
	global_load_lds_dwordx4 v[208:209], off
	v_lshl_add_u64 v[136:137], v[208:209], 0, s[0:1]
	s_mov_b32 m0, s62
	v_lshl_add_u64 v[248:249], s[38:39], 0, v[130:131]
	global_load_lds_dwordx4 v[136:137], off
	v_lshl_add_u64 v[136:137], v[208:209], 0, s[2:3]
	s_mov_b32 m0, s63
	s_nop 0
	global_load_lds_dwordx4 v[136:137], off
	v_lshl_add_u64 v[136:137], v[208:209], 0, s[4:5]
	s_mov_b32 m0, s64
	s_nop 0
	global_load_lds_dwordx4 v[136:137], off
	s_mov_b32 m0, s48
	v_lshl_add_u64 v[136:137], v[248:249], 0, s[0:1]
	global_load_lds_dwordx4 v[248:249], off
	s_mov_b32 m0, s49
	s_nop 0
	global_load_lds_dwordx4 v[136:137], off
	ds_read_b128 v[60:63], v142 offset:16384
	ds_read_b128 v[92:95], v142 offset:17408
	ds_read_b128 v[96:99], v142 offset:18432
	ds_read_b128 v[108:111], v142 offset:19456
	ds_read_b128 v[112:115], v142 offset:20480
	ds_read_b128 v[116:119], v142 offset:21504
	ds_read_b128 v[120:123], v142 offset:22528
	ds_read_b128 v[124:127], v142 offset:23552
	s_waitcnt vmcnt(16)
	s_waitcnt lgkmcnt(0)
	s_barrier
	s_waitcnt lgkmcnt(0)
	v_mfma_f32_16x16x32_bf16 v[144:147], v[0:3], v[60:63], 0
	v_mfma_f32_16x16x32_bf16 v[152:155], v[0:3], v[96:99], 0
	v_mfma_f32_16x16x32_bf16 v[160:163], v[0:3], v[112:115], 0
	v_mfma_f32_16x16x32_bf16 v[0:3], v[0:3], v[120:123], 0
	v_mfma_f32_16x16x32_bf16 v[144:147], v[4:7], v[92:95], v[144:147]
	v_mfma_f32_16x16x32_bf16 v[152:155], v[4:7], v[108:111], v[152:155]
	v_mfma_f32_16x16x32_bf16 v[160:163], v[4:7], v[116:119], v[160:163]
	v_mfma_f32_16x16x32_bf16 v[0:3], v[4:7], v[124:127], v[0:3]
	v_mfma_f32_16x16x32_bf16 v[4:7], v[8:11], v[120:123], 0
	v_mfma_f32_16x16x32_bf16 v[148:151], v[8:11], v[60:63], 0
	v_mfma_f32_16x16x32_bf16 v[156:159], v[8:11], v[96:99], 0
	v_mfma_f32_16x16x32_bf16 v[164:167], v[8:11], v[112:115], 0
	v_mfma_f32_16x16x32_bf16 v[4:7], v[12:15], v[124:127], v[4:7]
	v_mfma_f32_16x16x32_bf16 v[148:151], v[12:15], v[92:95], v[148:151]
	v_mfma_f32_16x16x32_bf16 v[156:159], v[12:15], v[108:111], v[156:159]
	v_mfma_f32_16x16x32_bf16 v[164:167], v[12:15], v[116:119], v[164:167]
	v_mfma_f32_16x16x32_bf16 v[12:15], v[24:27], v[60:63], 0
	v_mfma_f32_16x16x32_bf16 v[172:175], v[28:31], v[92:95], v[12:15]
	v_mfma_f32_16x16x32_bf16 v[12:15], v[16:19], v[96:99], 0
	v_mfma_f32_16x16x32_bf16 v[176:179], v[20:23], v[108:111], v[12:15]
	v_mfma_f32_16x16x32_bf16 v[12:15], v[24:27], v[96:99], 0
	v_mfma_f32_16x16x32_bf16 v[180:183], v[28:31], v[108:111], v[12:15]
	v_mfma_f32_16x16x32_bf16 v[12:15], v[16:19], v[112:115], 0
	v_mfma_f32_16x16x32_bf16 v[184:187], v[20:23], v[116:119], v[12:15]
	v_mfma_f32_16x16x32_bf16 v[12:15], v[24:27], v[112:115], 0
	v_mfma_f32_16x16x32_bf16 v[8:11], v[16:19], v[60:63], 0
	v_mfma_f32_16x16x32_bf16 v[188:191], v[28:31], v[116:119], v[12:15]
	v_mfma_f32_16x16x32_bf16 v[12:15], v[16:19], v[120:123], 0
	v_mfma_f32_16x16x32_bf16 v[8:11], v[20:23], v[92:95], v[8:11]
	v_mfma_f32_16x16x32_bf16 v[192:195], v[20:23], v[124:127], v[12:15]
	v_mfma_f32_16x16x32_bf16 v[12:15], v[24:27], v[120:123], 0
	v_mfma_f32_16x16x32_bf16 v[196:199], v[28:31], v[124:127], v[12:15]
	s_barrier
	s_add_i32 s71, 0, 0x1c000
	v_add_u32_e32 v136, s71, v139
	s_nop 2
	s_mov_b32 m0, s50
	v_lshl_add_u64 v[92:93], v[248:249], 0, s[2:3]
	global_load_lds_dwordx4 v[92:93], off
	v_lshl_add_u64 v[92:93], v[248:249], 0, s[4:5]
	s_mov_b32 m0, s51
	s_nop 0
	global_load_lds_dwordx4 v[92:93], off
	ds_read_b128 v[12:15], v143
	ds_read_b128 v[20:23], v143 offset:1024
	ds_read_b128 v[24:27], v143 offset:2048
	ds_read_b128 v[200:203], v143 offset:3072
	ds_read_b128 v[204:207], v136
	ds_read_b128 v[212:215], v136 offset:1024
	ds_read_b128 v[216:219], v136 offset:2048
	ds_read_b128 v[220:223], v136 offset:3072
	ds_read_b128 v[16:19], v142 offset:32768
	ds_read_b128 v[28:31], v142 offset:33792
	ds_read_b128 v[60:63], v142 offset:34816
	ds_read_b128 v[224:227], v142 offset:35840
	ds_read_b128 v[228:231], v142 offset:36864
	ds_read_b128 v[232:235], v142 offset:37888
	ds_read_b128 v[236:239], v142 offset:38912
	ds_read_b128 v[240:243], v142 offset:39936
	s_waitcnt vmcnt(8)
	s_waitcnt lgkmcnt(0)
	s_barrier
	s_waitcnt lgkmcnt(0)
	v_mfma_f32_16x16x32_bf16 v[64:67], v[12:15], v[16:19], v[64:67]
	v_mfma_f32_16x16x32_bf16 v[124:127], v[20:23], v[28:31], v[64:67]
	v_mfma_f32_16x16x32_bf16 v[64:67], v[24:27], v[16:19], v[68:71]
	v_mfma_f32_16x16x32_bf16 v[112:115], v[200:203], v[28:31], v[64:67]
	v_mfma_f32_16x16x32_bf16 v[64:67], v[12:15], v[60:63], v[72:75]
	v_mfma_f32_16x16x32_bf16 v[108:111], v[20:23], v[224:227], v[64:67]
	v_mfma_f32_16x16x32_bf16 v[64:67], v[24:27], v[60:63], v[76:79]
	v_mfma_f32_16x16x32_bf16 v[96:99], v[200:203], v[224:227], v[64:67]
	v_mfma_f32_16x16x32_bf16 v[64:67], v[12:15], v[228:231], v[80:83]
	v_mfma_f32_16x16x32_bf16 v[92:95], v[20:23], v[232:235], v[64:67]
	v_mfma_f32_16x16x32_bf16 v[64:67], v[24:27], v[228:231], v[84:87]
	v_mfma_f32_16x16x32_bf16 v[80:83], v[200:203], v[232:235], v[64:67]
	v_mfma_f32_16x16x32_bf16 v[64:67], v[12:15], v[236:239], v[88:91]
	v_mfma_f32_16x16x32_bf16 v[76:79], v[20:23], v[240:243], v[64:67]
	v_mfma_f32_16x16x32_bf16 v[64:67], v[24:27], v[236:239], v[100:103]
	v_mfma_f32_16x16x32_bf16 v[64:67], v[200:203], v[240:243], v[64:67]
	v_mfma_f32_16x16x32_bf16 v[68:71], v[204:207], v[16:19], v[104:107]
	v_mfma_f32_16x16x32_bf16 v[16:19], v[216:219], v[16:19], v[32:35]
	v_mfma_f32_16x16x32_bf16 v[116:119], v[220:223], v[28:31], v[16:19]
	v_mfma_f32_16x16x32_bf16 v[16:19], v[204:207], v[60:63], v[36:39]
	v_mfma_f32_16x16x32_bf16 v[104:107], v[212:215], v[224:227], v[16:19]
	v_mfma_f32_16x16x32_bf16 v[16:19], v[216:219], v[60:63], v[40:43]
	v_mfma_f32_16x16x32_bf16 v[100:103], v[220:223], v[224:227], v[16:19]
	v_mfma_f32_16x16x32_bf16 v[16:19], v[204:207], v[228:231], v[44:47]
	v_mfma_f32_16x16x32_bf16 v[88:91], v[212:215], v[232:235], v[16:19]
	v_mfma_f32_16x16x32_bf16 v[16:19], v[216:219], v[228:231], v[48:51]
	v_mfma_f32_16x16x32_bf16 v[84:87], v[220:223], v[232:235], v[16:19]
	v_mfma_f32_16x16x32_bf16 v[16:19], v[204:207], v[236:239], v[52:55]
	v_mfma_f32_16x16x32_bf16 v[72:75], v[212:215], v[240:243], v[16:19]
	v_mfma_f32_16x16x32_bf16 v[16:19], v[216:219], v[236:239], v[56:59]
	v_mfma_f32_16x16x32_bf16 v[120:123], v[212:215], v[28:31], v[68:71]
	v_mfma_f32_16x16x32_bf16 v[68:71], v[220:223], v[240:243], v[16:19]
	s_barrier
	s_add_i32 s69, s65, s45
	s_nop 2
	v_lshl_add_u64 v[16:17], v[208:209], 0, s[10:11]
	s_mov_b32 m0, s69
	s_add_i32 s70, s69, 0x2000
	global_load_lds_dwordx4 v[16:17], off
	v_lshl_add_u64 v[16:17], v[208:209], 0, s[12:13]
	s_mov_b32 m0, s70
	s_add_i32 s71, s71, s45
	global_load_lds_dwordx4 v[16:17], off
	v_lshl_add_u64 v[16:17], v[208:209], 0, s[14:15]
	s_mov_b32 m0, s71
	s_add_i32 s72, s71, 0x2000
	global_load_lds_dwordx4 v[16:17], off
	v_lshl_add_u64 v[16:17], v[208:209], 0, s[16:17]
	s_mov_b32 m0, s72
	s_nop 0
	global_load_lds_dwordx4 v[16:17], off
	v_lshl_add_u64 v[16:17], v[248:249], 0, s[10:11]
	s_mov_b32 m0, s53
	s_nop 0
	global_load_lds_dwordx4 v[16:17], off
	v_lshl_add_u64 v[16:17], v[248:249], 0, s[12:13]
	s_mov_b32 m0, s54
	s_nop 0
	global_load_lds_dwordx4 v[16:17], off
	ds_read_b128 v[36:39], v142 offset:49152
	ds_read_b128 v[40:43], v142 offset:50176
	ds_read_b128 v[224:227], v142 offset:51200
	ds_read_b128 v[228:231], v142 offset:52224
	ds_read_b128 v[232:235], v142 offset:53248
	ds_read_b128 v[236:239], v142 offset:54272
	ds_read_b128 v[240:243], v142 offset:55296
	ds_read_b128 v[244:247], v142 offset:56320
	s_waitcnt vmcnt(8)
	s_waitcnt lgkmcnt(0)
	s_barrier
	s_waitcnt lgkmcnt(0)
	v_mfma_f32_16x16x32_bf16 v[16:19], v[12:15], v[36:39], v[144:147]
	v_mfma_f32_16x16x32_bf16 v[60:63], v[20:23], v[40:43], v[16:19]
	v_mfma_f32_16x16x32_bf16 v[16:19], v[24:27], v[36:39], v[148:151]
	v_mfma_f32_16x16x32_bf16 v[48:51], v[200:203], v[40:43], v[16:19]
	v_mfma_f32_16x16x32_bf16 v[16:19], v[12:15], v[224:227], v[152:155]
	v_mfma_f32_16x16x32_bf16 v[44:47], v[20:23], v[228:231], v[16:19]
	v_mfma_f32_16x16x32_bf16 v[16:19], v[24:27], v[224:227], v[156:159]
	v_mfma_f32_16x16x32_bf16 v[32:35], v[200:203], v[228:231], v[16:19]
	v_mfma_f32_16x16x32_bf16 v[16:19], v[12:15], v[232:235], v[160:163]
	v_mfma_f32_16x16x32_bf16 v[0:3], v[12:15], v[240:243], v[0:3]
	v_mfma_f32_16x16x32_bf16 v[28:31], v[20:23], v[236:239], v[16:19]
	v_mfma_f32_16x16x32_bf16 v[16:19], v[24:27], v[232:235], v[164:167]
	v_mfma_f32_16x16x32_bf16 v[12:15], v[20:23], v[244:247], v[0:3]
	v_mfma_f32_16x16x32_bf16 v[0:3], v[24:27], v[240:243], v[4:7]
	v_mfma_f32_16x16x32_bf16 v[16:19], v[200:203], v[236:239], v[16:19]
	v_mfma_f32_16x16x32_bf16 v[0:3], v[200:203], v[244:247], v[0:3]
	v_mfma_f32_16x16x32_bf16 v[4:7], v[204:207], v[36:39], v[8:11]
	v_mfma_f32_16x16x32_bf16 v[56:59], v[212:215], v[40:43], v[4:7]
	v_mfma_f32_16x16x32_bf16 v[4:7], v[216:219], v[36:39], v[172:175]
	v_mfma_f32_16x16x32_bf16 v[52:55], v[220:223], v[40:43], v[4:7]
	v_mfma_f32_16x16x32_bf16 v[4:7], v[204:207], v[224:227], v[176:179]
	v_mfma_f32_16x16x32_bf16 v[40:43], v[212:215], v[228:231], v[4:7]
	v_mfma_f32_16x16x32_bf16 v[4:7], v[216:219], v[224:227], v[180:183]
	v_mfma_f32_16x16x32_bf16 v[36:39], v[220:223], v[228:231], v[4:7]
	v_mfma_f32_16x16x32_bf16 v[4:7], v[204:207], v[232:235], v[184:187]
	v_mfma_f32_16x16x32_bf16 v[24:27], v[212:215], v[236:239], v[4:7]
	v_mfma_f32_16x16x32_bf16 v[4:7], v[216:219], v[232:235], v[188:191]
	v_mfma_f32_16x16x32_bf16 v[20:23], v[220:223], v[236:239], v[4:7]
	v_mfma_f32_16x16x32_bf16 v[4:7], v[204:207], v[240:243], v[192:195]
	v_mfma_f32_16x16x32_bf16 v[8:11], v[212:215], v[244:247], v[4:7]
	v_mfma_f32_16x16x32_bf16 v[4:7], v[216:219], v[240:243], v[196:199]
	v_mfma_f32_16x16x32_bf16 v[4:7], v[220:223], v[244:247], v[4:7]
	s_barrier
.LBB0_970:
	s_add_i32 s21, s21, 2
	s_mov_b32 s38, s21
	s_ashr_i32 s39, s38, 31
	s_lshl_b64 s[74:75], s[38:39], 7
	s_add_u32 s39, s74, 0x100
	s_addc_u32 s73, s75, 0
	s_add_u32 s76, s34, s39
	s_addc_u32 s77, s35, s73
	s_add_u32 s78, s30, s39
	s_addc_u32 s73, s31, s73
	s_cmp_eq_u32 s38, 14
	s_cselect_b32 s39, s67, s77
	s_cselect_b32 s38, s68, s76
	s_cselect_b32 s77, s23, s73
	s_cselect_b32 s76, s66, s78
	s_add_u32 s74, s34, s74
	s_addc_u32 s75, s35, s75
	v_lshl_add_u64 v[208:209], s[74:75], 0, v[130:131]
	s_mov_b32 m0, s59
	v_lshl_add_u64 v[216:217], v[208:209], 0, s[14:15]
	global_load_lds_dwordx4 v[216:217], off
	v_lshl_add_u64 v[208:209], v[208:209], 0, s[16:17]
	s_mov_b32 m0, s60
	s_nop 0
	global_load_lds_dwordx4 v[208:209], off
	ds_read_b128 v[144:147], v140
	ds_read_b128 v[148:151], v140 offset:1024
	ds_read_b128 v[152:155], v140 offset:2048
	ds_read_b128 v[156:159], v140 offset:3072
	ds_read_b128 v[160:163], v141
	ds_read_b128 v[164:167], v141 offset:1024
	ds_read_b128 v[172:175], v141 offset:2048
	ds_read_b128 v[176:179], v141 offset:3072
	ds_read_b128 v[180:183], v142
	ds_read_b128 v[184:187], v142 offset:1024
	ds_read_b128 v[188:191], v142 offset:2048
	ds_read_b128 v[192:195], v142 offset:3072
	ds_read_b128 v[196:199], v142 offset:4096
	ds_read_b128 v[200:203], v142 offset:5120
	ds_read_b128 v[204:207], v142 offset:6144
	ds_read_b128 v[212:215], v142 offset:7168
	s_waitcnt vmcnt(8)
	s_waitcnt lgkmcnt(0)
	s_barrier
	s_waitcnt lgkmcnt(0)
	v_mfma_f32_16x16x32_bf16 v[124:127], v[144:147], v[180:183], v[124:127]
	v_mfma_f32_16x16x32_bf16 v[112:115], v[152:155], v[180:183], v[112:115]
	v_mfma_f32_16x16x32_bf16 v[108:111], v[144:147], v[188:191], v[108:111]
	v_mfma_f32_16x16x32_bf16 v[96:99], v[152:155], v[188:191], v[96:99]
	v_mfma_f32_16x16x32_bf16 v[92:95], v[144:147], v[196:199], v[92:95]
	v_mfma_f32_16x16x32_bf16 v[80:83], v[152:155], v[196:199], v[80:83]
	v_mfma_f32_16x16x32_bf16 v[76:79], v[144:147], v[204:207], v[76:79]
	v_mfma_f32_16x16x32_bf16 v[64:67], v[152:155], v[204:207], v[64:67]
	v_mfma_f32_16x16x32_bf16 v[124:127], v[148:151], v[184:187], v[124:127]
	v_mfma_f32_16x16x32_bf16 v[112:115], v[156:159], v[184:187], v[112:115]
	v_mfma_f32_16x16x32_bf16 v[108:111], v[148:151], v[192:195], v[108:111]
	v_mfma_f32_16x16x32_bf16 v[96:99], v[156:159], v[192:195], v[96:99]
	v_mfma_f32_16x16x32_bf16 v[92:95], v[148:151], v[200:203], v[92:95]
	v_mfma_f32_16x16x32_bf16 v[80:83], v[156:159], v[200:203], v[80:83]
	v_mfma_f32_16x16x32_bf16 v[76:79], v[148:151], v[212:215], v[76:79]
	v_mfma_f32_16x16x32_bf16 v[64:67], v[156:159], v[212:215], v[64:67]
	v_mfma_f32_16x16x32_bf16 v[120:123], v[160:163], v[180:183], v[120:123]
	v_mfma_f32_16x16x32_bf16 v[116:119], v[172:175], v[180:183], v[116:119]
	v_mfma_f32_16x16x32_bf16 v[104:107], v[160:163], v[188:191], v[104:107]
	v_mfma_f32_16x16x32_bf16 v[100:103], v[172:175], v[188:191], v[100:103]
	v_mfma_f32_16x16x32_bf16 v[88:91], v[160:163], v[196:199], v[88:91]
	v_mfma_f32_16x16x32_bf16 v[84:87], v[172:175], v[196:199], v[84:87]
	v_mfma_f32_16x16x32_bf16 v[72:75], v[160:163], v[204:207], v[72:75]
	v_mfma_f32_16x16x32_bf16 v[68:71], v[172:175], v[204:207], v[68:71]
	v_mfma_f32_16x16x32_bf16 v[120:123], v[164:167], v[184:187], v[120:123]
	v_mfma_f32_16x16x32_bf16 v[116:119], v[176:179], v[184:187], v[116:119]
	v_mfma_f32_16x16x32_bf16 v[104:107], v[164:167], v[192:195], v[104:107]
	v_mfma_f32_16x16x32_bf16 v[100:103], v[176:179], v[192:195], v[100:103]
	v_mfma_f32_16x16x32_bf16 v[88:91], v[164:167], v[200:203], v[88:91]
	v_mfma_f32_16x16x32_bf16 v[84:87], v[176:179], v[200:203], v[84:87]
	v_mfma_f32_16x16x32_bf16 v[72:75], v[164:167], v[212:215], v[72:75]
	v_mfma_f32_16x16x32_bf16 v[68:71], v[176:179], v[212:215], v[68:71]
	s_barrier
	s_mov_b32 m0, s61
	v_lshl_add_u64 v[208:209], s[76:77], 0, v[128:129]
	global_load_lds_dwordx4 v[208:209], off
	v_lshl_add_u64 v[216:217], v[208:209], 0, s[0:1]
	s_mov_b32 m0, s62
	s_nop 0
	global_load_lds_dwordx4 v[216:217], off
	v_lshl_add_u64 v[216:217], v[208:209], 0, s[2:3]
	s_mov_b32 m0, s63
	s_nop 0
	global_load_lds_dwordx4 v[216:217], off
	v_lshl_add_u64 v[216:217], v[208:209], 0, s[4:5]
	s_mov_b32 m0, s64
	s_nop 0
	global_load_lds_dwordx4 v[216:217], off
	v_lshl_add_u64 v[216:217], s[38:39], 0, v[130:131]
	s_mov_b32 m0, s48
	v_lshl_add_u64 v[218:219], v[216:217], 0, s[0:1]
	global_load_lds_dwordx4 v[216:217], off
	s_mov_b32 m0, s49
	s_nop 0
	global_load_lds_dwordx4 v[218:219], off
	ds_read_b128 v[180:183], v142 offset:16384
	ds_read_b128 v[184:187], v142 offset:17408
	ds_read_b128 v[188:191], v142 offset:18432
	ds_read_b128 v[192:195], v142 offset:19456
	ds_read_b128 v[196:199], v142 offset:20480
	ds_read_b128 v[200:203], v142 offset:21504
	ds_read_b128 v[204:207], v142 offset:22528
	ds_read_b128 v[212:215], v142 offset:23552
	s_waitcnt vmcnt(8)
	s_waitcnt lgkmcnt(0)
	s_barrier
	s_waitcnt lgkmcnt(0)
	v_mfma_f32_16x16x32_bf16 v[60:63], v[144:147], v[180:183], v[60:63]
	v_mfma_f32_16x16x32_bf16 v[48:51], v[152:155], v[180:183], v[48:51]
	v_mfma_f32_16x16x32_bf16 v[44:47], v[144:147], v[188:191], v[44:47]
	v_mfma_f32_16x16x32_bf16 v[32:35], v[152:155], v[188:191], v[32:35]
	v_mfma_f32_16x16x32_bf16 v[28:31], v[144:147], v[196:199], v[28:31]
	v_mfma_f32_16x16x32_bf16 v[16:19], v[152:155], v[196:199], v[16:19]
	v_mfma_f32_16x16x32_bf16 v[12:15], v[144:147], v[204:207], v[12:15]
	v_mfma_f32_16x16x32_bf16 v[0:3], v[152:155], v[204:207], v[0:3]
	v_mfma_f32_16x16x32_bf16 v[60:63], v[148:151], v[184:187], v[60:63]
	v_mfma_f32_16x16x32_bf16 v[48:51], v[156:159], v[184:187], v[48:51]
	v_mfma_f32_16x16x32_bf16 v[44:47], v[148:151], v[192:195], v[44:47]
	v_mfma_f32_16x16x32_bf16 v[32:35], v[156:159], v[192:195], v[32:35]
	v_mfma_f32_16x16x32_bf16 v[28:31], v[148:151], v[200:203], v[28:31]
	v_mfma_f32_16x16x32_bf16 v[16:19], v[156:159], v[200:203], v[16:19]
	v_mfma_f32_16x16x32_bf16 v[12:15], v[148:151], v[212:215], v[12:15]
	v_mfma_f32_16x16x32_bf16 v[0:3], v[156:159], v[212:215], v[0:3]
	v_mfma_f32_16x16x32_bf16 v[56:59], v[160:163], v[180:183], v[56:59]
	v_mfma_f32_16x16x32_bf16 v[52:55], v[172:175], v[180:183], v[52:55]
	v_mfma_f32_16x16x32_bf16 v[40:43], v[160:163], v[188:191], v[40:43]
	v_mfma_f32_16x16x32_bf16 v[36:39], v[172:175], v[188:191], v[36:39]
	v_mfma_f32_16x16x32_bf16 v[24:27], v[160:163], v[196:199], v[24:27]
	v_mfma_f32_16x16x32_bf16 v[20:23], v[172:175], v[196:199], v[20:23]
	v_mfma_f32_16x16x32_bf16 v[8:11], v[160:163], v[204:207], v[8:11]
	v_mfma_f32_16x16x32_bf16 v[4:7], v[172:175], v[204:207], v[4:7]
	v_mfma_f32_16x16x32_bf16 v[56:59], v[164:167], v[184:187], v[56:59]
	v_mfma_f32_16x16x32_bf16 v[52:55], v[176:179], v[184:187], v[52:55]
	v_mfma_f32_16x16x32_bf16 v[40:43], v[164:167], v[192:195], v[40:43]
	v_mfma_f32_16x16x32_bf16 v[36:39], v[176:179], v[192:195], v[36:39]
	v_mfma_f32_16x16x32_bf16 v[24:27], v[164:167], v[200:203], v[24:27]
	v_mfma_f32_16x16x32_bf16 v[20:23], v[176:179], v[200:203], v[20:23]
	v_mfma_f32_16x16x32_bf16 v[8:11], v[164:167], v[212:215], v[8:11]
	v_mfma_f32_16x16x32_bf16 v[4:7], v[176:179], v[212:215], v[4:7]
	s_barrier
	s_mov_b32 m0, s50
	v_lshl_add_u64 v[218:219], v[216:217], 0, s[2:3]
	global_load_lds_dwordx4 v[218:219], off
	v_lshl_add_u64 v[218:219], v[216:217], 0, s[4:5]
	s_mov_b32 m0, s51
	s_nop 0
	global_load_lds_dwordx4 v[218:219], off
	ds_read_b128 v[144:147], v143
	ds_read_b128 v[148:151], v143 offset:1024
	ds_read_b128 v[152:155], v143 offset:2048
	ds_read_b128 v[156:159], v143 offset:3072
	ds_read_b128 v[160:163], v136
	ds_read_b128 v[164:167], v136 offset:1024
	ds_read_b128 v[172:175], v136 offset:2048
	ds_read_b128 v[176:179], v136 offset:3072
	ds_read_b128 v[180:183], v142 offset:32768
	ds_read_b128 v[184:187], v142 offset:33792
	ds_read_b128 v[188:191], v142 offset:34816
	ds_read_b128 v[192:195], v142 offset:35840
	ds_read_b128 v[196:199], v142 offset:36864
	ds_read_b128 v[200:203], v142 offset:37888
	ds_read_b128 v[204:207], v142 offset:38912
	ds_read_b128 v[212:215], v142 offset:39936
	s_waitcnt vmcnt(8)
	s_waitcnt lgkmcnt(0)
	s_barrier
	s_waitcnt lgkmcnt(0)
	v_mfma_f32_16x16x32_bf16 v[124:127], v[144:147], v[180:183], v[124:127]
	v_mfma_f32_16x16x32_bf16 v[112:115], v[152:155], v[180:183], v[112:115]
	v_mfma_f32_16x16x32_bf16 v[108:111], v[144:147], v[188:191], v[108:111]
	v_mfma_f32_16x16x32_bf16 v[96:99], v[152:155], v[188:191], v[96:99]
	v_mfma_f32_16x16x32_bf16 v[92:95], v[144:147], v[196:199], v[92:95]
	v_mfma_f32_16x16x32_bf16 v[80:83], v[152:155], v[196:199], v[80:83]
	v_mfma_f32_16x16x32_bf16 v[76:79], v[144:147], v[204:207], v[76:79]
	v_mfma_f32_16x16x32_bf16 v[64:67], v[152:155], v[204:207], v[64:67]
	v_mfma_f32_16x16x32_bf16 v[124:127], v[148:151], v[184:187], v[124:127]
	v_mfma_f32_16x16x32_bf16 v[112:115], v[156:159], v[184:187], v[112:115]
	v_mfma_f32_16x16x32_bf16 v[108:111], v[148:151], v[192:195], v[108:111]
	v_mfma_f32_16x16x32_bf16 v[96:99], v[156:159], v[192:195], v[96:99]
	v_mfma_f32_16x16x32_bf16 v[92:95], v[148:151], v[200:203], v[92:95]
	v_mfma_f32_16x16x32_bf16 v[80:83], v[156:159], v[200:203], v[80:83]
	v_mfma_f32_16x16x32_bf16 v[76:79], v[148:151], v[212:215], v[76:79]
	v_mfma_f32_16x16x32_bf16 v[64:67], v[156:159], v[212:215], v[64:67]
	v_mfma_f32_16x16x32_bf16 v[120:123], v[160:163], v[180:183], v[120:123]
	v_mfma_f32_16x16x32_bf16 v[116:119], v[172:175], v[180:183], v[116:119]
	v_mfma_f32_16x16x32_bf16 v[104:107], v[160:163], v[188:191], v[104:107]
	v_mfma_f32_16x16x32_bf16 v[100:103], v[172:175], v[188:191], v[100:103]
	v_mfma_f32_16x16x32_bf16 v[88:91], v[160:163], v[196:199], v[88:91]
	v_mfma_f32_16x16x32_bf16 v[84:87], v[172:175], v[196:199], v[84:87]
	v_mfma_f32_16x16x32_bf16 v[72:75], v[160:163], v[204:207], v[72:75]
	v_mfma_f32_16x16x32_bf16 v[68:71], v[172:175], v[204:207], v[68:71]
	v_mfma_f32_16x16x32_bf16 v[120:123], v[164:167], v[184:187], v[120:123]
	v_mfma_f32_16x16x32_bf16 v[116:119], v[176:179], v[184:187], v[116:119]
	v_mfma_f32_16x16x32_bf16 v[104:107], v[164:167], v[192:195], v[104:107]
	v_mfma_f32_16x16x32_bf16 v[100:103], v[176:179], v[192:195], v[100:103]
	v_mfma_f32_16x16x32_bf16 v[88:91], v[164:167], v[200:203], v[88:91]
	v_mfma_f32_16x16x32_bf16 v[84:87], v[176:179], v[200:203], v[84:87]
	v_mfma_f32_16x16x32_bf16 v[72:75], v[164:167], v[212:215], v[72:75]
	v_mfma_f32_16x16x32_bf16 v[68:71], v[176:179], v[212:215], v[68:71]
	s_barrier
	s_mov_b32 m0, s69
	v_lshl_add_u64 v[218:219], v[208:209], 0, s[10:11]
	global_load_lds_dwordx4 v[218:219], off
	v_lshl_add_u64 v[218:219], v[208:209], 0, s[12:13]
	s_mov_b32 m0, s70
	s_nop 0
	global_load_lds_dwordx4 v[218:219], off
	v_lshl_add_u64 v[218:219], v[208:209], 0, s[14:15]
	s_mov_b32 m0, s71
	v_lshl_add_u64 v[208:209], v[208:209], 0, s[16:17]
	global_load_lds_dwordx4 v[218:219], off
	s_mov_b32 m0, s72
	s_nop 0
	global_load_lds_dwordx4 v[208:209], off
	v_lshl_add_u64 v[208:209], v[216:217], 0, s[10:11]
	s_mov_b32 m0, s53
	s_nop 0
	global_load_lds_dwordx4 v[208:209], off
	v_lshl_add_u64 v[208:209], v[216:217], 0, s[12:13]
	s_mov_b32 m0, s54
	s_nop 0
	global_load_lds_dwordx4 v[208:209], off
	ds_read_b128 v[180:183], v142 offset:49152
	ds_read_b128 v[184:187], v142 offset:50176
	ds_read_b128 v[188:191], v142 offset:51200
	ds_read_b128 v[192:195], v142 offset:52224
	ds_read_b128 v[196:199], v142 offset:53248
	ds_read_b128 v[200:203], v142 offset:54272
	ds_read_b128 v[204:207], v142 offset:55296
	ds_read_b128 v[212:215], v142 offset:56320
	s_waitcnt vmcnt(8)
	s_waitcnt lgkmcnt(0)
	s_barrier
	s_waitcnt lgkmcnt(0)
	v_mfma_f32_16x16x32_bf16 v[60:63], v[144:147], v[180:183], v[60:63]
	v_mfma_f32_16x16x32_bf16 v[48:51], v[152:155], v[180:183], v[48:51]
	v_mfma_f32_16x16x32_bf16 v[44:47], v[144:147], v[188:191], v[44:47]
	v_mfma_f32_16x16x32_bf16 v[32:35], v[152:155], v[188:191], v[32:35]
	v_mfma_f32_16x16x32_bf16 v[28:31], v[144:147], v[196:199], v[28:31]
	v_mfma_f32_16x16x32_bf16 v[16:19], v[152:155], v[196:199], v[16:19]
	v_mfma_f32_16x16x32_bf16 v[12:15], v[144:147], v[204:207], v[12:15]
	v_mfma_f32_16x16x32_bf16 v[0:3], v[152:155], v[204:207], v[0:3]
	v_mfma_f32_16x16x32_bf16 v[60:63], v[148:151], v[184:187], v[60:63]
	v_mfma_f32_16x16x32_bf16 v[48:51], v[156:159], v[184:187], v[48:51]
	v_mfma_f32_16x16x32_bf16 v[44:47], v[148:151], v[192:195], v[44:47]
	v_mfma_f32_16x16x32_bf16 v[32:35], v[156:159], v[192:195], v[32:35]
	v_mfma_f32_16x16x32_bf16 v[28:31], v[148:151], v[200:203], v[28:31]
	v_mfma_f32_16x16x32_bf16 v[16:19], v[156:159], v[200:203], v[16:19]
	v_mfma_f32_16x16x32_bf16 v[12:15], v[148:151], v[212:215], v[12:15]
	v_mfma_f32_16x16x32_bf16 v[0:3], v[156:159], v[212:215], v[0:3]
	v_mfma_f32_16x16x32_bf16 v[56:59], v[160:163], v[180:183], v[56:59]
	v_mfma_f32_16x16x32_bf16 v[52:55], v[172:175], v[180:183], v[52:55]
	v_mfma_f32_16x16x32_bf16 v[40:43], v[160:163], v[188:191], v[40:43]
	v_mfma_f32_16x16x32_bf16 v[36:39], v[172:175], v[188:191], v[36:39]
	v_mfma_f32_16x16x32_bf16 v[24:27], v[160:163], v[196:199], v[24:27]
	v_mfma_f32_16x16x32_bf16 v[20:23], v[172:175], v[196:199], v[20:23]
	v_mfma_f32_16x16x32_bf16 v[8:11], v[160:163], v[204:207], v[8:11]
	v_mfma_f32_16x16x32_bf16 v[4:7], v[172:175], v[204:207], v[4:7]
	v_mfma_f32_16x16x32_bf16 v[56:59], v[164:167], v[184:187], v[56:59]
	v_mfma_f32_16x16x32_bf16 v[52:55], v[176:179], v[184:187], v[52:55]
	v_mfma_f32_16x16x32_bf16 v[40:43], v[164:167], v[192:195], v[40:43]
	v_mfma_f32_16x16x32_bf16 v[36:39], v[176:179], v[192:195], v[36:39]
	v_mfma_f32_16x16x32_bf16 v[24:27], v[164:167], v[200:203], v[24:27]
	v_mfma_f32_16x16x32_bf16 v[20:23], v[176:179], v[200:203], v[20:23]
	v_mfma_f32_16x16x32_bf16 v[8:11], v[164:167], v[212:215], v[8:11]
	v_mfma_f32_16x16x32_bf16 v[4:7], v[176:179], v[212:215], v[4:7]
	s_barrier
	s_cmp_gt_u32 s21, 13
	s_cbranch_scc0 .LBB0_970
	s_and_b64 vcc, exec, s[18:19]
	s_cbranch_vccz .LBB0_973
	s_barrier

.LBB0_1046:
	s_add_i32 s55, s55, 2
	s_mov_b32 s56, s55
	s_ashr_i32 s57, s56, 31
	s_lshl_b64 s[58:59], s[56:57], 7
	s_add_u32 s57, s58, 0x100
	s_addc_u32 s60, s59, 0
	s_add_u32 s61, s24, s57
	s_addc_u32 s62, s25, s60
	s_add_u32 s63, s22, s57
	s_addc_u32 s60, s23, s60
	s_cmp_eq_u32 s56, 42
	s_cselect_b32 s57, s1, s62
	s_cselect_b32 s56, s0, s61
	s_cselect_b32 s61, s27, s60
	s_cselect_b32 s60, s26, s63
	v_lshl_add_u64 v[208:209], v[136:137], 0, s[58:59]
	v_lshl_add_u64 v[216:217], v[208:209], 0, s[12:13]
	s_add_i32 m0, s39, 0xc000
	s_nop 0
	global_load_lds_dwordx4 v[216:217], off
	v_lshl_add_u64 v[208:209], v[208:209], 0, s[14:15]
	s_add_i32 m0, s39, 0xe000
	s_nop 0
	global_load_lds_dwordx4 v[208:209], off
	ds_read_b128 v[144:147], v140
	ds_read_b128 v[148:151], v140 offset:1024
	ds_read_b128 v[152:155], v140 offset:2048
	ds_read_b128 v[156:159], v140 offset:3072
	ds_read_b128 v[160:163], v141
	ds_read_b128 v[164:167], v141 offset:1024
	ds_read_b128 v[172:175], v141 offset:2048
	ds_read_b128 v[176:179], v141 offset:3072
	ds_read_b128 v[180:183], v142
	ds_read_b128 v[184:187], v142 offset:1024
	ds_read_b128 v[188:191], v142 offset:2048
	ds_read_b128 v[192:195], v142 offset:3072
	ds_read_b128 v[196:199], v142 offset:4096
	ds_read_b128 v[200:203], v142 offset:5120
	ds_read_b128 v[204:207], v142 offset:6144
	ds_read_b128 v[212:215], v142 offset:7168
	s_waitcnt vmcnt(8)
	s_waitcnt lgkmcnt(0)
	s_barrier
	s_waitcnt lgkmcnt(0)
	v_mfma_f32_16x16x32_bf16 v[124:127], v[144:147], v[180:183], v[124:127]
	v_mfma_f32_16x16x32_bf16 v[120:123], v[152:155], v[180:183], v[120:123]
	v_mfma_f32_16x16x32_bf16 v[116:119], v[144:147], v[188:191], v[116:119]
	v_mfma_f32_16x16x32_bf16 v[112:115], v[152:155], v[188:191], v[112:115]
	v_mfma_f32_16x16x32_bf16 v[100:103], v[144:147], v[196:199], v[100:103]
	v_mfma_f32_16x16x32_bf16 v[96:99], v[152:155], v[196:199], v[96:99]
	v_mfma_f32_16x16x32_bf16 v[84:87], v[144:147], v[204:207], v[84:87]
	v_mfma_f32_16x16x32_bf16 v[80:83], v[152:155], v[204:207], v[80:83]
	v_mfma_f32_16x16x32_bf16 v[124:127], v[148:151], v[184:187], v[124:127]
	v_mfma_f32_16x16x32_bf16 v[120:123], v[156:159], v[184:187], v[120:123]
	v_mfma_f32_16x16x32_bf16 v[116:119], v[148:151], v[192:195], v[116:119]
	v_mfma_f32_16x16x32_bf16 v[112:115], v[156:159], v[192:195], v[112:115]
	v_mfma_f32_16x16x32_bf16 v[100:103], v[148:151], v[200:203], v[100:103]
	v_mfma_f32_16x16x32_bf16 v[96:99], v[156:159], v[200:203], v[96:99]
	v_mfma_f32_16x16x32_bf16 v[84:87], v[148:151], v[212:215], v[84:87]
	v_mfma_f32_16x16x32_bf16 v[80:83], v[156:159], v[212:215], v[80:83]
	v_mfma_f32_16x16x32_bf16 v[108:111], v[160:163], v[180:183], v[108:111]
	v_mfma_f32_16x16x32_bf16 v[104:107], v[172:175], v[180:183], v[104:107]
	v_mfma_f32_16x16x32_bf16 v[92:95], v[160:163], v[188:191], v[92:95]
	v_mfma_f32_16x16x32_bf16 v[88:91], v[172:175], v[188:191], v[88:91]
	v_mfma_f32_16x16x32_bf16 v[76:79], v[160:163], v[196:199], v[76:79]
	v_mfma_f32_16x16x32_bf16 v[72:75], v[172:175], v[196:199], v[72:75]
	v_mfma_f32_16x16x32_bf16 v[68:71], v[160:163], v[204:207], v[68:71]
	v_mfma_f32_16x16x32_bf16 v[64:67], v[172:175], v[204:207], v[64:67]
	v_mfma_f32_16x16x32_bf16 v[108:111], v[164:167], v[184:187], v[108:111]
	v_mfma_f32_16x16x32_bf16 v[104:107], v[176:179], v[184:187], v[104:107]
	v_mfma_f32_16x16x32_bf16 v[92:95], v[164:167], v[192:195], v[92:95]
	v_mfma_f32_16x16x32_bf16 v[88:91], v[176:179], v[192:195], v[88:91]
	v_mfma_f32_16x16x32_bf16 v[76:79], v[164:167], v[200:203], v[76:79]
	v_mfma_f32_16x16x32_bf16 v[72:75], v[176:179], v[200:203], v[72:75]
	v_mfma_f32_16x16x32_bf16 v[68:71], v[164:167], v[212:215], v[68:71]
	v_mfma_f32_16x16x32_bf16 v[64:67], v[176:179], v[212:215], v[64:67]
	s_barrier
	s_add_i32 s58, s49, s38
	v_lshl_add_u64 v[208:209], s[60:61], 0, v[130:131]
	s_mov_b32 m0, s58
	s_nop 0
	global_load_lds_dwordx4 v[208:209], off
	v_lshl_add_u64 v[216:217], v[208:209], 0, s[2:3]
	s_add_i32 m0, s58, 0x2000
	s_add_i32 s58, s50, s38
	global_load_lds_dwordx4 v[216:217], off
	v_lshl_add_u64 v[216:217], v[208:209], 0, s[4:5]
	s_mov_b32 m0, s58
	s_nop 0
	global_load_lds_dwordx4 v[216:217], off
	v_lshl_add_u64 v[216:217], v[208:209], 0, s[6:7]
	s_add_i32 m0, s58, 0x2000
	s_nop 0
	global_load_lds_dwordx4 v[216:217], off
	v_lshl_add_u64 v[216:217], s[56:57], 0, v[128:129]
	s_mov_b32 m0, s39
	v_lshl_add_u64 v[218:219], v[216:217], 0, s[2:3]
	global_load_lds_dwordx4 v[216:217], off
	s_mov_b32 m0, s40
	s_nop 0
	global_load_lds_dwordx4 v[218:219], off
	ds_read_b128 v[180:183], v142 offset:16384
	ds_read_b128 v[184:187], v142 offset:17408
	ds_read_b128 v[188:191], v142 offset:18432
	ds_read_b128 v[192:195], v142 offset:19456
	ds_read_b128 v[196:199], v142 offset:20480
	ds_read_b128 v[200:203], v142 offset:21504
	ds_read_b128 v[204:207], v142 offset:22528
	ds_read_b128 v[212:215], v142 offset:23552
	s_waitcnt vmcnt(8)
	s_waitcnt lgkmcnt(0)
	s_barrier
	s_waitcnt lgkmcnt(0)
	v_mfma_f32_16x16x32_bf16 v[60:63], v[144:147], v[180:183], v[60:63]
	v_mfma_f32_16x16x32_bf16 v[56:59], v[152:155], v[180:183], v[56:59]
	v_mfma_f32_16x16x32_bf16 v[52:55], v[144:147], v[188:191], v[52:55]
	v_mfma_f32_16x16x32_bf16 v[48:51], v[152:155], v[188:191], v[48:51]
	v_mfma_f32_16x16x32_bf16 v[36:39], v[144:147], v[196:199], v[36:39]
	v_mfma_f32_16x16x32_bf16 v[32:35], v[152:155], v[196:199], v[32:35]
	v_mfma_f32_16x16x32_bf16 v[20:23], v[144:147], v[204:207], v[20:23]
	v_mfma_f32_16x16x32_bf16 v[16:19], v[152:155], v[204:207], v[16:19]
	v_mfma_f32_16x16x32_bf16 v[60:63], v[148:151], v[184:187], v[60:63]
	v_mfma_f32_16x16x32_bf16 v[56:59], v[156:159], v[184:187], v[56:59]
	v_mfma_f32_16x16x32_bf16 v[52:55], v[148:151], v[192:195], v[52:55]
	v_mfma_f32_16x16x32_bf16 v[48:51], v[156:159], v[192:195], v[48:51]
	v_mfma_f32_16x16x32_bf16 v[36:39], v[148:151], v[200:203], v[36:39]
	v_mfma_f32_16x16x32_bf16 v[32:35], v[156:159], v[200:203], v[32:35]
	v_mfma_f32_16x16x32_bf16 v[20:23], v[148:151], v[212:215], v[20:23]
	v_mfma_f32_16x16x32_bf16 v[16:19], v[156:159], v[212:215], v[16:19]
	v_mfma_f32_16x16x32_bf16 v[44:47], v[160:163], v[180:183], v[44:47]
	v_mfma_f32_16x16x32_bf16 v[40:43], v[172:175], v[180:183], v[40:43]
	v_mfma_f32_16x16x32_bf16 v[28:31], v[160:163], v[188:191], v[28:31]
	v_mfma_f32_16x16x32_bf16 v[24:27], v[172:175], v[188:191], v[24:27]
	v_mfma_f32_16x16x32_bf16 v[12:15], v[160:163], v[196:199], v[12:15]
	v_mfma_f32_16x16x32_bf16 v[8:11], v[172:175], v[196:199], v[8:11]
	v_mfma_f32_16x16x32_bf16 v[4:7], v[160:163], v[204:207], v[4:7]
	v_mfma_f32_16x16x32_bf16 v[0:3], v[172:175], v[204:207], v[0:3]
	v_mfma_f32_16x16x32_bf16 v[44:47], v[164:167], v[184:187], v[44:47]
	v_mfma_f32_16x16x32_bf16 v[40:43], v[176:179], v[184:187], v[40:43]
	v_mfma_f32_16x16x32_bf16 v[28:31], v[164:167], v[192:195], v[28:31]
	v_mfma_f32_16x16x32_bf16 v[24:27], v[176:179], v[192:195], v[24:27]
	v_mfma_f32_16x16x32_bf16 v[12:15], v[164:167], v[200:203], v[12:15]
	v_mfma_f32_16x16x32_bf16 v[8:11], v[176:179], v[200:203], v[8:11]
	v_mfma_f32_16x16x32_bf16 v[4:7], v[164:167], v[212:215], v[4:7]
	v_mfma_f32_16x16x32_bf16 v[0:3], v[176:179], v[212:215], v[0:3]
	s_barrier
	s_mov_b32 m0, s41
	v_lshl_add_u64 v[218:219], v[216:217], 0, s[4:5]
	global_load_lds_dwordx4 v[218:219], off
	v_lshl_add_u64 v[218:219], v[216:217], 0, s[6:7]
	s_mov_b32 m0, s42
	s_nop 0
	global_load_lds_dwordx4 v[218:219], off
	s_add_i32 s56, 0, 0x18000
	v_add_u32_e32 v143, s56, v139
	s_add_i32 s57, 0, 0x1c000
	ds_read_b128 v[144:147], v143
	ds_read_b128 v[148:151], v143 offset:1024
	ds_read_b128 v[152:155], v143 offset:2048
	ds_read_b128 v[156:159], v143 offset:3072
	v_add_u32_e32 v143, s57, v139
	ds_read_b128 v[160:163], v143
	ds_read_b128 v[164:167], v143 offset:1024
	ds_read_b128 v[172:175], v143 offset:2048
	ds_read_b128 v[176:179], v143 offset:3072
	ds_read_b128 v[180:183], v142 offset:32768
	ds_read_b128 v[184:187], v142 offset:33792
	ds_read_b128 v[188:191], v142 offset:34816
	ds_read_b128 v[192:195], v142 offset:35840
	ds_read_b128 v[196:199], v142 offset:36864
	ds_read_b128 v[200:203], v142 offset:37888
	ds_read_b128 v[204:207], v142 offset:38912
	ds_read_b128 v[212:215], v142 offset:39936
	s_nop 0
	s_waitcnt vmcnt(8)
	s_waitcnt lgkmcnt(0)
	s_barrier
	s_waitcnt lgkmcnt(0)
	v_mfma_f32_16x16x32_bf16 v[124:127], v[144:147], v[180:183], v[124:127]
	v_mfma_f32_16x16x32_bf16 v[120:123], v[152:155], v[180:183], v[120:123]
	v_mfma_f32_16x16x32_bf16 v[116:119], v[144:147], v[188:191], v[116:119]
	v_mfma_f32_16x16x32_bf16 v[112:115], v[152:155], v[188:191], v[112:115]
	v_mfma_f32_16x16x32_bf16 v[100:103], v[144:147], v[196:199], v[100:103]
	v_mfma_f32_16x16x32_bf16 v[96:99], v[152:155], v[196:199], v[96:99]
	v_mfma_f32_16x16x32_bf16 v[84:87], v[144:147], v[204:207], v[84:87]
	v_mfma_f32_16x16x32_bf16 v[80:83], v[152:155], v[204:207], v[80:83]
	v_mfma_f32_16x16x32_bf16 v[124:127], v[148:151], v[184:187], v[124:127]
	v_mfma_f32_16x16x32_bf16 v[120:123], v[156:159], v[184:187], v[120:123]
	v_mfma_f32_16x16x32_bf16 v[116:119], v[148:151], v[192:195], v[116:119]
	v_mfma_f32_16x16x32_bf16 v[112:115], v[156:159], v[192:195], v[112:115]
	v_mfma_f32_16x16x32_bf16 v[100:103], v[148:151], v[200:203], v[100:103]
	v_mfma_f32_16x16x32_bf16 v[96:99], v[156:159], v[200:203], v[96:99]
	v_mfma_f32_16x16x32_bf16 v[84:87], v[148:151], v[212:215], v[84:87]
	v_mfma_f32_16x16x32_bf16 v[80:83], v[156:159], v[212:215], v[80:83]
	v_mfma_f32_16x16x32_bf16 v[108:111], v[160:163], v[180:183], v[108:111]
	v_mfma_f32_16x16x32_bf16 v[104:107], v[172:175], v[180:183], v[104:107]
	v_mfma_f32_16x16x32_bf16 v[92:95], v[160:163], v[188:191], v[92:95]
	v_mfma_f32_16x16x32_bf16 v[88:91], v[172:175], v[188:191], v[88:91]
	v_mfma_f32_16x16x32_bf16 v[76:79], v[160:163], v[196:199], v[76:79]
	v_mfma_f32_16x16x32_bf16 v[72:75], v[172:175], v[196:199], v[72:75]
	v_mfma_f32_16x16x32_bf16 v[68:71], v[160:163], v[204:207], v[68:71]
	v_mfma_f32_16x16x32_bf16 v[64:67], v[172:175], v[204:207], v[64:67]
	v_mfma_f32_16x16x32_bf16 v[108:111], v[164:167], v[184:187], v[108:111]
	v_mfma_f32_16x16x32_bf16 v[104:107], v[176:179], v[184:187], v[104:107]
	v_mfma_f32_16x16x32_bf16 v[92:95], v[164:167], v[192:195], v[92:95]
	v_mfma_f32_16x16x32_bf16 v[88:91], v[176:179], v[192:195], v[88:91]
	v_mfma_f32_16x16x32_bf16 v[76:79], v[164:167], v[200:203], v[76:79]
	v_mfma_f32_16x16x32_bf16 v[72:75], v[176:179], v[200:203], v[72:75]
	v_mfma_f32_16x16x32_bf16 v[68:71], v[164:167], v[212:215], v[68:71]
	v_mfma_f32_16x16x32_bf16 v[64:67], v[176:179], v[212:215], v[64:67]
	s_barrier
	s_add_i32 s56, s56, s38
	v_lshl_add_u64 v[218:219], v[208:209], 0, s[12:13]
	s_mov_b32 m0, s56
	s_nop 0
	global_load_lds_dwordx4 v[218:219], off
	v_lshl_add_u64 v[218:219], v[208:209], 0, s[14:15]
	s_add_i32 m0, s56, 0x2000
	s_add_i32 s56, s57, s38
	global_load_lds_dwordx4 v[218:219], off
	v_lshl_add_u64 v[218:219], v[208:209], 0, s[16:17]
	s_mov_b32 m0, s56
	v_lshl_add_u64 v[208:209], v[208:209], 0, s[18:19]
	global_load_lds_dwordx4 v[218:219], off
	s_add_i32 m0, s56, 0x2000
	s_nop 0
	global_load_lds_dwordx4 v[208:209], off
	v_lshl_add_u64 v[208:209], v[216:217], 0, s[12:13]
	s_mov_b32 m0, s44
	s_nop 0
	global_load_lds_dwordx4 v[208:209], off
	v_lshl_add_u64 v[208:209], v[216:217], 0, s[14:15]
	s_mov_b32 m0, s45
	s_nop 0
	global_load_lds_dwordx4 v[208:209], off
	ds_read_b128 v[180:183], v142 offset:49152
	ds_read_b128 v[184:187], v142 offset:50176
	ds_read_b128 v[188:191], v142 offset:51200
	ds_read_b128 v[192:195], v142 offset:52224
	ds_read_b128 v[196:199], v142 offset:53248
	ds_read_b128 v[200:203], v142 offset:54272
	ds_read_b128 v[204:207], v142 offset:55296
	ds_read_b128 v[212:215], v142 offset:56320
	s_waitcnt vmcnt(8)
	s_waitcnt lgkmcnt(0)
	s_barrier
	s_waitcnt lgkmcnt(0)
	v_mfma_f32_16x16x32_bf16 v[60:63], v[144:147], v[180:183], v[60:63]
	v_mfma_f32_16x16x32_bf16 v[56:59], v[152:155], v[180:183], v[56:59]
	v_mfma_f32_16x16x32_bf16 v[52:55], v[144:147], v[188:191], v[52:55]
	v_mfma_f32_16x16x32_bf16 v[48:51], v[152:155], v[188:191], v[48:51]
	v_mfma_f32_16x16x32_bf16 v[36:39], v[144:147], v[196:199], v[36:39]
	v_mfma_f32_16x16x32_bf16 v[32:35], v[152:155], v[196:199], v[32:35]
	v_mfma_f32_16x16x32_bf16 v[20:23], v[144:147], v[204:207], v[20:23]
	v_mfma_f32_16x16x32_bf16 v[16:19], v[152:155], v[204:207], v[16:19]
	v_mfma_f32_16x16x32_bf16 v[60:63], v[148:151], v[184:187], v[60:63]
	v_mfma_f32_16x16x32_bf16 v[56:59], v[156:159], v[184:187], v[56:59]
	v_mfma_f32_16x16x32_bf16 v[52:55], v[148:151], v[192:195], v[52:55]
	v_mfma_f32_16x16x32_bf16 v[48:51], v[156:159], v[192:195], v[48:51]
	v_mfma_f32_16x16x32_bf16 v[36:39], v[148:151], v[200:203], v[36:39]
	v_mfma_f32_16x16x32_bf16 v[32:35], v[156:159], v[200:203], v[32:35]
	v_mfma_f32_16x16x32_bf16 v[20:23], v[148:151], v[212:215], v[20:23]
	v_mfma_f32_16x16x32_bf16 v[16:19], v[156:159], v[212:215], v[16:19]
	v_mfma_f32_16x16x32_bf16 v[44:47], v[160:163], v[180:183], v[44:47]
	v_mfma_f32_16x16x32_bf16 v[40:43], v[172:175], v[180:183], v[40:43]
	v_mfma_f32_16x16x32_bf16 v[28:31], v[160:163], v[188:191], v[28:31]
	v_mfma_f32_16x16x32_bf16 v[24:27], v[172:175], v[188:191], v[24:27]
	v_mfma_f32_16x16x32_bf16 v[12:15], v[160:163], v[196:199], v[12:15]
	v_mfma_f32_16x16x32_bf16 v[8:11], v[172:175], v[196:199], v[8:11]
	v_mfma_f32_16x16x32_bf16 v[4:7], v[160:163], v[204:207], v[4:7]
	v_mfma_f32_16x16x32_bf16 v[0:3], v[172:175], v[204:207], v[0:3]
	v_mfma_f32_16x16x32_bf16 v[44:47], v[164:167], v[184:187], v[44:47]
	v_mfma_f32_16x16x32_bf16 v[40:43], v[176:179], v[184:187], v[40:43]
	v_mfma_f32_16x16x32_bf16 v[28:31], v[164:167], v[192:195], v[28:31]
	v_mfma_f32_16x16x32_bf16 v[24:27], v[176:179], v[192:195], v[24:27]
	v_mfma_f32_16x16x32_bf16 v[12:15], v[164:167], v[200:203], v[12:15]
	v_mfma_f32_16x16x32_bf16 v[8:11], v[176:179], v[200:203], v[8:11]
	v_mfma_f32_16x16x32_bf16 v[4:7], v[164:167], v[212:215], v[4:7]
	v_mfma_f32_16x16x32_bf16 v[0:3], v[176:179], v[212:215], v[0:3]
	s_barrier
	s_cmp_gt_u32 s55, 41
	s_cbranch_scc0 .LBB0_1046
	s_and_b64 vcc, exec, s[20:21]
	s_cbranch_vccz .LBB0_1049
	s_barrier
